# up-phase row-scale pre-pass: batched all SSX loads (one memory round trip) instead of one round trip per unit
# speedup vs baseline: 1.0056x; 1.0056x over previous
; #define PG8_STAGE(bufoff, gbase, voff) glds16s2((voff)[0], (voff)[1], (const void*)(gbase), ldsn + (unsigned)(bufoff))
; #define PG8_LDA(dst, b, h) do { _Pragma("unroll") for (int m = 0; m < 4; ++m) _Pragma("unroll") for (int k = 0; k < 2; ++k) dst[m][k] = *(const LAS bf16x8*)(lds + PG8_SA(b, h) + aoff + m * 2048 + k * 1024); } while (0)
; #define PG8_LDB(dst, b, h) do { _Pragma("unroll") for (int n = 0; n < 2; ++n) _Pragma("unroll") for (int k = 0; k < 2; ++k) dst[n][k] = *(const LAS bf16x8*)(lds + PG8_SB(b, h) + boff + n * 2048 + k * 1024); } while (0)
; #define PG8_WAIT_V(n) asm volatile("s_waitcnt vmcnt(" #n ")" ::: "memory")
; #define PG8_WAIT_L(n) asm volatile("s_waitcnt lgkmcnt(" #n ")" ::: "memory")
; #define PG8_BAR __builtin_amdgcn_s_barrier()
; #define PG8_SCHED __builtin_amdgcn_sched_barrier(0)
; template <class Epi, bool ALIGN_EPI, bool EARLY_DRAIN = true, class Pre = NoPre>
; __device__ __forceinline__ void gemm_phase(LAS unsigned char* lds, const Gemm g, const StaticOrder& S, const Epi& E, int wv, const Pre& pre = Pre()) {
;     ...
;         for (int t = th; t < th + (Epi::MIDK ? nt / 2 : nt); t += 2) {
;             const bool last = (t == nt - 2);
;             const char* a1 = cA + (size_t)(t + 1) * kstep;
;             const char* a2 = last ? nA : cA + (size_t)(t + 2) * kstep; const char* b2 = last ? nB : cB + (size_t)(t + 2) * kstep;
;             const char* a3 = a2 + kstep; const char* b3 = b2 + kstep;
;             int lf_ = EARLY_DRAIN ? __builtin_amdgcn_readfirstlane(landed_flag) : landed_flag; if constexpr (EARLY_DRAIN) asm volatile("" : "+s"(lf_)); landed_flag = 0;
;             PG8_LDB(B0, 0, 0); PG8_LDB(B1, 0, 1); PG8_SCHED; PG8_LDA(At, 0, 0); PG8_STAGE(PG8_SA(1, 1), a1 + ahs, voffA);
;             if (!lf_) PG8_WAIT_V(8);
;             PG8_WAIT_L(0); PG8_BAR; PG8_MMA(0, 0, At, B0); PG8_MMA(0, 1, At, B1); PG8_BAR; PG8_SCHED;
;             PG8_LDA(At, 0, 1); PG8_STAGE(PG8_SB(0, 0), b2, voffB); PG8_STAGE(PG8_SB(0, 1), b2 + bhs, voffB); PG8_STAGE(PG8_SA(0, 0), a2, voffA);
;             if (!lf_) PG8_WAIT_V(8);
;             PG8_WAIT_L(0); PG8_BAR; PG8_MMA(1, 0, At, B0); PG8_MMA(1, 1, At, B1); PG8_BAR; PG8_SCHED;
;             PG8_LDB(B0, 1, 0); PG8_LDB(B1, 1, 1); PG8_SCHED; PG8_LDA(At, 1, 0); PG8_STAGE(PG8_SA(0, 1), a2 + ahs, voffA);
.LBB0_172:
	s_add_u32 s50, s70, 0x100
	s_addc_u32 s51, s71, 0
	s_waitcnt lgkmcnt(0)
	s_add_u32 s38, s68, 0x100
	s_addc_u32 s39, s69, 0
	s_barrier
	s_setprio 1
	s_waitcnt lgkmcnt(7)
	v_mfma_f32_16x16x32_bf16 v[2:5], v[86:89], v[38:41], 0
	v_mfma_f32_16x16x32_bf16 v[6:9], v[94:97], v[38:41], 0
	s_waitcnt lgkmcnt(5)
	v_mfma_f32_16x16x32_bf16 v[10:13], v[86:89], v[46:49], 0
	v_mfma_f32_16x16x32_bf16 v[14:17], v[94:97], v[46:49], 0
	s_waitcnt lgkmcnt(3)
	v_mfma_f32_16x16x32_bf16 v[18:21], v[86:89], v[58:61], 0
	v_mfma_f32_16x16x32_bf16 v[22:25], v[94:97], v[58:61], 0
	s_waitcnt lgkmcnt(1)
	v_mfma_f32_16x16x32_bf16 v[26:29], v[86:89], v[74:77], 0
	v_mfma_f32_16x16x32_bf16 v[30:33], v[94:97], v[74:77], 0
	v_mfma_f32_16x16x32_bf16 v[2:5], v[90:93], v[42:45], v[2:5]
	v_mfma_f32_16x16x32_bf16 v[6:9], v[98:101], v[42:45], v[6:9]
	v_mfma_f32_16x16x32_bf16 v[10:13], v[90:93], v[54:57], v[10:13]
	v_mfma_f32_16x16x32_bf16 v[14:17], v[98:101], v[54:57], v[14:17]
	v_mfma_f32_16x16x32_bf16 v[18:21], v[90:93], v[66:69], v[18:21]
	v_mfma_f32_16x16x32_bf16 v[22:25], v[98:101], v[66:69], v[22:25]
	s_waitcnt lgkmcnt(0)
	v_mfma_f32_16x16x32_bf16 v[26:29], v[90:93], v[78:81], v[26:29]
	v_mfma_f32_16x16x32_bf16 v[30:33], v[98:101], v[78:81], v[30:33]
	s_setprio 0
	s_setprio 1
	v_mfma_f32_16x16x32_bf16 v[34:37], v[50:53], v[38:41], 0
	v_mfma_f32_16x16x32_bf16 v[38:41], v[70:73], v[38:41], 0
	v_mfma_f32_16x16x32_bf16 v[34:37], v[62:65], v[42:45], v[34:37]
	v_mfma_f32_16x16x32_bf16 v[38:41], v[82:85], v[42:45], v[38:41]
	v_mfma_f32_16x16x32_bf16 v[42:45], v[50:53], v[46:49], 0
	v_mfma_f32_16x16x32_bf16 v[46:49], v[70:73], v[46:49], 0
	v_mfma_f32_16x16x32_bf16 v[42:45], v[62:65], v[54:57], v[42:45]
	v_mfma_f32_16x16x32_bf16 v[46:49], v[82:85], v[54:57], v[46:49]
	v_mfma_f32_16x16x32_bf16 v[54:57], v[50:53], v[58:61], 0
	v_mfma_f32_16x16x32_bf16 v[58:61], v[70:73], v[58:61], 0
	v_mfma_f32_16x16x32_bf16 v[54:57], v[62:65], v[66:69], v[54:57]
	v_mfma_f32_16x16x32_bf16 v[58:61], v[82:85], v[66:69], v[58:61]
	v_mfma_f32_16x16x32_bf16 v[66:69], v[50:53], v[74:77], 0
	v_mfma_f32_16x16x32_bf16 v[74:77], v[70:73], v[74:77], 0
	v_mfma_f32_16x16x32_bf16 v[66:69], v[62:65], v[78:81], v[66:69]
	v_mfma_f32_16x16x32_bf16 v[74:77], v[82:85], v[78:81], v[74:77]
	s_setprio 0
	s_barrier
	ds_read_b128 v[126:129], v244 offset:16384
	ds_read_b128 v[162:165], v244 offset:17408
	ds_read_b128 v[118:121], v244 offset:18432
	ds_read_b128 v[122:125], v244 offset:19456
	ds_read_b128 v[110:113], v244 offset:20480
	ds_read_b128 v[114:117], v244 offset:21504
	ds_read_b128 v[102:105], v244 offset:22528
	ds_read_b128 v[106:109], v244 offset:23552
	s_mov_b32 m0, s10
	s_nop 0
	global_load_lds_dwordx4 v230, s[38:39]
	s_add_u32 m0, m0, 0x2000
	s_nop 0
	global_load_lds_dwordx4 v232, s[38:39]
	s_add_u32 s38, s68, 0x40100
	s_addc_u32 s39, s69, 0
	s_mov_b32 m0, s12
	s_nop 0
	global_load_lds_dwordx4 v230, s[38:39]
	s_add_u32 m0, m0, 0x2000
	s_nop 0
	global_load_lds_dwordx4 v232, s[38:39]
	v_cndmask_b32_e64 v78, 0, 1, s[84:85]
	s_mov_b32 m0, s5
	s_nop 0
	global_load_lds_dwordx4 v0, s[50:51]
	s_add_u32 m0, m0, 0x2000
	s_nop 0
	global_load_lds_dwordx4 v231, s[50:51]
	v_cmp_ne_u32_e64 s[38:39], 1, v78
	s_andn2_b64 vcc, exec, s[84:85]
	s_cbranch_vccnz .LBB0_174
	s_waitcnt vmcnt(8)
.LBB0_174:
	s_waitcnt lgkmcnt(0)
	s_barrier
	s_setprio 1
	s_waitcnt lgkmcnt(7)
	v_mfma_f32_16x16x32_bf16 v[78:81], v[86:89], v[126:129], 0
	s_waitcnt lgkmcnt(5)
	v_mfma_f32_16x16x32_bf16 v[134:137], v[86:89], v[118:121], 0
	s_waitcnt lgkmcnt(3)
	v_mfma_f32_16x16x32_bf16 v[142:145], v[86:89], v[110:113], 0
	s_waitcnt lgkmcnt(1)
	v_mfma_f32_16x16x32_bf16 v[86:89], v[86:89], v[102:105], 0
	v_mfma_f32_16x16x32_bf16 v[130:133], v[94:97], v[126:129], 0
	v_mfma_f32_16x16x32_bf16 v[138:141], v[94:97], v[118:121], 0
	v_mfma_f32_16x16x32_bf16 v[146:149], v[94:97], v[110:113], 0
	s_waitcnt lgkmcnt(0)
	v_mfma_f32_16x16x32_bf16 v[150:153], v[90:93], v[106:109], v[86:89]
	v_mfma_f32_16x16x32_bf16 v[86:89], v[94:97], v[102:105], 0
	v_mfma_f32_16x16x32_bf16 v[78:81], v[90:93], v[162:165], v[78:81]
	v_mfma_f32_16x16x32_bf16 v[130:133], v[98:101], v[162:165], v[130:133]
	v_mfma_f32_16x16x32_bf16 v[134:137], v[90:93], v[122:125], v[134:137]
	v_mfma_f32_16x16x32_bf16 v[138:141], v[98:101], v[122:125], v[138:141]
	v_mfma_f32_16x16x32_bf16 v[142:145], v[90:93], v[114:117], v[142:145]
	v_mfma_f32_16x16x32_bf16 v[146:149], v[98:101], v[114:117], v[146:149]
	v_mfma_f32_16x16x32_bf16 v[154:157], v[98:101], v[106:109], v[86:89]
	s_setprio 0
	s_setprio 1
	v_mfma_f32_16x16x32_bf16 v[86:89], v[50:53], v[126:129], 0
	v_mfma_f32_16x16x32_bf16 v[158:161], v[62:65], v[162:165], v[86:89]
	v_mfma_f32_16x16x32_bf16 v[86:89], v[70:73], v[126:129], 0
	v_mfma_f32_16x16x32_bf16 v[162:165], v[82:85], v[162:165], v[86:89]
	v_mfma_f32_16x16x32_bf16 v[86:89], v[50:53], v[118:121], 0
	v_mfma_f32_16x16x32_bf16 v[166:169], v[62:65], v[122:125], v[86:89]
	v_mfma_f32_16x16x32_bf16 v[86:89], v[70:73], v[118:121], 0
	v_mfma_f32_16x16x32_bf16 v[170:173], v[82:85], v[122:125], v[86:89]
	v_mfma_f32_16x16x32_bf16 v[86:89], v[50:53], v[110:113], 0
	v_mfma_f32_16x16x32_bf16 v[50:53], v[50:53], v[102:105], 0
	v_mfma_f32_16x16x32_bf16 v[174:177], v[62:65], v[114:117], v[86:89]
	v_mfma_f32_16x16x32_bf16 v[86:89], v[70:73], v[110:113], 0
	v_mfma_f32_16x16x32_bf16 v[182:185], v[62:65], v[106:109], v[50:53]
	v_mfma_f32_16x16x32_bf16 v[50:53], v[70:73], v[102:105], 0
	v_mfma_f32_16x16x32_bf16 v[178:181], v[82:85], v[114:117], v[86:89]
	v_mfma_f32_16x16x32_bf16 v[186:189], v[82:85], v[106:109], v[50:53]
	s_setprio 0
	s_barrier
	v_add_u32_e32 v234, 0x18000, v233
	v_add_u32_e32 v235, 0x1c000, v233
	ds_read_b128 v[206:209], v234
	ds_read_b128 v[210:213], v234 offset:1024
	ds_read_b128 v[214:217], v234 offset:2048
	ds_read_b128 v[218:221], v234 offset:3072
	ds_read_b128 v[190:193], v235
	ds_read_b128 v[194:197], v235 offset:1024
	ds_read_b128 v[198:201], v235 offset:2048
	ds_read_b128 v[202:205], v235 offset:3072
	ds_read_b128 v[110:113], v244 offset:32768
	ds_read_b128 v[118:121], v244 offset:33792
	ds_read_b128 v[94:97], v244 offset:34816
	ds_read_b128 v[102:105], v244 offset:35840
	ds_read_b128 v[70:73], v244 offset:36864
	ds_read_b128 v[86:89], v244 offset:37888
	ds_read_b128 v[222:225], v244 offset:38912
	ds_read_b128 v[226:229], v244 offset:39936
	s_add_u32 s50, s70, 0x40100
	s_addc_u32 s51, s71, 0
	s_mov_b32 m0, s13
	s_nop 0
	global_load_lds_dwordx4 v0, s[50:51]
	s_add_u32 m0, m0, 0x2000
	s_nop 0
	global_load_lds_dwordx4 v231, s[50:51]
	s_and_b64 vcc, exec, s[38:39]
	s_cbranch_vccnz .LBB0_176
	s_waitcnt vmcnt(8)
; #define PG8_BAR __builtin_amdgcn_s_barrier()
; template <class Epi, bool ALIGN_EPI, bool EARLY_DRAIN = true, class Pre = NoPre>
; __device__ __forceinline__ void gemm_phase(LAS unsigned char* lds, const Gemm g, const StaticOrder& S, const Epi& E, int wv, const Pre& pre = Pre()) {
;     ...
;         const bool has_next = S.next(ui + 1, nxt);
;         const char* nA = has_next ? g.A + (size_t)nxt.pm * g.a_tstep + (size_t)(nxt.pm >> 6) * g.a_pad : cA; const char* nB = has_next ? g.Bt + (size_t)nxt.pn * g.b_tstep : cB;
;         int landed_flag = fresh ? 1 : 0;
;         typename Epi::PF pf;
;         if constexpr (Epi::PREF) { int pt_ = lane_now(); asm volatile("" : "+v"(pt_)); E.prefetch(pf, cur, wr, wc, pt_ & 15, pt_ >> 4); }
;         for (int th = 0; th < nt; th += (Epi::MIDK ? nt / 2 : nt)) {
;         if constexpr (Epi::MIDK) { if (th) E.midk(acc, ui, wr, fr); }
;         for (int t = th; t < th + (Epi::MIDK ? nt / 2 : nt); t += 2) {
;             const bool last = (t == nt - 2);
;             const char* a1 = cA + (size_t)(t + 1) * kstep;
;             const char* a2 = last ? nA : cA + (size_t)(t + 2) * kstep; const char* b2 = last ? nB : cB + (size_t)(t + 2) * kstep;
;             const char* a3 = a2 + kstep; const char* b3 = b2 + kstep;
;             int lf_ = EARLY_DRAIN ? __builtin_amdgcn_readfirstlane(landed_flag) : landed_flag; if constexpr (EARLY_DRAIN) asm volatile("" : "+s"(lf_)); landed_flag = 0;
;             PG8_LDB(B0, 0, 0); PG8_LDB(B1, 0, 1); PG8_SCHED; PG8_LDA(At, 0, 0); PG8_STAGE(PG8_SA(1, 1), a1 + ahs, voffA);
;             if (!lf_) PG8_WAIT_V(8);
;             PG8_WAIT_L(0); PG8_BAR; PG8_MMA(0, 0, At, B0); PG8_MMA(0, 1, At, B1); PG8_BAR; PG8_SCHED;
;             PG8_LDA(At, 0, 1); PG8_STAGE(PG8_SB(0, 0), b2, voffB); PG8_STAGE(PG8_SB(0, 1), b2 + bhs, voffB); PG8_STAGE(PG8_SA(0, 0), a2, voffA);
;             if (!lf_) PG8_WAIT_V(8);
;             PG8_WAIT_L(0); PG8_BAR; PG8_MMA(1, 0, At, B0); PG8_MMA(1, 1, At, B1); PG8_BAR; PG8_SCHED;
;             PG8_LDB(B0, 1, 0); PG8_LDB(B1, 1, 1); PG8_SCHED; PG8_LDA(At, 1, 0); PG8_STAGE(PG8_SA(0, 1), a2 + ahs, voffA);
;             if (!lf_) PG8_WAIT_V(8);
;             PG8_WAIT_L(0); PG8_BAR; PG8_MMA(0, 0, At, B0); PG8_MMA(0, 1, At, B1); PG8_BAR; PG8_SCHED;
;             PG8_LDA(At, 1, 1); PG8_STAGE(PG8_SB(1, 0), b3, voffB); PG8_STAGE(PG8_SB(1, 1), b3 + bhs, voffB); PG8_STAGE(PG8_SA(1, 0), a3, voffA);
.LBB0_176:
	s_ashr_i32 s43, s42, 31
	s_lshl_b64 s[38:39], s[42:43], 19
	s_add_u32 s38, s4, s38
	s_addc_u32 s39, s9, s39
	s_and_b64 s[36:37], s[36:37], exec
	s_cselect_b32 s43, s39, s69
	s_cselect_b32 s47, s38, s68
	s_add_u32 s36, s70, 0x180
	s_addc_u32 s37, s71, 0
	s_waitcnt lgkmcnt(0)
	s_add_u32 s50, s68, 0x180
	s_addc_u32 s51, s69, 0
	s_barrier
	s_setprio 1
	s_waitcnt lgkmcnt(7)
	v_mfma_f32_16x16x32_bf16 v[2:5], v[206:209], v[110:113], v[2:5]
	s_waitcnt lgkmcnt(6)
	v_mfma_f32_16x16x32_bf16 v[122:125], v[210:213], v[118:121], v[2:5]
	v_mfma_f32_16x16x32_bf16 v[2:5], v[214:217], v[110:113], v[6:9]
	v_mfma_f32_16x16x32_bf16 v[114:117], v[218:221], v[118:121], v[2:5]
	s_waitcnt lgkmcnt(5)
	v_mfma_f32_16x16x32_bf16 v[2:5], v[206:209], v[94:97], v[10:13]
	s_waitcnt lgkmcnt(4)
	v_mfma_f32_16x16x32_bf16 v[106:109], v[210:213], v[102:105], v[2:5]
	v_mfma_f32_16x16x32_bf16 v[2:5], v[214:217], v[94:97], v[14:17]
	v_mfma_f32_16x16x32_bf16 v[98:101], v[218:221], v[102:105], v[2:5]
	s_waitcnt lgkmcnt(3)
	v_mfma_f32_16x16x32_bf16 v[2:5], v[206:209], v[70:73], v[18:21]
	s_waitcnt lgkmcnt(2)
	v_mfma_f32_16x16x32_bf16 v[90:93], v[210:213], v[86:89], v[2:5]
	v_mfma_f32_16x16x32_bf16 v[2:5], v[214:217], v[70:73], v[22:25]
	v_mfma_f32_16x16x32_bf16 v[82:85], v[218:221], v[86:89], v[2:5]
	s_waitcnt lgkmcnt(1)
	v_mfma_f32_16x16x32_bf16 v[2:5], v[206:209], v[222:225], v[26:29]
	s_waitcnt lgkmcnt(0)
	v_mfma_f32_16x16x32_bf16 v[62:65], v[210:213], v[226:229], v[2:5]
	v_mfma_f32_16x16x32_bf16 v[2:5], v[214:217], v[222:225], v[30:33]
	v_mfma_f32_16x16x32_bf16 v[50:53], v[218:221], v[226:229], v[2:5]
	s_setprio 0
	s_setprio 1
	v_mfma_f32_16x16x32_bf16 v[2:5], v[190:193], v[110:113], v[34:37]
	v_mfma_f32_16x16x32_bf16 v[126:129], v[194:197], v[118:121], v[2:5]
	v_mfma_f32_16x16x32_bf16 v[2:5], v[198:201], v[110:113], v[38:41]
	v_mfma_f32_16x16x32_bf16 v[118:121], v[202:205], v[118:121], v[2:5]
	v_mfma_f32_16x16x32_bf16 v[2:5], v[190:193], v[94:97], v[42:45]
	v_mfma_f32_16x16x32_bf16 v[110:113], v[194:197], v[102:105], v[2:5]
	v_mfma_f32_16x16x32_bf16 v[2:5], v[198:201], v[94:97], v[46:49]
	v_mfma_f32_16x16x32_bf16 v[102:105], v[202:205], v[102:105], v[2:5]
	v_mfma_f32_16x16x32_bf16 v[2:5], v[190:193], v[70:73], v[54:57]
	v_mfma_f32_16x16x32_bf16 v[94:97], v[194:197], v[86:89], v[2:5]
	v_mfma_f32_16x16x32_bf16 v[2:5], v[198:201], v[70:73], v[58:61]
	v_mfma_f32_16x16x32_bf16 v[86:89], v[202:205], v[86:89], v[2:5]
	v_mfma_f32_16x16x32_bf16 v[2:5], v[190:193], v[222:225], v[66:69]
	v_mfma_f32_16x16x32_bf16 v[70:73], v[194:197], v[226:229], v[2:5]
	v_mfma_f32_16x16x32_bf16 v[2:5], v[198:201], v[222:225], v[74:77]
	v_mfma_f32_16x16x32_bf16 v[54:57], v[202:205], v[226:229], v[2:5]
	s_setprio 0
	s_barrier
	ds_read_b128 v[6:9], v244 offset:49152
	ds_read_b128 v[14:17], v244 offset:50176
	ds_read_b128 v[22:25], v244 offset:51200
	ds_read_b128 v[30:33], v244 offset:52224
	ds_read_b128 v[222:225], v244 offset:53248
	ds_read_b128 v[226:229], v244 offset:54272
	ds_read_b128 v[236:239], v244 offset:55296
	ds_read_b128 v[240:243], v244 offset:56320
	s_mov_b32 m0, s23
	s_nop 0
	global_load_lds_dwordx4 v230, s[50:51]
	s_add_u32 m0, m0, 0x2000
	s_nop 0
	global_load_lds_dwordx4 v232, s[50:51]
	s_add_u32 s50, s68, 0x40180
	s_addc_u32 s51, s69, 0
	s_mov_b32 m0, s25
	s_nop 0
	global_load_lds_dwordx4 v230, s[50:51]
	s_add_u32 m0, m0, 0x2000
	s_nop 0
	global_load_lds_dwordx4 v232, s[50:51]
	s_nop 0
	s_mov_b32 m0, s24
	s_nop 0
	global_load_lds_dwordx4 v0, s[36:37]
	s_add_u32 m0, m0, 0x2000
	s_nop 0
	global_load_lds_dwordx4 v231, s[36:37]
	s_waitcnt vmcnt(8)
	s_waitcnt lgkmcnt(0)
	s_barrier
	s_setprio 1
	s_waitcnt lgkmcnt(7)
	v_mfma_f32_16x16x32_bf16 v[2:5], v[206:209], v[6:9], v[78:81]
	s_waitcnt lgkmcnt(6)
	v_mfma_f32_16x16x32_bf16 v[74:77], v[210:213], v[14:17], v[2:5]
	v_mfma_f32_16x16x32_bf16 v[2:5], v[214:217], v[6:9], v[130:133]
	v_mfma_f32_16x16x32_bf16 v[58:61], v[218:221], v[14:17], v[2:5]
	s_waitcnt lgkmcnt(5)
	v_mfma_f32_16x16x32_bf16 v[2:5], v[206:209], v[22:25], v[134:137]
	s_waitcnt lgkmcnt(4)
	v_mfma_f32_16x16x32_bf16 v[42:45], v[210:213], v[30:33], v[2:5]
	v_mfma_f32_16x16x32_bf16 v[2:5], v[214:217], v[22:25], v[138:141]
	v_mfma_f32_16x16x32_bf16 v[34:37], v[218:221], v[30:33], v[2:5]
	s_waitcnt lgkmcnt(3)
	v_mfma_f32_16x16x32_bf16 v[2:5], v[206:209], v[222:225], v[142:145]
	s_waitcnt lgkmcnt(2)
	v_mfma_f32_16x16x32_bf16 v[26:29], v[210:213], v[226:229], v[2:5]
	v_mfma_f32_16x16x32_bf16 v[2:5], v[214:217], v[222:225], v[146:149]
	v_mfma_f32_16x16x32_bf16 v[18:21], v[218:221], v[226:229], v[2:5]
	s_waitcnt lgkmcnt(1)
	v_mfma_f32_16x16x32_bf16 v[2:5], v[206:209], v[236:239], v[150:153]
	s_waitcnt lgkmcnt(0)
	v_mfma_f32_16x16x32_bf16 v[10:13], v[210:213], v[240:243], v[2:5]
	v_mfma_f32_16x16x32_bf16 v[2:5], v[214:217], v[236:239], v[154:157]
	v_mfma_f32_16x16x32_bf16 v[2:5], v[218:221], v[240:243], v[2:5]
	s_setprio 0
	s_setprio 1
	v_mfma_f32_16x16x32_bf16 v[38:41], v[190:193], v[6:9], v[158:161]
	v_mfma_f32_16x16x32_bf16 v[6:9], v[198:201], v[6:9], v[162:165]
	v_mfma_f32_16x16x32_bf16 v[66:69], v[202:205], v[14:17], v[6:9]
	v_mfma_f32_16x16x32_bf16 v[6:9], v[190:193], v[22:25], v[166:169]
	v_mfma_f32_16x16x32_bf16 v[46:49], v[194:197], v[30:33], v[6:9]
	v_mfma_f32_16x16x32_bf16 v[6:9], v[198:201], v[22:25], v[170:173]
	v_mfma_f32_16x16x32_bf16 v[78:81], v[194:197], v[14:17], v[38:41]
	v_mfma_f32_16x16x32_bf16 v[38:41], v[202:205], v[30:33], v[6:9]
	v_mfma_f32_16x16x32_bf16 v[6:9], v[190:193], v[222:225], v[174:177]
	v_mfma_f32_16x16x32_bf16 v[30:33], v[194:197], v[226:229], v[6:9]
	v_mfma_f32_16x16x32_bf16 v[6:9], v[198:201], v[222:225], v[178:181]
	v_mfma_f32_16x16x32_bf16 v[22:25], v[202:205], v[226:229], v[6:9]
	v_mfma_f32_16x16x32_bf16 v[6:9], v[190:193], v[236:239], v[182:185]
	v_mfma_f32_16x16x32_bf16 v[14:17], v[194:197], v[240:243], v[6:9]
	v_mfma_f32_16x16x32_bf16 v[6:9], v[198:201], v[236:239], v[186:189]
	v_mfma_f32_16x16x32_bf16 v[6:9], v[202:205], v[240:243], v[6:9]
	s_setprio 0
	s_barrier
	s_add_u32 s50, s70, 0x200
	s_addc_u32 s51, s71, 0
	s_add_u32 s52, s68, 0x200
	s_addc_u32 s53, s69, 0
	s_add_u32 s68, s70, 0x40180
	s_addc_u32 s69, s71, 0
	s_mov_b32 s64, 0
	s_branch .LBB0_178
; #define PG8_STAGE(bufoff, gbase, voff) glds16s2((voff)[0], (voff)[1], (const void*)(gbase), ldsn + (unsigned)(bufoff))
; #define PG8_LDA(dst, b, h) do { _Pragma("unroll") for (int m = 0; m < 4; ++m) _Pragma("unroll") for (int k = 0; k < 2; ++k) dst[m][k] = *(const LAS bf16x8*)(lds + PG8_SA(b, h) + aoff + m * 2048 + k * 1024); } while (0)
; #define PG8_WAIT_V(n) asm volatile("s_waitcnt vmcnt(" #n ")" ::: "memory")
; #define PG8_WAIT_L(n) asm volatile("s_waitcnt lgkmcnt(" #n ")" ::: "memory")
; template <class Epi, bool ALIGN_EPI, bool EARLY_DRAIN = true, class Pre = NoPre>
; __device__ __forceinline__ void gemm_phase(LAS unsigned char* lds, const Gemm g, const StaticOrder& S, const Epi& E, int wv, const Pre& pre = Pre()) {
;     ...
;         for (int t = th; t < th + (Epi::MIDK ? nt / 2 : nt); t += 2) {
;             const bool last = (t == nt - 2);
;             const char* a1 = cA + (size_t)(t + 1) * kstep;
;             const char* a2 = last ? nA : cA + (size_t)(t + 2) * kstep; const char* b2 = last ? nB : cB + (size_t)(t + 2) * kstep;
;             const char* a3 = a2 + kstep; const char* b3 = b2 + kstep;
;             int lf_ = EARLY_DRAIN ? __builtin_amdgcn_readfirstlane(landed_flag) : landed_flag; if constexpr (EARLY_DRAIN) asm volatile("" : "+s"(lf_)); landed_flag = 0;
;             PG8_LDB(B0, 0, 0); PG8_LDB(B1, 0, 1); PG8_SCHED; PG8_LDA(At, 0, 0); PG8_STAGE(PG8_SA(1, 1), a1 + ahs, voffA);
;             if (!lf_) PG8_WAIT_V(8);
;             PG8_WAIT_L(0); PG8_BAR; PG8_MMA(0, 0, At, B0); PG8_MMA(0, 1, At, B1); PG8_BAR; PG8_SCHED;
;             PG8_LDA(At, 0, 1); PG8_STAGE(PG8_SB(0, 0), b2, voffB); PG8_STAGE(PG8_SB(0, 1), b2 + bhs, voffB); PG8_STAGE(PG8_SA(0, 0), a2, voffA);
;             if (!lf_) PG8_WAIT_V(8);
;             PG8_WAIT_L(0); PG8_BAR; PG8_MMA(1, 0, At, B0); PG8_MMA(1, 1, At, B1); PG8_BAR; PG8_SCHED;
;             PG8_LDB(B0, 1, 0); PG8_LDB(B1, 1, 1); PG8_SCHED; PG8_LDA(At, 1, 0); PG8_STAGE(PG8_SA(0, 1), a2 + ahs, voffA);
;             if (!lf_) PG8_WAIT_V(8);
;             PG8_WAIT_L(0); PG8_BAR; PG8_MMA(0, 0, At, B0); PG8_MMA(0, 1, At, B1); PG8_BAR; PG8_SCHED;
;             PG8_LDA(At, 1, 1); PG8_STAGE(PG8_SB(1, 0), b3, voffB); PG8_STAGE(PG8_SB(1, 1), b3 + bhs, voffB); PG8_STAGE(PG8_SA(1, 0), a3, voffA);
;             PG8_WAIT_V(8); PG8_WAIT_L(0); PG8_BAR; PG8_MMA(1, 0, At, B0); PG8_MMA(1, 1, At, B1); PG8_BAR; PG8_SCHED;
.LBB0_177:
	s_add_u32 s36, s84, 0x80
	s_waitcnt lgkmcnt(0)
	s_addc_u32 s37, s85, 0
	s_add_u32 s66, s70, 0x80
	s_addc_u32 s67, s71, 0
	s_barrier
	s_setprio 1
	s_waitcnt lgkmcnt(7)
	v_mfma_f32_16x16x32_bf16 v[122:125], v[146:149], v[186:189], v[122:125]
	v_mfma_f32_16x16x32_bf16 v[114:117], v[154:157], v[186:189], v[114:117]
	s_waitcnt lgkmcnt(5)
	v_mfma_f32_16x16x32_bf16 v[106:109], v[146:149], v[178:181], v[106:109]
	v_mfma_f32_16x16x32_bf16 v[98:101], v[154:157], v[178:181], v[98:101]
	s_waitcnt lgkmcnt(3)
	v_mfma_f32_16x16x32_bf16 v[90:93], v[146:149], v[170:173], v[90:93]
	v_mfma_f32_16x16x32_bf16 v[82:85], v[154:157], v[170:173], v[82:85]
	s_waitcnt lgkmcnt(1)
	v_mfma_f32_16x16x32_bf16 v[62:65], v[146:149], v[162:165], v[62:65]
	v_mfma_f32_16x16x32_bf16 v[50:53], v[154:157], v[162:165], v[50:53]
	v_mfma_f32_16x16x32_bf16 v[122:125], v[150:153], v[190:193], v[122:125]
	v_mfma_f32_16x16x32_bf16 v[114:117], v[158:161], v[190:193], v[114:117]
	v_mfma_f32_16x16x32_bf16 v[106:109], v[150:153], v[182:185], v[106:109]
	v_mfma_f32_16x16x32_bf16 v[98:101], v[158:161], v[182:185], v[98:101]
	v_mfma_f32_16x16x32_bf16 v[90:93], v[150:153], v[174:177], v[90:93]
	v_mfma_f32_16x16x32_bf16 v[82:85], v[158:161], v[174:177], v[82:85]
	s_waitcnt lgkmcnt(0)
	v_mfma_f32_16x16x32_bf16 v[62:65], v[150:153], v[166:169], v[62:65]
	v_mfma_f32_16x16x32_bf16 v[50:53], v[158:161], v[166:169], v[50:53]
	s_setprio 0
	s_setprio 1
	v_mfma_f32_16x16x32_bf16 v[126:129], v[130:133], v[186:189], v[126:129]
	v_mfma_f32_16x16x32_bf16 v[118:121], v[138:141], v[186:189], v[118:121]
	v_mfma_f32_16x16x32_bf16 v[110:113], v[130:133], v[178:181], v[110:113]
	v_mfma_f32_16x16x32_bf16 v[102:105], v[138:141], v[178:181], v[102:105]
	v_mfma_f32_16x16x32_bf16 v[94:97], v[130:133], v[170:173], v[94:97]
	v_mfma_f32_16x16x32_bf16 v[86:89], v[138:141], v[170:173], v[86:89]
	v_mfma_f32_16x16x32_bf16 v[70:73], v[130:133], v[162:165], v[70:73]
	v_mfma_f32_16x16x32_bf16 v[54:57], v[138:141], v[162:165], v[54:57]
	v_mfma_f32_16x16x32_bf16 v[126:129], v[134:137], v[190:193], v[126:129]
	v_mfma_f32_16x16x32_bf16 v[118:121], v[142:145], v[190:193], v[118:121]
	v_mfma_f32_16x16x32_bf16 v[110:113], v[134:137], v[182:185], v[110:113]
	v_mfma_f32_16x16x32_bf16 v[102:105], v[142:145], v[182:185], v[102:105]
	v_mfma_f32_16x16x32_bf16 v[94:97], v[134:137], v[174:177], v[94:97]
	v_mfma_f32_16x16x32_bf16 v[86:89], v[142:145], v[174:177], v[86:89]
	v_mfma_f32_16x16x32_bf16 v[70:73], v[134:137], v[166:169], v[70:73]
	v_mfma_f32_16x16x32_bf16 v[54:57], v[142:145], v[166:169], v[54:57]
	s_setprio 0
	s_barrier
	ds_read_b128 v[162:165], v244 offset:49152
	ds_read_b128 v[166:169], v244 offset:50176
	ds_read_b128 v[170:173], v244 offset:51200
	ds_read_b128 v[174:177], v244 offset:52224
	ds_read_b128 v[178:181], v244 offset:53248
	ds_read_b128 v[182:185], v244 offset:54272
	ds_read_b128 v[186:189], v244 offset:55296
	ds_read_b128 v[190:193], v244 offset:56320
	s_mov_b32 m0, s23
	s_nop 0
	global_load_lds_dwordx4 v230, s[66:67]
	s_add_u32 m0, m0, 0x2000
	s_nop 0
	global_load_lds_dwordx4 v232, s[66:67]
	s_add_u32 s66, s70, 0x40080
	s_addc_u32 s67, s71, 0
	s_mov_b32 m0, s25
	s_nop 0
	global_load_lds_dwordx4 v230, s[66:67]
	s_add_u32 m0, m0, 0x2000
	s_nop 0
	global_load_lds_dwordx4 v232, s[66:67]
	s_nop 0
	s_mov_b32 m0, s24
	s_nop 0
	global_load_lds_dwordx4 v0, s[36:37]
	s_add_u32 m0, m0, 0x2000
	s_nop 0
	global_load_lds_dwordx4 v231, s[36:37]
	s_waitcnt vmcnt(8)
	s_waitcnt lgkmcnt(0)
	s_barrier
	s_setprio 1
	s_waitcnt lgkmcnt(7)
	v_mfma_f32_16x16x32_bf16 v[74:77], v[146:149], v[162:165], v[74:77]
	v_mfma_f32_16x16x32_bf16 v[58:61], v[154:157], v[162:165], v[58:61]
	s_waitcnt lgkmcnt(5)
	v_mfma_f32_16x16x32_bf16 v[42:45], v[146:149], v[170:173], v[42:45]
	v_mfma_f32_16x16x32_bf16 v[34:37], v[154:157], v[170:173], v[34:37]
	s_waitcnt lgkmcnt(3)
	v_mfma_f32_16x16x32_bf16 v[26:29], v[146:149], v[178:181], v[26:29]
	v_mfma_f32_16x16x32_bf16 v[18:21], v[154:157], v[178:181], v[18:21]
	s_waitcnt lgkmcnt(1)
	v_mfma_f32_16x16x32_bf16 v[10:13], v[146:149], v[186:189], v[10:13]
	v_mfma_f32_16x16x32_bf16 v[2:5], v[154:157], v[186:189], v[2:5]
	v_mfma_f32_16x16x32_bf16 v[74:77], v[150:153], v[166:169], v[74:77]
	v_mfma_f32_16x16x32_bf16 v[58:61], v[158:161], v[166:169], v[58:61]
	v_mfma_f32_16x16x32_bf16 v[42:45], v[150:153], v[174:177], v[42:45]
	v_mfma_f32_16x16x32_bf16 v[34:37], v[158:161], v[174:177], v[34:37]
	v_mfma_f32_16x16x32_bf16 v[26:29], v[150:153], v[182:185], v[26:29]
	v_mfma_f32_16x16x32_bf16 v[18:21], v[158:161], v[182:185], v[18:21]
	s_waitcnt lgkmcnt(0)
	v_mfma_f32_16x16x32_bf16 v[10:13], v[150:153], v[190:193], v[10:13]
	v_mfma_f32_16x16x32_bf16 v[2:5], v[158:161], v[190:193], v[2:5]
	s_setprio 0
	s_setprio 1
	v_mfma_f32_16x16x32_bf16 v[78:81], v[130:133], v[162:165], v[78:81]
	v_mfma_f32_16x16x32_bf16 v[66:69], v[138:141], v[162:165], v[66:69]
	v_mfma_f32_16x16x32_bf16 v[46:49], v[130:133], v[170:173], v[46:49]
	v_mfma_f32_16x16x32_bf16 v[38:41], v[138:141], v[170:173], v[38:41]
	v_mfma_f32_16x16x32_bf16 v[30:33], v[130:133], v[178:181], v[30:33]
	v_mfma_f32_16x16x32_bf16 v[22:25], v[138:141], v[178:181], v[22:25]
	v_mfma_f32_16x16x32_bf16 v[14:17], v[130:133], v[186:189], v[14:17]
	v_mfma_f32_16x16x32_bf16 v[6:9], v[138:141], v[186:189], v[6:9]
	v_mfma_f32_16x16x32_bf16 v[78:81], v[134:137], v[166:169], v[78:81]
	v_mfma_f32_16x16x32_bf16 v[66:69], v[142:145], v[166:169], v[66:69]
	v_mfma_f32_16x16x32_bf16 v[46:49], v[134:137], v[174:177], v[46:49]
	v_mfma_f32_16x16x32_bf16 v[38:41], v[142:145], v[174:177], v[38:41]
	v_mfma_f32_16x16x32_bf16 v[30:33], v[134:137], v[182:185], v[30:33]
	v_mfma_f32_16x16x32_bf16 v[22:25], v[142:145], v[182:185], v[22:25]
	v_mfma_f32_16x16x32_bf16 v[14:17], v[134:137], v[190:193], v[14:17]
	v_mfma_f32_16x16x32_bf16 v[6:9], v[142:145], v[190:193], v[6:9]
	s_setprio 0
	s_barrier
	s_add_i32 s64, s64, 2
	s_add_u32 s50, s50, 0x100
	s_addc_u32 s51, s51, 0
	s_add_u32 s52, s52, 0x100
	s_addc_u32 s53, s53, 0
	s_add_u32 s68, s68, 0x100
	s_addc_u32 s69, s69, 0
	s_cmp_gt_u32 s64, 13
	s_cbranch_scc1 .LBB0_184

; #define PG8_STAGE(bufoff, gbase, voff) glds16s2((voff)[0], (voff)[1], (const void*)(gbase), ldsn + (unsigned)(bufoff))
; #define PG8_LDA(dst, b, h) do { _Pragma("unroll") for (int m = 0; m < 4; ++m) _Pragma("unroll") for (int k = 0; k < 2; ++k) dst[m][k] = *(const LAS bf16x8*)(lds + PG8_SA(b, h) + aoff + m * 2048 + k * 1024); } while (0)
; #define PG8_WAIT_V(n) asm volatile("s_waitcnt vmcnt(" #n ")" ::: "memory")
; #define PG8_WAIT_L(n) asm volatile("s_waitcnt lgkmcnt(" #n ")" ::: "memory")
; template <class Epi, bool ALIGN_EPI, bool EARLY_DRAIN = true, class Pre = NoPre>
; __device__ __forceinline__ void gemm_phase(LAS unsigned char* lds, const Gemm g, const StaticOrder& S, const Epi& E, int wv, const Pre& pre = Pre()) {
;     ...
;         for (int t = th; t < th + (Epi::MIDK ? nt / 2 : nt); t += 2) {
;             const bool last = (t == nt - 2);
;             const char* a1 = cA + (size_t)(t + 1) * kstep;
;             const char* a2 = last ? nA : cA + (size_t)(t + 2) * kstep; const char* b2 = last ? nB : cB + (size_t)(t + 2) * kstep;
;             const char* a3 = a2 + kstep; const char* b3 = b2 + kstep;
;             int lf_ = EARLY_DRAIN ? __builtin_amdgcn_readfirstlane(landed_flag) : landed_flag; if constexpr (EARLY_DRAIN) asm volatile("" : "+s"(lf_)); landed_flag = 0;
;             PG8_LDB(B0, 0, 0); PG8_LDB(B1, 0, 1); PG8_SCHED; PG8_LDA(At, 0, 0); PG8_STAGE(PG8_SA(1, 1), a1 + ahs, voffA);
;             if (!lf_) PG8_WAIT_V(8);
;             PG8_WAIT_L(0); PG8_BAR; PG8_MMA(0, 0, At, B0); PG8_MMA(0, 1, At, B1); PG8_BAR; PG8_SCHED;
;             PG8_LDA(At, 0, 1); PG8_STAGE(PG8_SB(0, 0), b2, voffB); PG8_STAGE(PG8_SB(0, 1), b2 + bhs, voffB); PG8_STAGE(PG8_SA(0, 0), a2, voffA);
;             if (!lf_) PG8_WAIT_V(8);
;             PG8_WAIT_L(0); PG8_BAR; PG8_MMA(1, 0, At, B0); PG8_MMA(1, 1, At, B1); PG8_BAR; PG8_SCHED;
;             PG8_LDB(B0, 1, 0); PG8_LDB(B1, 1, 1); PG8_SCHED; PG8_LDA(At, 1, 0); PG8_STAGE(PG8_SA(0, 1), a2 + ahs, voffA);
;             if (!lf_) PG8_WAIT_V(8);
;             PG8_WAIT_L(0); PG8_BAR; PG8_MMA(0, 0, At, B0); PG8_MMA(0, 1, At, B1); PG8_BAR; PG8_SCHED;
;             PG8_LDA(At, 1, 1); PG8_STAGE(PG8_SB(1, 0), b3, voffB); PG8_STAGE(PG8_SB(1, 1), b3 + bhs, voffB); PG8_STAGE(PG8_SA(1, 0), a3, voffA);
;             PG8_WAIT_V(8); PG8_WAIT_L(0); PG8_BAR; PG8_MMA(1, 0, At, B0); PG8_MMA(1, 1, At, B1); PG8_BAR; PG8_SCHED;
.LBB0_180:
	s_waitcnt lgkmcnt(0)
	s_cmp_eq_u32 s64, 12
	s_cselect_b32 s85, s61, s51
	s_cselect_b32 s84, s60, s50
	s_cselect_b32 s71, s43, s53
	s_cselect_b32 s70, s47, s52
	s_barrier
	s_setprio 1
	s_waitcnt lgkmcnt(7)
	v_mfma_f32_16x16x32_bf16 v[122:125], v[146:149], v[186:189], v[122:125]
	v_mfma_f32_16x16x32_bf16 v[114:117], v[154:157], v[186:189], v[114:117]
	s_waitcnt lgkmcnt(5)
	v_mfma_f32_16x16x32_bf16 v[106:109], v[146:149], v[178:181], v[106:109]
	v_mfma_f32_16x16x32_bf16 v[98:101], v[154:157], v[178:181], v[98:101]
	s_waitcnt lgkmcnt(3)
	v_mfma_f32_16x16x32_bf16 v[90:93], v[146:149], v[170:173], v[90:93]
	v_mfma_f32_16x16x32_bf16 v[82:85], v[154:157], v[170:173], v[82:85]
	s_waitcnt lgkmcnt(1)
	v_mfma_f32_16x16x32_bf16 v[62:65], v[146:149], v[162:165], v[62:65]
	v_mfma_f32_16x16x32_bf16 v[50:53], v[154:157], v[162:165], v[50:53]
	v_mfma_f32_16x16x32_bf16 v[122:125], v[150:153], v[190:193], v[122:125]
	v_mfma_f32_16x16x32_bf16 v[114:117], v[158:161], v[190:193], v[114:117]
	v_mfma_f32_16x16x32_bf16 v[106:109], v[150:153], v[182:185], v[106:109]
	v_mfma_f32_16x16x32_bf16 v[98:101], v[158:161], v[182:185], v[98:101]
	v_mfma_f32_16x16x32_bf16 v[90:93], v[150:153], v[174:177], v[90:93]
	v_mfma_f32_16x16x32_bf16 v[82:85], v[158:161], v[174:177], v[82:85]
	s_waitcnt lgkmcnt(0)
	v_mfma_f32_16x16x32_bf16 v[62:65], v[150:153], v[166:169], v[62:65]
	v_mfma_f32_16x16x32_bf16 v[50:53], v[158:161], v[166:169], v[50:53]
	s_setprio 0
	s_setprio 1
	v_mfma_f32_16x16x32_bf16 v[126:129], v[130:133], v[186:189], v[126:129]
	v_mfma_f32_16x16x32_bf16 v[118:121], v[138:141], v[186:189], v[118:121]
	v_mfma_f32_16x16x32_bf16 v[110:113], v[130:133], v[178:181], v[110:113]
	v_mfma_f32_16x16x32_bf16 v[102:105], v[138:141], v[178:181], v[102:105]
	v_mfma_f32_16x16x32_bf16 v[94:97], v[130:133], v[170:173], v[94:97]
	v_mfma_f32_16x16x32_bf16 v[86:89], v[138:141], v[170:173], v[86:89]
	v_mfma_f32_16x16x32_bf16 v[70:73], v[130:133], v[162:165], v[70:73]
	v_mfma_f32_16x16x32_bf16 v[54:57], v[138:141], v[162:165], v[54:57]
	v_mfma_f32_16x16x32_bf16 v[126:129], v[134:137], v[190:193], v[126:129]
	v_mfma_f32_16x16x32_bf16 v[118:121], v[142:145], v[190:193], v[118:121]
	v_mfma_f32_16x16x32_bf16 v[110:113], v[134:137], v[182:185], v[110:113]
	v_mfma_f32_16x16x32_bf16 v[102:105], v[142:145], v[182:185], v[102:105]
	v_mfma_f32_16x16x32_bf16 v[94:97], v[134:137], v[174:177], v[94:97]
	v_mfma_f32_16x16x32_bf16 v[86:89], v[142:145], v[174:177], v[86:89]
	v_mfma_f32_16x16x32_bf16 v[70:73], v[134:137], v[166:169], v[70:73]
	v_mfma_f32_16x16x32_bf16 v[54:57], v[142:145], v[166:169], v[54:57]
	s_setprio 0
	s_barrier
	ds_read_b128 v[186:189], v244 offset:16384
	ds_read_b128 v[190:193], v244 offset:17408
	ds_read_b128 v[178:181], v244 offset:18432
	ds_read_b128 v[182:185], v244 offset:19456
	ds_read_b128 v[170:173], v244 offset:20480
	ds_read_b128 v[174:177], v244 offset:21504
	ds_read_b128 v[162:165], v244 offset:22528
	ds_read_b128 v[166:169], v244 offset:23552
	s_mov_b32 m0, s10
	s_nop 0
	global_load_lds_dwordx4 v230, s[70:71]
	s_add_u32 m0, m0, 0x2000
	s_nop 0
	global_load_lds_dwordx4 v232, s[70:71]
	s_add_u32 s36, s70, 0x40000
	s_addc_u32 s37, s71, 0
	s_mov_b32 m0, s12
	s_nop 0
	global_load_lds_dwordx4 v230, s[36:37]
	s_add_u32 m0, m0, 0x2000
	s_nop 0
	global_load_lds_dwordx4 v232, s[36:37]
	v_cndmask_b32_e64 v194, 0, 1, s[86:87]
	s_mov_b32 m0, s5
	s_nop 0
	global_load_lds_dwordx4 v0, s[84:85]
	s_add_u32 m0, m0, 0x2000
	s_nop 0
	global_load_lds_dwordx4 v231, s[84:85]
	v_cmp_ne_u32_e64 s[36:37], 1, v194
	s_andn2_b64 vcc, exec, s[86:87]
	s_cbranch_vccnz .LBB0_182
	s_waitcnt vmcnt(8)
.LBB0_182:
	s_waitcnt lgkmcnt(0)
	s_barrier
	s_setprio 1
	s_waitcnt lgkmcnt(7)
	v_mfma_f32_16x16x32_bf16 v[74:77], v[146:149], v[186:189], v[74:77]
	v_mfma_f32_16x16x32_bf16 v[58:61], v[154:157], v[186:189], v[58:61]
	s_waitcnt lgkmcnt(5)
	v_mfma_f32_16x16x32_bf16 v[42:45], v[146:149], v[178:181], v[42:45]
	v_mfma_f32_16x16x32_bf16 v[34:37], v[154:157], v[178:181], v[34:37]
	s_waitcnt lgkmcnt(3)
	v_mfma_f32_16x16x32_bf16 v[26:29], v[146:149], v[170:173], v[26:29]
	v_mfma_f32_16x16x32_bf16 v[18:21], v[154:157], v[170:173], v[18:21]
	s_waitcnt lgkmcnt(1)
	v_mfma_f32_16x16x32_bf16 v[10:13], v[146:149], v[162:165], v[10:13]
	v_mfma_f32_16x16x32_bf16 v[2:5], v[154:157], v[162:165], v[2:5]
	v_mfma_f32_16x16x32_bf16 v[74:77], v[150:153], v[190:193], v[74:77]
	v_mfma_f32_16x16x32_bf16 v[58:61], v[158:161], v[190:193], v[58:61]
	v_mfma_f32_16x16x32_bf16 v[42:45], v[150:153], v[182:185], v[42:45]
	v_mfma_f32_16x16x32_bf16 v[34:37], v[158:161], v[182:185], v[34:37]
	v_mfma_f32_16x16x32_bf16 v[26:29], v[150:153], v[174:177], v[26:29]
	v_mfma_f32_16x16x32_bf16 v[18:21], v[158:161], v[174:177], v[18:21]
	s_waitcnt lgkmcnt(0)
	v_mfma_f32_16x16x32_bf16 v[10:13], v[150:153], v[166:169], v[10:13]
	v_mfma_f32_16x16x32_bf16 v[2:5], v[158:161], v[166:169], v[2:5]
	s_setprio 0
	s_setprio 1
	v_mfma_f32_16x16x32_bf16 v[78:81], v[130:133], v[186:189], v[78:81]
	v_mfma_f32_16x16x32_bf16 v[66:69], v[138:141], v[186:189], v[66:69]
	v_mfma_f32_16x16x32_bf16 v[46:49], v[130:133], v[178:181], v[46:49]
	v_mfma_f32_16x16x32_bf16 v[38:41], v[138:141], v[178:181], v[38:41]
	v_mfma_f32_16x16x32_bf16 v[30:33], v[130:133], v[170:173], v[30:33]
	v_mfma_f32_16x16x32_bf16 v[22:25], v[138:141], v[170:173], v[22:25]
	v_mfma_f32_16x16x32_bf16 v[14:17], v[130:133], v[162:165], v[14:17]
	v_mfma_f32_16x16x32_bf16 v[6:9], v[138:141], v[162:165], v[6:9]
	v_mfma_f32_16x16x32_bf16 v[78:81], v[134:137], v[190:193], v[78:81]
	v_mfma_f32_16x16x32_bf16 v[66:69], v[142:145], v[190:193], v[66:69]
	v_mfma_f32_16x16x32_bf16 v[46:49], v[134:137], v[182:185], v[46:49]
	v_mfma_f32_16x16x32_bf16 v[38:41], v[142:145], v[182:185], v[38:41]
	v_mfma_f32_16x16x32_bf16 v[30:33], v[134:137], v[174:177], v[30:33]
	v_mfma_f32_16x16x32_bf16 v[22:25], v[142:145], v[174:177], v[22:25]
	v_mfma_f32_16x16x32_bf16 v[14:17], v[134:137], v[166:169], v[14:17]
	v_mfma_f32_16x16x32_bf16 v[6:9], v[142:145], v[166:169], v[6:9]
	s_setprio 0
	s_barrier
	ds_read_b128 v[146:149], v234
	ds_read_b128 v[150:153], v234 offset:1024
	ds_read_b128 v[154:157], v234 offset:2048
	ds_read_b128 v[158:161], v234 offset:3072
	ds_read_b128 v[130:133], v235
	ds_read_b128 v[134:137], v235 offset:1024
	ds_read_b128 v[138:141], v235 offset:2048
	ds_read_b128 v[142:145], v235 offset:3072
	ds_read_b128 v[186:189], v244 offset:32768
	ds_read_b128 v[190:193], v244 offset:33792
	ds_read_b128 v[178:181], v244 offset:34816
	ds_read_b128 v[182:185], v244 offset:35840
	ds_read_b128 v[170:173], v244 offset:36864
	ds_read_b128 v[174:177], v244 offset:37888
	ds_read_b128 v[162:165], v244 offset:38912
	ds_read_b128 v[166:169], v244 offset:39936
	s_add_u32 s66, s84, 0x40000
	s_addc_u32 s67, s85, 0
	s_mov_b32 m0, s13
	s_nop 0
	global_load_lds_dwordx4 v0, s[66:67]
	s_add_u32 m0, m0, 0x2000
	s_nop 0
	global_load_lds_dwordx4 v231, s[66:67]
	s_and_b64 vcc, exec, s[36:37]
	s_cbranch_vccnz .LBB0_177
	s_waitcnt vmcnt(8)
	s_branch .LBB0_177

; #define PG8_STAGE(bufoff, gbase, voff) glds16s2((voff)[0], (voff)[1], (const void*)(gbase), ldsn + (unsigned)(bufoff))
; #define PG8_LDA(dst, b, h) do { _Pragma("unroll") for (int m = 0; m < 4; ++m) _Pragma("unroll") for (int k = 0; k < 2; ++k) dst[m][k] = *(const LAS bf16x8*)(lds + PG8_SA(b, h) + aoff + m * 2048 + k * 1024); } while (0)
; template <class Epi, bool ALIGN_EPI, bool EARLY_DRAIN = true, class Pre = NoPre>
; __device__ __forceinline__ void gemm_phase(LAS unsigned char* lds, const Gemm g, const StaticOrder& S, const Epi& E, int wv, const Pre& pre = Pre()) {
;     ...
;         for (int th = 0; th < nt; th += (Epi::MIDK ? nt / 2 : nt)) {
;         if constexpr (Epi::MIDK) { if (th) E.midk(acc, ui, wr, fr); }
;         for (int t = th; t < th + (Epi::MIDK ? nt / 2 : nt); t += 2) {
;             const bool last = (t == nt - 2);
;             const char* a1 = cA + (size_t)(t + 1) * kstep;
;             const char* a2 = last ? nA : cA + (size_t)(t + 2) * kstep; const char* b2 = last ? nB : cB + (size_t)(t + 2) * kstep;
;             const char* a3 = a2 + kstep; const char* b3 = b2 + kstep;
;             int lf_ = EARLY_DRAIN ? __builtin_amdgcn_readfirstlane(landed_flag) : landed_flag; if constexpr (EARLY_DRAIN) asm volatile("" : "+s"(lf_)); landed_flag = 0;
;             PG8_LDB(B0, 0, 0); PG8_LDB(B1, 0, 1); PG8_SCHED; PG8_LDA(At, 0, 0); PG8_STAGE(PG8_SA(1, 1), a1 + ahs, voffA);
;             if (!lf_) PG8_WAIT_V(8);
;             PG8_WAIT_L(0); PG8_BAR; PG8_MMA(0, 0, At, B0); PG8_MMA(0, 1, At, B1); PG8_BAR; PG8_SCHED;
;             PG8_LDA(At, 0, 1); PG8_STAGE(PG8_SB(0, 0), b2, voffB); PG8_STAGE(PG8_SB(0, 1), b2 + bhs, voffB); PG8_STAGE(PG8_SA(0, 0), a2, voffA);
;             if (!lf_) PG8_WAIT_V(8);
;             PG8_WAIT_L(0); PG8_BAR; PG8_MMA(1, 0, At, B0); PG8_MMA(1, 1, At, B1); PG8_BAR; PG8_SCHED;
;             PG8_LDB(B0, 1, 0); PG8_LDB(B1, 1, 1); PG8_SCHED; PG8_LDA(At, 1, 0); PG8_STAGE(PG8_SA(0, 1), a2 + ahs, voffA);
;             if (!lf_) PG8_WAIT_V(8);
;             PG8_WAIT_L(0); PG8_BAR; PG8_MMA(0, 0, At, B0); PG8_MMA(0, 1, At, B1); PG8_BAR; PG8_SCHED;
;             PG8_LDA(At, 1, 1); PG8_STAGE(PG8_SB(1, 0), b3, voffB); PG8_STAGE(PG8_SB(1, 1), b3 + bhs, voffB); PG8_STAGE(PG8_SA(1, 0), a3, voffA);
;             PG8_WAIT_V(8); PG8_WAIT_L(0); PG8_BAR; PG8_MMA(1, 0, At, B0); PG8_MMA(1, 1, At, B1); PG8_BAR; PG8_SCHED;
;         }
.LBB0_442:
	v_add_u32_e32 v0, 0x10000, v203
	ds_read_b128 v[166:169], v0
	ds_read_b128 v[170:173], v0 offset:1024
	ds_read_b128 v[174:177], v0 offset:2048
	ds_read_b128 v[178:181], v0 offset:3072
	v_add_u32_e32 v0, 0x14000, v203
	ds_read_b128 v[182:185], v0
	ds_read_b128 v[186:189], v0 offset:1024
	ds_read_b128 v[190:193], v0 offset:2048
	ds_read_b128 v[194:197], v0 offset:3072
	s_add_i32 s91, s20, 2
	s_cmp_eq_u32 s20, 14
	s_cselect_b32 s86, s45, vcc_lo
	s_cselect_b32 s87, s37, vcc_hi
	s_cselect_b32 s84, s67, s76
	s_cselect_b32 s85, s65, s77
	s_add_u32 s70, s86, 0x80
	s_addc_u32 s71, s87, 0
	ds_read_b128 v[206:209], v204
	ds_read_b128 v[210:213], v204 offset:1024
	ds_read_b128 v[214:217], v204 offset:2048
	ds_read_b128 v[218:221], v204 offset:3072
	ds_read_b128 v[222:225], v204 offset:4096
	ds_read_b128 v[226:229], v204 offset:5120
	ds_read_b128 v[230:233], v204 offset:6144
	ds_read_b128 v[234:237], v204 offset:7168
	s_mov_b32 m0, s26
	s_nop 0
	global_load_lds_dwordx4 v198, s[68:69]
	s_add_u32 m0, m0, 0x2000
	s_nop 0
	global_load_lds_dwordx4 v200, s[68:69]
	s_waitcnt vmcnt(8)
	s_waitcnt lgkmcnt(0)
	s_barrier
	s_setprio 1
	s_waitcnt lgkmcnt(7)
	v_mfma_f32_16x16x32_bf16 v[160:163], v[166:169], v[206:209], v[160:163]
	v_mfma_f32_16x16x32_bf16 v[156:159], v[174:177], v[206:209], v[156:159]
	s_waitcnt lgkmcnt(5)
	v_mfma_f32_16x16x32_bf16 v[144:147], v[166:169], v[214:217], v[144:147]
	v_mfma_f32_16x16x32_bf16 v[140:143], v[174:177], v[214:217], v[140:143]
	s_waitcnt lgkmcnt(3)
	v_mfma_f32_16x16x32_bf16 v[124:127], v[166:169], v[222:225], v[124:127]
	v_mfma_f32_16x16x32_bf16 v[116:119], v[174:177], v[222:225], v[116:119]
	s_waitcnt lgkmcnt(1)
	v_mfma_f32_16x16x32_bf16 v[96:99], v[166:169], v[230:233], v[96:99]
	v_mfma_f32_16x16x32_bf16 v[92:95], v[174:177], v[230:233], v[92:95]
	v_mfma_f32_16x16x32_bf16 v[160:163], v[170:173], v[210:213], v[160:163]
	v_mfma_f32_16x16x32_bf16 v[156:159], v[178:181], v[210:213], v[156:159]
	v_mfma_f32_16x16x32_bf16 v[144:147], v[170:173], v[218:221], v[144:147]
	v_mfma_f32_16x16x32_bf16 v[140:143], v[178:181], v[218:221], v[140:143]
	v_mfma_f32_16x16x32_bf16 v[124:127], v[170:173], v[226:229], v[124:127]
	v_mfma_f32_16x16x32_bf16 v[116:119], v[178:181], v[226:229], v[116:119]
	s_waitcnt lgkmcnt(0)
	v_mfma_f32_16x16x32_bf16 v[96:99], v[170:173], v[234:237], v[96:99]
	v_mfma_f32_16x16x32_bf16 v[92:95], v[178:181], v[234:237], v[92:95]
	s_setprio 0
	s_setprio 1
	v_mfma_f32_16x16x32_bf16 v[152:155], v[182:185], v[206:209], v[152:155]
	v_mfma_f32_16x16x32_bf16 v[148:151], v[190:193], v[206:209], v[148:151]
	v_mfma_f32_16x16x32_bf16 v[136:139], v[182:185], v[214:217], v[136:139]
	v_mfma_f32_16x16x32_bf16 v[132:135], v[190:193], v[214:217], v[132:135]
	v_mfma_f32_16x16x32_bf16 v[112:115], v[182:185], v[222:225], v[112:115]
	v_mfma_f32_16x16x32_bf16 v[108:111], v[190:193], v[222:225], v[108:111]
	v_mfma_f32_16x16x32_bf16 v[88:91], v[182:185], v[230:233], v[88:91]
	v_mfma_f32_16x16x32_bf16 v[80:83], v[190:193], v[230:233], v[80:83]
	v_mfma_f32_16x16x32_bf16 v[152:155], v[186:189], v[210:213], v[152:155]
	v_mfma_f32_16x16x32_bf16 v[148:151], v[194:197], v[210:213], v[148:151]
	v_mfma_f32_16x16x32_bf16 v[136:139], v[186:189], v[218:221], v[136:139]
	v_mfma_f32_16x16x32_bf16 v[132:135], v[194:197], v[218:221], v[132:135]
	v_mfma_f32_16x16x32_bf16 v[112:115], v[186:189], v[226:229], v[112:115]
	v_mfma_f32_16x16x32_bf16 v[108:111], v[194:197], v[226:229], v[108:111]
	v_mfma_f32_16x16x32_bf16 v[88:91], v[186:189], v[234:237], v[88:91]
	v_mfma_f32_16x16x32_bf16 v[80:83], v[194:197], v[234:237], v[80:83]
	s_setprio 0
	s_barrier
	ds_read_b128 v[206:209], v204 offset:16384
	ds_read_b128 v[210:213], v204 offset:17408
	ds_read_b128 v[214:217], v204 offset:18432
	ds_read_b128 v[218:221], v204 offset:19456
	ds_read_b128 v[222:225], v204 offset:20480
	ds_read_b128 v[226:229], v204 offset:21504
	ds_read_b128 v[230:233], v204 offset:22528
	ds_read_b128 v[234:237], v204 offset:23552
	s_mov_b32 m0, s10
	s_nop 0
	global_load_lds_dwordx4 v199, s[84:85]
	s_add_u32 m0, m0, 0x2000
	s_nop 0
	global_load_lds_dwordx4 v201, s[84:85]
	s_add_u32 s14, s84, 0x40000
	s_addc_u32 s15, s85, 0
	s_mov_b32 m0, s12
	s_nop 0
	global_load_lds_dwordx4 v199, s[14:15]
	s_add_u32 m0, m0, 0x2000
	s_nop 0
	global_load_lds_dwordx4 v201, s[14:15]
	s_nop 0
	s_mov_b32 m0, s89
	s_nop 0
	global_load_lds_dwordx4 v198, s[86:87]
	s_add_u32 m0, m0, 0x2000
	s_nop 0
	global_load_lds_dwordx4 v200, s[86:87]
	s_waitcnt vmcnt(8)
	s_waitcnt lgkmcnt(0)
	s_barrier
; #define PG8_STAGE(bufoff, gbase, voff) glds16s2((voff)[0], (voff)[1], (const void*)(gbase), ldsn + (unsigned)(bufoff))
; #define PG8_LDA(dst, b, h) do { _Pragma("unroll") for (int m = 0; m < 4; ++m) _Pragma("unroll") for (int k = 0; k < 2; ++k) dst[m][k] = *(const LAS bf16x8*)(lds + PG8_SA(b, h) + aoff + m * 2048 + k * 1024); } while (0)
; #define PG8_WAIT_V(n) asm volatile("s_waitcnt vmcnt(" #n ")" ::: "memory")
; #define PG8_WAIT_L(n) asm volatile("s_waitcnt lgkmcnt(" #n ")" ::: "memory")
; template <class Epi, bool ALIGN_EPI, bool EARLY_DRAIN = true, class Pre = NoPre>
; __device__ __forceinline__ void gemm_phase(LAS unsigned char* lds, const Gemm g, const StaticOrder& S, const Epi& E, int wv, const Pre& pre = Pre()) {
;     ...
;         for (int t = th; t < th + (Epi::MIDK ? nt / 2 : nt); t += 2) {
;             const bool last = (t == nt - 2);
;             const char* a1 = cA + (size_t)(t + 1) * kstep;
;             const char* a2 = last ? nA : cA + (size_t)(t + 2) * kstep; const char* b2 = last ? nB : cB + (size_t)(t + 2) * kstep;
;             const char* a3 = a2 + kstep; const char* b3 = b2 + kstep;
;             int lf_ = EARLY_DRAIN ? __builtin_amdgcn_readfirstlane(landed_flag) : landed_flag; if constexpr (EARLY_DRAIN) asm volatile("" : "+s"(lf_)); landed_flag = 0;
;             PG8_LDB(B0, 0, 0); PG8_LDB(B1, 0, 1); PG8_SCHED; PG8_LDA(At, 0, 0); PG8_STAGE(PG8_SA(1, 1), a1 + ahs, voffA);
;             if (!lf_) PG8_WAIT_V(8);
;             PG8_WAIT_L(0); PG8_BAR; PG8_MMA(0, 0, At, B0); PG8_MMA(0, 1, At, B1); PG8_BAR; PG8_SCHED;
;             PG8_LDA(At, 0, 1); PG8_STAGE(PG8_SB(0, 0), b2, voffB); PG8_STAGE(PG8_SB(0, 1), b2 + bhs, voffB); PG8_STAGE(PG8_SA(0, 0), a2, voffA);
;             if (!lf_) PG8_WAIT_V(8);
;             PG8_WAIT_L(0); PG8_BAR; PG8_MMA(1, 0, At, B0); PG8_MMA(1, 1, At, B1); PG8_BAR; PG8_SCHED;
;             PG8_LDB(B0, 1, 0); PG8_LDB(B1, 1, 1); PG8_SCHED; PG8_LDA(At, 1, 0); PG8_STAGE(PG8_SA(0, 1), a2 + ahs, voffA);
;             if (!lf_) PG8_WAIT_V(8);
;             PG8_WAIT_L(0); PG8_BAR; PG8_MMA(0, 0, At, B0); PG8_MMA(0, 1, At, B1); PG8_BAR; PG8_SCHED;
;             PG8_LDA(At, 1, 1); PG8_STAGE(PG8_SB(1, 0), b3, voffB); PG8_STAGE(PG8_SB(1, 1), b3 + bhs, voffB); PG8_STAGE(PG8_SA(1, 0), a3, voffA);
;             PG8_WAIT_V(8); PG8_WAIT_L(0); PG8_BAR; PG8_MMA(1, 0, At, B0); PG8_MMA(1, 1, At, B1); PG8_BAR; PG8_SCHED;
	s_setprio 1
	s_waitcnt lgkmcnt(7)
	v_mfma_f32_16x16x32_bf16 v[72:75], v[166:169], v[206:209], v[72:75]
	v_mfma_f32_16x16x32_bf16 v[68:71], v[174:177], v[206:209], v[68:71]
	s_waitcnt lgkmcnt(5)
	v_mfma_f32_16x16x32_bf16 v[48:51], v[166:169], v[214:217], v[48:51]
	v_mfma_f32_16x16x32_bf16 v[44:47], v[174:177], v[214:217], v[44:47]
	s_waitcnt lgkmcnt(3)
	v_mfma_f32_16x16x32_bf16 v[32:35], v[166:169], v[222:225], v[32:35]
	v_mfma_f32_16x16x32_bf16 v[28:31], v[174:177], v[222:225], v[28:31]
	s_waitcnt lgkmcnt(1)
	v_mfma_f32_16x16x32_bf16 v[16:19], v[166:169], v[230:233], v[16:19]
	v_mfma_f32_16x16x32_bf16 v[12:15], v[174:177], v[230:233], v[12:15]
	v_mfma_f32_16x16x32_bf16 v[72:75], v[170:173], v[210:213], v[72:75]
	v_mfma_f32_16x16x32_bf16 v[68:71], v[178:181], v[210:213], v[68:71]
	v_mfma_f32_16x16x32_bf16 v[48:51], v[170:173], v[218:221], v[48:51]
	v_mfma_f32_16x16x32_bf16 v[44:47], v[178:181], v[218:221], v[44:47]
	v_mfma_f32_16x16x32_bf16 v[32:35], v[170:173], v[226:229], v[32:35]
	v_mfma_f32_16x16x32_bf16 v[28:31], v[178:181], v[226:229], v[28:31]
	s_waitcnt lgkmcnt(0)
	v_mfma_f32_16x16x32_bf16 v[16:19], v[170:173], v[234:237], v[16:19]
	v_mfma_f32_16x16x32_bf16 v[12:15], v[178:181], v[234:237], v[12:15]
	s_setprio 0
	s_setprio 1
	v_mfma_f32_16x16x32_bf16 v[60:63], v[182:185], v[206:209], v[60:63]
	v_mfma_f32_16x16x32_bf16 v[56:59], v[190:193], v[206:209], v[56:59]
	v_mfma_f32_16x16x32_bf16 v[40:43], v[182:185], v[214:217], v[40:43]
	v_mfma_f32_16x16x32_bf16 v[36:39], v[190:193], v[214:217], v[36:39]
	v_mfma_f32_16x16x32_bf16 v[24:27], v[182:185], v[222:225], v[24:27]
	v_mfma_f32_16x16x32_bf16 v[20:23], v[190:193], v[222:225], v[20:23]
	v_mfma_f32_16x16x32_bf16 v[8:11], v[182:185], v[230:233], v[8:11]
	v_mfma_f32_16x16x32_bf16 v[2:5], v[190:193], v[230:233], v[4:7]
	v_mfma_f32_16x16x32_bf16 v[60:63], v[186:189], v[210:213], v[60:63]
	v_mfma_f32_16x16x32_bf16 v[56:59], v[194:197], v[210:213], v[56:59]
	v_mfma_f32_16x16x32_bf16 v[40:43], v[186:189], v[218:221], v[40:43]
	v_mfma_f32_16x16x32_bf16 v[36:39], v[194:197], v[218:221], v[36:39]
	v_mfma_f32_16x16x32_bf16 v[24:27], v[186:189], v[226:229], v[24:27]
	v_mfma_f32_16x16x32_bf16 v[20:23], v[194:197], v[226:229], v[20:23]
	v_mfma_f32_16x16x32_bf16 v[8:11], v[186:189], v[234:237], v[8:11]
	v_mfma_f32_16x16x32_bf16 v[2:5], v[194:197], v[234:237], v[2:5]
	s_setprio 0
	s_barrier
	v_add_u32_e32 v0, 0x18000, v203
	ds_read_b128 v[166:169], v0
	ds_read_b128 v[170:173], v0 offset:1024
	ds_read_b128 v[174:177], v0 offset:2048
	ds_read_b128 v[178:181], v0 offset:3072
	v_add_u32_e32 v0, 0x1c000, v203
	ds_read_b128 v[182:185], v0
	ds_read_b128 v[186:189], v0 offset:1024
	ds_read_b128 v[190:193], v0 offset:2048
	ds_read_b128 v[194:197], v0 offset:3072
	ds_read_b128 v[206:209], v204 offset:32768
	ds_read_b128 v[210:213], v204 offset:33792
	ds_read_b128 v[214:217], v204 offset:34816
	ds_read_b128 v[218:221], v204 offset:35840
	ds_read_b128 v[222:225], v204 offset:36864
	ds_read_b128 v[226:229], v204 offset:37888
	ds_read_b128 v[230:233], v204 offset:38912
	ds_read_b128 v[234:237], v204 offset:39936
	s_add_u32 s14, s86, 0x40000
	s_addc_u32 s15, s87, 0
	s_mov_b32 m0, s13
	s_nop 0
	global_load_lds_dwordx4 v198, s[14:15]
	s_add_u32 m0, m0, 0x2000
	s_nop 0
	global_load_lds_dwordx4 v200, s[14:15]
	s_waitcnt vmcnt(8)
	s_waitcnt lgkmcnt(0)
	s_barrier
	s_setprio 1
	s_waitcnt lgkmcnt(7)
	v_mfma_f32_16x16x32_bf16 v[160:163], v[166:169], v[206:209], v[160:163]
	v_mfma_f32_16x16x32_bf16 v[156:159], v[174:177], v[206:209], v[156:159]
	s_waitcnt lgkmcnt(5)
	v_mfma_f32_16x16x32_bf16 v[144:147], v[166:169], v[214:217], v[144:147]
	v_mfma_f32_16x16x32_bf16 v[140:143], v[174:177], v[214:217], v[140:143]
	s_waitcnt lgkmcnt(3)
	v_mfma_f32_16x16x32_bf16 v[124:127], v[166:169], v[222:225], v[124:127]
	v_mfma_f32_16x16x32_bf16 v[116:119], v[174:177], v[222:225], v[116:119]
	s_waitcnt lgkmcnt(1)
	v_mfma_f32_16x16x32_bf16 v[96:99], v[166:169], v[230:233], v[96:99]
	v_mfma_f32_16x16x32_bf16 v[92:95], v[174:177], v[230:233], v[92:95]
	v_mfma_f32_16x16x32_bf16 v[160:163], v[170:173], v[210:213], v[160:163]
	v_mfma_f32_16x16x32_bf16 v[156:159], v[178:181], v[210:213], v[156:159]
	v_mfma_f32_16x16x32_bf16 v[144:147], v[170:173], v[218:221], v[144:147]
	v_mfma_f32_16x16x32_bf16 v[140:143], v[178:181], v[218:221], v[140:143]
	v_mfma_f32_16x16x32_bf16 v[124:127], v[170:173], v[226:229], v[124:127]
	v_mfma_f32_16x16x32_bf16 v[116:119], v[178:181], v[226:229], v[116:119]
	s_waitcnt lgkmcnt(0)
	v_mfma_f32_16x16x32_bf16 v[96:99], v[170:173], v[234:237], v[96:99]
	v_mfma_f32_16x16x32_bf16 v[92:95], v[178:181], v[234:237], v[92:95]
	s_setprio 0
	s_setprio 1
	v_mfma_f32_16x16x32_bf16 v[152:155], v[182:185], v[206:209], v[152:155]
	v_mfma_f32_16x16x32_bf16 v[148:151], v[190:193], v[206:209], v[148:151]
	v_mfma_f32_16x16x32_bf16 v[136:139], v[182:185], v[214:217], v[136:139]
	v_mfma_f32_16x16x32_bf16 v[132:135], v[190:193], v[214:217], v[132:135]
	v_mfma_f32_16x16x32_bf16 v[112:115], v[182:185], v[222:225], v[112:115]
	v_mfma_f32_16x16x32_bf16 v[108:111], v[190:193], v[222:225], v[108:111]
	v_mfma_f32_16x16x32_bf16 v[88:91], v[182:185], v[230:233], v[88:91]
	v_mfma_f32_16x16x32_bf16 v[80:83], v[190:193], v[230:233], v[80:83]
	v_mfma_f32_16x16x32_bf16 v[152:155], v[186:189], v[210:213], v[152:155]
	v_mfma_f32_16x16x32_bf16 v[148:151], v[194:197], v[210:213], v[148:151]
	v_mfma_f32_16x16x32_bf16 v[136:139], v[186:189], v[218:221], v[136:139]
	v_mfma_f32_16x16x32_bf16 v[132:135], v[194:197], v[218:221], v[132:135]
	v_mfma_f32_16x16x32_bf16 v[112:115], v[186:189], v[226:229], v[112:115]
	v_mfma_f32_16x16x32_bf16 v[108:111], v[194:197], v[226:229], v[108:111]
	v_mfma_f32_16x16x32_bf16 v[88:91], v[186:189], v[234:237], v[88:91]
	v_mfma_f32_16x16x32_bf16 v[80:83], v[194:197], v[234:237], v[80:83]
	s_setprio 0
	s_barrier
; #define PG8_STAGE(bufoff, gbase, voff) glds16s2((voff)[0], (voff)[1], (const void*)(gbase), ldsn + (unsigned)(bufoff))
; #define PG8_LDA(dst, b, h) do { _Pragma("unroll") for (int m = 0; m < 4; ++m) _Pragma("unroll") for (int k = 0; k < 2; ++k) dst[m][k] = *(const LAS bf16x8*)(lds + PG8_SA(b, h) + aoff + m * 2048 + k * 1024); } while (0)
; #define PG8_WAIT_V(n) asm volatile("s_waitcnt vmcnt(" #n ")" ::: "memory")
; template <class Epi, bool ALIGN_EPI, bool EARLY_DRAIN = true, class Pre = NoPre>
; __device__ __forceinline__ void gemm_phase(LAS unsigned char* lds, const Gemm g, const StaticOrder& S, const Epi& E, int wv, const Pre& pre = Pre()) {
;     ...
;         for (int t = th; t < th + (Epi::MIDK ? nt / 2 : nt); t += 2) {
;             const bool last = (t == nt - 2);
;             const char* a1 = cA + (size_t)(t + 1) * kstep;
;             const char* a2 = last ? nA : cA + (size_t)(t + 2) * kstep; const char* b2 = last ? nB : cB + (size_t)(t + 2) * kstep;
;             const char* a3 = a2 + kstep; const char* b3 = b2 + kstep;
;             int lf_ = EARLY_DRAIN ? __builtin_amdgcn_readfirstlane(landed_flag) : landed_flag; if constexpr (EARLY_DRAIN) asm volatile("" : "+s"(lf_)); landed_flag = 0;
;             PG8_LDB(B0, 0, 0); PG8_LDB(B1, 0, 1); PG8_SCHED; PG8_LDA(At, 0, 0); PG8_STAGE(PG8_SA(1, 1), a1 + ahs, voffA);
;             if (!lf_) PG8_WAIT_V(8);
;             PG8_WAIT_L(0); PG8_BAR; PG8_MMA(0, 0, At, B0); PG8_MMA(0, 1, At, B1); PG8_BAR; PG8_SCHED;
;             PG8_LDA(At, 0, 1); PG8_STAGE(PG8_SB(0, 0), b2, voffB); PG8_STAGE(PG8_SB(0, 1), b2 + bhs, voffB); PG8_STAGE(PG8_SA(0, 0), a2, voffA);
;             if (!lf_) PG8_WAIT_V(8);
;             PG8_WAIT_L(0); PG8_BAR; PG8_MMA(1, 0, At, B0); PG8_MMA(1, 1, At, B1); PG8_BAR; PG8_SCHED;
;             PG8_LDB(B0, 1, 0); PG8_LDB(B1, 1, 1); PG8_SCHED; PG8_LDA(At, 1, 0); PG8_STAGE(PG8_SA(0, 1), a2 + ahs, voffA);
;             if (!lf_) PG8_WAIT_V(8);
;             PG8_WAIT_L(0); PG8_BAR; PG8_MMA(0, 0, At, B0); PG8_MMA(0, 1, At, B1); PG8_BAR; PG8_SCHED;
;             PG8_LDA(At, 1, 1); PG8_STAGE(PG8_SB(1, 0), b3, voffB); PG8_STAGE(PG8_SB(1, 1), b3 + bhs, voffB); PG8_STAGE(PG8_SA(1, 0), a3, voffA);
;             PG8_WAIT_V(8); PG8_WAIT_L(0); PG8_BAR; PG8_MMA(1, 0, At, B0); PG8_MMA(1, 1, At, B1); PG8_BAR; PG8_SCHED;
;         }
;         }
;         if constexpr (ALIGN_EPI) { if (wr == 0) PG8_BAR; }
	ds_read_b128 v[206:209], v204 offset:49152
	ds_read_b128 v[210:213], v204 offset:50176
	ds_read_b128 v[214:217], v204 offset:51200
	ds_read_b128 v[218:221], v204 offset:52224
	ds_read_b128 v[222:225], v204 offset:53248
	ds_read_b128 v[226:229], v204 offset:54272
	ds_read_b128 v[230:233], v204 offset:55296
	ds_read_b128 v[234:237], v204 offset:56320
	s_add_u32 s14, s84, 0x80
	s_addc_u32 s15, s85, 0
	s_mov_b32 m0, s23
	s_nop 0
	global_load_lds_dwordx4 v199, s[14:15]
	s_add_u32 m0, m0, 0x2000
	s_nop 0
	global_load_lds_dwordx4 v201, s[14:15]
	s_add_u32 s14, s84, 0x40080
	s_addc_u32 s15, s85, 0
	s_mov_b32 m0, s25
	s_nop 0
	global_load_lds_dwordx4 v199, s[14:15]
	s_add_u32 m0, m0, 0x2000
	s_nop 0
	global_load_lds_dwordx4 v201, s[14:15]
	s_nop 0
	s_mov_b32 m0, s24
	s_nop 0
	global_load_lds_dwordx4 v198, s[70:71]
	s_add_u32 m0, m0, 0x2000
	s_nop 0
	global_load_lds_dwordx4 v200, s[70:71]
	s_waitcnt vmcnt(8)
	s_waitcnt lgkmcnt(0)
	s_barrier
	s_setprio 1
	s_waitcnt lgkmcnt(7)
	v_mfma_f32_16x16x32_bf16 v[72:75], v[166:169], v[206:209], v[72:75]
	v_mfma_f32_16x16x32_bf16 v[68:71], v[174:177], v[206:209], v[68:71]
	s_waitcnt lgkmcnt(5)
	v_mfma_f32_16x16x32_bf16 v[48:51], v[166:169], v[214:217], v[48:51]
	v_mfma_f32_16x16x32_bf16 v[44:47], v[174:177], v[214:217], v[44:47]
	s_waitcnt lgkmcnt(3)
	v_mfma_f32_16x16x32_bf16 v[32:35], v[166:169], v[222:225], v[32:35]
	v_mfma_f32_16x16x32_bf16 v[28:31], v[174:177], v[222:225], v[28:31]
	s_waitcnt lgkmcnt(1)
	v_mfma_f32_16x16x32_bf16 v[16:19], v[166:169], v[230:233], v[16:19]
	v_mfma_f32_16x16x32_bf16 v[12:15], v[174:177], v[230:233], v[12:15]
	v_mfma_f32_16x16x32_bf16 v[72:75], v[170:173], v[210:213], v[72:75]
	v_mfma_f32_16x16x32_bf16 v[68:71], v[178:181], v[210:213], v[68:71]
	v_mfma_f32_16x16x32_bf16 v[48:51], v[170:173], v[218:221], v[48:51]
	v_mfma_f32_16x16x32_bf16 v[44:47], v[178:181], v[218:221], v[44:47]
	v_mfma_f32_16x16x32_bf16 v[32:35], v[170:173], v[226:229], v[32:35]
	v_mfma_f32_16x16x32_bf16 v[28:31], v[178:181], v[226:229], v[28:31]
	s_waitcnt lgkmcnt(0)
	v_mfma_f32_16x16x32_bf16 v[16:19], v[170:173], v[234:237], v[16:19]
	v_mfma_f32_16x16x32_bf16 v[12:15], v[178:181], v[234:237], v[12:15]
	s_setprio 0
	s_setprio 1
	v_mfma_f32_16x16x32_bf16 v[60:63], v[182:185], v[206:209], v[60:63]
	v_mfma_f32_16x16x32_bf16 v[56:59], v[190:193], v[206:209], v[56:59]
	v_mfma_f32_16x16x32_bf16 v[40:43], v[182:185], v[214:217], v[40:43]
	v_mfma_f32_16x16x32_bf16 v[36:39], v[190:193], v[214:217], v[36:39]
	v_mfma_f32_16x16x32_bf16 v[24:27], v[182:185], v[222:225], v[24:27]
	v_mfma_f32_16x16x32_bf16 v[20:23], v[190:193], v[222:225], v[20:23]
	v_mfma_f32_16x16x32_bf16 v[6:9], v[182:185], v[230:233], v[8:11]
	v_mfma_f32_16x16x32_bf16 v[2:5], v[190:193], v[230:233], v[2:5]
	v_mfma_f32_16x16x32_bf16 v[60:63], v[186:189], v[210:213], v[60:63]
	v_mfma_f32_16x16x32_bf16 v[56:59], v[194:197], v[210:213], v[56:59]
	v_mfma_f32_16x16x32_bf16 v[40:43], v[186:189], v[218:221], v[40:43]
	v_mfma_f32_16x16x32_bf16 v[36:39], v[194:197], v[218:221], v[36:39]
	v_mfma_f32_16x16x32_bf16 v[24:27], v[186:189], v[226:229], v[24:27]
	v_mfma_f32_16x16x32_bf16 v[20:23], v[194:197], v[226:229], v[20:23]
	v_mfma_f32_16x16x32_bf16 v[8:11], v[186:189], v[234:237], v[6:9]
	v_mfma_f32_16x16x32_bf16 v[4:7], v[194:197], v[234:237], v[2:5]
	s_setprio 0
	s_barrier
	s_add_u32 s68, s68, 0x100
	s_addc_u32 s69, s69, 0
	s_add_u32 vcc_lo, vcc_lo, 0x100
	s_addc_u32 vcc_hi, vcc_hi, 0
	s_add_u32 s76, s76, 0x100
	s_addc_u32 s77, s77, 0
	s_cmp_ge_u32 s91, s0
	s_mov_b32 s20, s91
	s_cbranch_scc0 .LBB0_442
	s_mov_b32 s20, 8
	s_andn2_b64 vcc, exec, s[60:61]
	s_mov_b64 s[60:61], 0
	s_cbranch_vccnz .LBB0_439
	s_and_b64 vcc, exec, s[18:19]
	s_cbranch_vccz .LBB0_446
	s_barrier

;     __device__ bool next(int i, Unit& u) const {
;         const long L = (long)i * G + c; if (L >= nwg) return false;
;         int wgid = (int)L; { const int q = nwg / NXCD, r = nwg % NXCD, xcd = wgid % NXCD, off = wgid / NXCD; wgid = (xcd < r ? xcd * (q + 1) : r * (q + 1) + (xcd - r) * q) + off; }
;         const int nig = wgm * nN, gid = wgid / nig, fm = gid * wgm, gsz = (nM - fm) < wgm ? (nM - fm) : wgm;
;         u.pm = fm + ((wgid % nig) % gsz); u.pn = (wgid % nig) / gsz; if (rev) u.pm = nM - 1 - u.pm; return true;
; __global__ void __launch_bounds__(NWAVES * 64, 2) fwd_kernel(Args args) {
;     ...
;             { pg8::Unit u; for (int i = wave >> 2; S.next(i, u); i += 2)       { const int row = tid & 255; const int ai = row >> 7, wr = (row >> 6) & 1, m = (row >> 4) & 3, fr = row & 15;
;                 const int pp = UPM * u.pm - 1 + 126 * wr + 8 * fr + 4 * ai + m;
;                 const int tok = min(max(pp - (pp > SEQ ? 1 : 0) - (pp > 2 * SEQ + 1 ? 1 : 0), 0), M - 1);
;                 const float* p = SSX + (size_t)tok * 16;
;                 const f32x4 a = *(const f32x4*)p, b = *(const f32x4*)(p + 4), c = *(const f32x4*)(p + 8), d = *(const f32x4*)(p + 12);
;                 const float s = ((a[0] + a[1]) + (a[2] + a[3])) + ((b[0] + b[1]) + (b[2] + b[3])) + ((c[0] + c[1]) + (c[2] + c[3])) + ((d[0] + d[1]) + (d[2] + d[3]));
;                 tab[i * 256 + row] = (pp >= 0 && pp < MP && pp != SEQ && pp != 2 * SEQ + 1) ? 1.0f / sqrtf(s * (1.0f / D) + EPS) : 0.f; } }
.LBB0_522:
	v_readlane_b32 s12, v255, 2
	v_readlane_b32 s13, v255, 3
	s_xor_b64 s[22:23], s[12:13], -1
	s_xor_b64 s[24:25], s[88:89], -1
	v_readlane_b32 s14, v252, 3
	v_readlane_b32 s15, v252, 4
	s_cmp_le_i32 s14, s5
	s_cselect_b64 s[12:13], -1, 0
	s_cmp_lt_i32 s5, s15
	s_cselect_b64 s[14:15], -1, 0
	s_and_b64 s[34:35], s[12:13], s[14:15]
	s_andn2_b64 vcc, exec, s[34:35]
	s_cbranch_vccnz .LBB0_619
	v_mbcnt_lo_u32_b32 v0, -1, 0
	v_mbcnt_hi_u32_b32 v0, -1, v0
	v_readlane_b32 s0, v252, 43
	v_readlane_b32 s18, v254, 48
	v_readlane_b32 s5, v254, 51
	s_nop 0
	v_add_u32_e32 v0, s0, v0
	v_and_b32_e32 v2, 0xff, v0
	v_bfe_u32 v3, v0, 4, 2
	v_bfe_i32 v4, v0, 6, 1
	v_lshlrev_b32_e32 v5, 3, v0
	v_lshrrev_b32_e32 v0, 5, v0
	v_and_b32_e32 v5, 0x78, v5
	v_and_b32_e32 v0, 4, v0
	v_and_b32_e32 v4, 0x7e, v4
	v_or3_b32 v0, v5, v0, v3
	v_add3_u32 v0, v0, v4, -1
	v_lshl_add_u32 v2, v2, 2, s5
	v_mov_b32_e32 v175, 0xbfff
	s_mov_b32 s10, 0
	s_cmpk_lt_u32 s18, 0x10d8
	s_cbranch_scc0 .Lupre_issued
	s_and_b32 s12, s18, 7
	s_lshr_b32 s13, s18, 3
	s_mulk_i32 s12, 0x21b
	s_add_i32 s12, s12, s13
	s_lshr_b32 s13, s12, 4
	s_mul_hi_u32 s13, s13, 0xba2e8ba3
	s_lshr_b32 s13, s13, 3
	s_mul_i32 s14, s13, 0xb0
	s_sub_i32 s12, s12, s14
	s_lshl_b32 s13, s13, 3
	s_sub_i32 s14, 0xc4, s13
	s_min_u32 s14, s14, 8
	s_sub_i32 s14, s14, 1
	s_and_b32 s12, s12, s14
	s_add_i32 s12, s13, s12
	s_mulk_i32 s12, 0xfc
	v_add_u32_e32 v166, s12, v0
	v_cmp_lt_i32_e32 vcc, 0x4000, v166
	s_nop 1
	v_subbrev_co_u32_e32 v3, vcc, 0, v166, vcc
	v_cmp_lt_i32_e32 vcc, 0x8001, v166
	s_nop 1
	v_subbrev_co_u32_e32 v3, vcc, 0, v3, vcc
	v_med3_i32 v3, v3, 0, v175
	v_lshlrev_b32_e32 v3, 6, v3
	global_load_dwordx4 v[22:25], v3, s[28:29] offset:48
	global_load_dwordx4 v[26:29], v3, s[28:29] offset:32
	global_load_dwordx4 v[30:33], v3, s[28:29] offset:16
	global_load_dwordx4 v[34:37], v3, s[28:29]
	s_add_u32 s18, s18, s74
	s_add_i32 s10, s10, 1
	s_cmpk_lt_u32 s18, 0x10d8
	s_cbranch_scc0 .Lupre_issued
	s_and_b32 s12, s18, 7
	s_lshr_b32 s13, s18, 3
	s_mulk_i32 s12, 0x21b
	s_add_i32 s12, s12, s13
	s_lshr_b32 s13, s12, 4
	s_mul_hi_u32 s13, s13, 0xba2e8ba3
	s_lshr_b32 s13, s13, 3
	s_mul_i32 s14, s13, 0xb0
	s_sub_i32 s12, s12, s14
	s_lshl_b32 s13, s13, 3
	s_sub_i32 s14, 0xc4, s13
	s_min_u32 s14, s14, 8
	s_sub_i32 s14, s14, 1
	s_and_b32 s12, s12, s14
	s_add_i32 s12, s13, s12
	s_mulk_i32 s12, 0xfc
	v_add_u32_e32 v167, s12, v0
	v_cmp_lt_i32_e32 vcc, 0x4000, v167
	s_nop 1
	v_subbrev_co_u32_e32 v3, vcc, 0, v167, vcc
	v_cmp_lt_i32_e32 vcc, 0x8001, v167
	s_nop 1
	v_subbrev_co_u32_e32 v3, vcc, 0, v3, vcc
	v_med3_i32 v3, v3, 0, v175
	v_lshlrev_b32_e32 v3, 6, v3
	global_load_dwordx4 v[38:41], v3, s[28:29] offset:48
	global_load_dwordx4 v[42:45], v3, s[28:29] offset:32
	global_load_dwordx4 v[46:49], v3, s[28:29] offset:16
	global_load_dwordx4 v[50:53], v3, s[28:29]
	s_add_u32 s18, s18, s74
	s_add_i32 s10, s10, 1
	s_cmpk_lt_u32 s18, 0x10d8
	s_cbranch_scc0 .Lupre_issued
	s_and_b32 s12, s18, 7
	s_lshr_b32 s13, s18, 3
	s_mulk_i32 s12, 0x21b
	s_add_i32 s12, s12, s13
	s_lshr_b32 s13, s12, 4
	s_mul_hi_u32 s13, s13, 0xba2e8ba3
	s_lshr_b32 s13, s13, 3
	s_mul_i32 s14, s13, 0xb0
	s_sub_i32 s12, s12, s14
	s_lshl_b32 s13, s13, 3
	s_sub_i32 s14, 0xc4, s13
	s_min_u32 s14, s14, 8
	s_sub_i32 s14, s14, 1
	s_and_b32 s12, s12, s14
	s_add_i32 s12, s13, s12
	s_mulk_i32 s12, 0xfc
	v_add_u32_e32 v168, s12, v0
	v_cmp_lt_i32_e32 vcc, 0x4000, v168
	s_nop 1
	v_subbrev_co_u32_e32 v3, vcc, 0, v168, vcc
	v_cmp_lt_i32_e32 vcc, 0x8001, v168
	s_nop 1
	v_subbrev_co_u32_e32 v3, vcc, 0, v3, vcc
	v_med3_i32 v3, v3, 0, v175
	v_lshlrev_b32_e32 v3, 6, v3
	global_load_dwordx4 v[54:57], v3, s[28:29] offset:48
	global_load_dwordx4 v[58:61], v3, s[28:29] offset:32
	global_load_dwordx4 v[62:65], v3, s[28:29] offset:16
	global_load_dwordx4 v[66:69], v3, s[28:29]
	s_add_u32 s18, s18, s74
	s_add_i32 s10, s10, 1
	s_cmpk_lt_u32 s18, 0x10d8
	s_cbranch_scc0 .Lupre_issued
	s_and_b32 s12, s18, 7
	s_lshr_b32 s13, s18, 3
	s_mulk_i32 s12, 0x21b
	s_add_i32 s12, s12, s13
	s_lshr_b32 s13, s12, 4
	s_mul_hi_u32 s13, s13, 0xba2e8ba3
	s_lshr_b32 s13, s13, 3
	s_mul_i32 s14, s13, 0xb0
	s_sub_i32 s12, s12, s14
	s_lshl_b32 s13, s13, 3
	s_sub_i32 s14, 0xc4, s13
	s_min_u32 s14, s14, 8
	s_sub_i32 s14, s14, 1
	s_and_b32 s12, s12, s14
	s_add_i32 s12, s13, s12
	s_mulk_i32 s12, 0xfc
	v_add_u32_e32 v169, s12, v0
	v_cmp_lt_i32_e32 vcc, 0x4000, v169
	s_nop 1
	v_subbrev_co_u32_e32 v3, vcc, 0, v169, vcc
	v_cmp_lt_i32_e32 vcc, 0x8001, v169
	s_nop 1
	v_subbrev_co_u32_e32 v3, vcc, 0, v3, vcc
	v_med3_i32 v3, v3, 0, v175
	v_lshlrev_b32_e32 v3, 6, v3
	global_load_dwordx4 v[70:73], v3, s[28:29] offset:48
	global_load_dwordx4 v[74:77], v3, s[28:29] offset:32
	global_load_dwordx4 v[78:81], v3, s[28:29] offset:16
	global_load_dwordx4 v[82:85], v3, s[28:29]
	s_add_u32 s18, s18, s74
	s_add_i32 s10, s10, 1
	s_cmpk_lt_u32 s18, 0x10d8
	s_cbranch_scc0 .Lupre_issued
	s_and_b32 s12, s18, 7
	s_lshr_b32 s13, s18, 3
	s_mulk_i32 s12, 0x21b
	s_add_i32 s12, s12, s13
	s_lshr_b32 s13, s12, 4
	s_mul_hi_u32 s13, s13, 0xba2e8ba3
	s_lshr_b32 s13, s13, 3
	s_mul_i32 s14, s13, 0xb0
	s_sub_i32 s12, s12, s14
	s_lshl_b32 s13, s13, 3
	s_sub_i32 s14, 0xc4, s13
	s_min_u32 s14, s14, 8
	s_sub_i32 s14, s14, 1
	s_and_b32 s12, s12, s14
	s_add_i32 s12, s13, s12
	s_mulk_i32 s12, 0xfc
	v_add_u32_e32 v170, s12, v0
	v_cmp_lt_i32_e32 vcc, 0x4000, v170
	s_nop 1
	v_subbrev_co_u32_e32 v3, vcc, 0, v170, vcc
	v_cmp_lt_i32_e32 vcc, 0x8001, v170
	s_nop 1
	v_subbrev_co_u32_e32 v3, vcc, 0, v3, vcc
	v_med3_i32 v3, v3, 0, v175
	v_lshlrev_b32_e32 v3, 6, v3
	global_load_dwordx4 v[86:89], v3, s[28:29] offset:48
	global_load_dwordx4 v[90:93], v3, s[28:29] offset:32
	global_load_dwordx4 v[94:97], v3, s[28:29] offset:16
	global_load_dwordx4 v[98:101], v3, s[28:29]
	s_add_u32 s18, s18, s74
	s_add_i32 s10, s10, 1
	s_cmpk_lt_u32 s18, 0x10d8
	s_cbranch_scc0 .Lupre_issued
; __global__ void __launch_bounds__(NWAVES * 64, 2) fwd_kernel(Args args) {
;     ...
;             { pg8::Unit u; for (int i = wave >> 2; S.next(i, u); i += 2)       { const int row = tid & 255; const int ai = row >> 7, wr = (row >> 6) & 1, m = (row >> 4) & 3, fr = row & 15;
;                 const int pp = UPM * u.pm - 1 + 126 * wr + 8 * fr + 4 * ai + m;
;                 const int tok = min(max(pp - (pp > SEQ ? 1 : 0) - (pp > 2 * SEQ + 1 ? 1 : 0), 0), M - 1);
;                 const float* p = SSX + (size_t)tok * 16;
;                 const f32x4 a = *(const f32x4*)p, b = *(const f32x4*)(p + 4), c = *(const f32x4*)(p + 8), d = *(const f32x4*)(p + 12);
;                 const float s = ((a[0] + a[1]) + (a[2] + a[3])) + ((b[0] + b[1]) + (b[2] + b[3])) + ((c[0] + c[1]) + (c[2] + c[3])) + ((d[0] + d[1]) + (d[2] + d[3]));
;                 tab[i * 256 + row] = (pp >= 0 && pp < MP && pp != SEQ && pp != 2 * SEQ + 1) ? 1.0f / sqrtf(s * (1.0f / D) + EPS) : 0.f; } }
	s_and_b32 s12, s18, 7
	s_lshr_b32 s13, s18, 3
	s_mulk_i32 s12, 0x21b
	s_add_i32 s12, s12, s13
	s_lshr_b32 s13, s12, 4
	s_mul_hi_u32 s13, s13, 0xba2e8ba3
	s_lshr_b32 s13, s13, 3
	s_mul_i32 s14, s13, 0xb0
	s_sub_i32 s12, s12, s14
	s_lshl_b32 s13, s13, 3
	s_sub_i32 s14, 0xc4, s13
	s_min_u32 s14, s14, 8
	s_sub_i32 s14, s14, 1
	s_and_b32 s12, s12, s14
	s_add_i32 s12, s13, s12
	s_mulk_i32 s12, 0xfc
	v_add_u32_e32 v171, s12, v0
	v_cmp_lt_i32_e32 vcc, 0x4000, v171
	s_nop 1
	v_subbrev_co_u32_e32 v3, vcc, 0, v171, vcc
	v_cmp_lt_i32_e32 vcc, 0x8001, v171
	s_nop 1
	v_subbrev_co_u32_e32 v3, vcc, 0, v3, vcc
	v_med3_i32 v3, v3, 0, v175
	v_lshlrev_b32_e32 v3, 6, v3
	global_load_dwordx4 v[102:105], v3, s[28:29] offset:48
	global_load_dwordx4 v[106:109], v3, s[28:29] offset:32
	global_load_dwordx4 v[110:113], v3, s[28:29] offset:16
	global_load_dwordx4 v[114:117], v3, s[28:29]
	s_add_u32 s18, s18, s74
	s_add_i32 s10, s10, 1
	s_cmpk_lt_u32 s18, 0x10d8
	s_cbranch_scc0 .Lupre_issued
	s_and_b32 s12, s18, 7
	s_lshr_b32 s13, s18, 3
	s_mulk_i32 s12, 0x21b
	s_add_i32 s12, s12, s13
	s_lshr_b32 s13, s12, 4
	s_mul_hi_u32 s13, s13, 0xba2e8ba3
	s_lshr_b32 s13, s13, 3
	s_mul_i32 s14, s13, 0xb0
	s_sub_i32 s12, s12, s14
	s_lshl_b32 s13, s13, 3
	s_sub_i32 s14, 0xc4, s13
	s_min_u32 s14, s14, 8
	s_sub_i32 s14, s14, 1
	s_and_b32 s12, s12, s14
	s_add_i32 s12, s13, s12
	s_mulk_i32 s12, 0xfc
	v_add_u32_e32 v172, s12, v0
	v_cmp_lt_i32_e32 vcc, 0x4000, v172
	s_nop 1
	v_subbrev_co_u32_e32 v3, vcc, 0, v172, vcc
	v_cmp_lt_i32_e32 vcc, 0x8001, v172
	s_nop 1
	v_subbrev_co_u32_e32 v3, vcc, 0, v3, vcc
	v_med3_i32 v3, v3, 0, v175
	v_lshlrev_b32_e32 v3, 6, v3
	global_load_dwordx4 v[118:121], v3, s[28:29] offset:48
	global_load_dwordx4 v[122:125], v3, s[28:29] offset:32
	global_load_dwordx4 v[126:129], v3, s[28:29] offset:16
	global_load_dwordx4 v[130:133], v3, s[28:29]
	s_add_u32 s18, s18, s74
	s_add_i32 s10, s10, 1
	s_cmpk_lt_u32 s18, 0x10d8
	s_cbranch_scc0 .Lupre_issued
	s_and_b32 s12, s18, 7
	s_lshr_b32 s13, s18, 3
	s_mulk_i32 s12, 0x21b
	s_add_i32 s12, s12, s13
	s_lshr_b32 s13, s12, 4
	s_mul_hi_u32 s13, s13, 0xba2e8ba3
	s_lshr_b32 s13, s13, 3
	s_mul_i32 s14, s13, 0xb0
	s_sub_i32 s12, s12, s14
	s_lshl_b32 s13, s13, 3
	s_sub_i32 s14, 0xc4, s13
	s_min_u32 s14, s14, 8
	s_sub_i32 s14, s14, 1
	s_and_b32 s12, s12, s14
	s_add_i32 s12, s13, s12
	s_mulk_i32 s12, 0xfc
	v_add_u32_e32 v173, s12, v0
	v_cmp_lt_i32_e32 vcc, 0x4000, v173
	s_nop 1
	v_subbrev_co_u32_e32 v3, vcc, 0, v173, vcc
	v_cmp_lt_i32_e32 vcc, 0x8001, v173
	s_nop 1
	v_subbrev_co_u32_e32 v3, vcc, 0, v3, vcc
	v_med3_i32 v3, v3, 0, v175
	v_lshlrev_b32_e32 v3, 6, v3
	global_load_dwordx4 v[134:137], v3, s[28:29] offset:48
	global_load_dwordx4 v[138:141], v3, s[28:29] offset:32
	global_load_dwordx4 v[142:145], v3, s[28:29] offset:16
	global_load_dwordx4 v[146:149], v3, s[28:29]
	s_add_u32 s18, s18, s74
	s_add_i32 s10, s10, 1
	s_cmpk_lt_u32 s18, 0x10d8
	s_cbranch_scc0 .Lupre_issued
	s_and_b32 s12, s18, 7
	s_lshr_b32 s13, s18, 3
	s_mulk_i32 s12, 0x21b
	s_add_i32 s12, s12, s13
	s_lshr_b32 s13, s12, 4
	s_mul_hi_u32 s13, s13, 0xba2e8ba3
	s_lshr_b32 s13, s13, 3
	s_mul_i32 s14, s13, 0xb0
	s_sub_i32 s12, s12, s14
	s_lshl_b32 s13, s13, 3
	s_sub_i32 s14, 0xc4, s13
	s_min_u32 s14, s14, 8
	s_sub_i32 s14, s14, 1
	s_and_b32 s12, s12, s14
	s_add_i32 s12, s13, s12
	s_mulk_i32 s12, 0xfc
	v_add_u32_e32 v174, s12, v0
	v_cmp_lt_i32_e32 vcc, 0x4000, v174
	s_nop 1
	v_subbrev_co_u32_e32 v3, vcc, 0, v174, vcc
	v_cmp_lt_i32_e32 vcc, 0x8001, v174
	s_nop 1
	v_subbrev_co_u32_e32 v3, vcc, 0, v3, vcc
	v_med3_i32 v3, v3, 0, v175
	v_lshlrev_b32_e32 v3, 6, v3
	global_load_dwordx4 v[150:153], v3, s[28:29] offset:48
	global_load_dwordx4 v[154:157], v3, s[28:29] offset:32
	global_load_dwordx4 v[158:161], v3, s[28:29] offset:16
	global_load_dwordx4 v[162:165], v3, s[28:29]
	s_add_u32 s18, s18, s74
	s_add_i32 s10, s10, 1
.Lupre_issued:
	s_mov_b32 s30, 0x4000
	s_mov_b32 s15, 0x8001
	s_mov_b32 s31, 0xf800000
	s_waitcnt vmcnt(0)
	s_cmp_eq_u32 s10, 0
	s_cbranch_scc1 .Lupre_done
	v_add_f32_e32 v34, v34, v35
	v_add_f32_e32 v36, v36, v37
	v_add_f32_e32 v30, v30, v31
	v_add_f32_e32 v32, v32, v33
	v_add_f32_e32 v26, v26, v27
	v_add_f32_e32 v28, v28, v29
	v_add_f32_e32 v22, v22, v23
	v_add_f32_e32 v24, v24, v25
	v_add_f32_e32 v34, v34, v36
	v_add_f32_e32 v30, v30, v32
	v_add_f32_e32 v26, v26, v28
	v_add_f32_e32 v22, v22, v24
	v_add_f32_e32 v3, v34, v30
	v_add_f32_e32 v3, v3, v26
	v_add_f32_e32 v3, v3, v22
	v_fmamk_f32 v3, v3, 0x3a800000, v251
	v_cmp_gt_f32_e32 vcc, s31, v3
	v_mul_f32_e32 v4, 0x4f800000, v3
	s_nop 0
	v_cndmask_b32_e32 v3, v3, v4, vcc
	v_sqrt_f32_e32 v4, v3
	s_nop 0
	v_add_u32_e32 v5, -1, v4
	v_fma_f32 v6, -v5, v4, v3
	v_cmp_ge_f32_e64 s[38:39], 0, v6
	v_add_u32_e32 v6, 1, v4
	s_nop 0
	v_cndmask_b32_e64 v5, v4, v5, s[38:39]
	v_fma_f32 v4, -v6, v4, v3
	v_cmp_lt_f32_e64 s[38:39], 0, v4
	s_nop 1
	v_cndmask_b32_e64 v4, v5, v6, s[38:39]
	v_mul_f32_e32 v5, 0x37800000, v4
	v_cndmask_b32_e32 v4, v4, v5, vcc
	v_cmp_class_f32_e32 vcc, v3, v247
	s_nop 1
	v_cndmask_b32_e32 v3, v4, v3, vcc
	v_div_scale_f32 v4, s[12:13], v3, v3, 1.0
	v_rcp_f32_e32 v5, v4
	s_nop 0
	v_fma_f32 v6, -v4, v5, 1.0
	v_fmac_f32_e32 v5, v6, v5
	v_div_scale_f32 v6, vcc, 1.0, v3, 1.0
	v_mul_f32_e32 v7, v6, v5
	v_fma_f32 v8, -v4, v7, v6
	v_fmac_f32_e32 v7, v8, v5
	v_fma_f32 v4, -v4, v7, v6
	v_div_fmas_f32 v4, v4, v5, v7
	v_div_fixup_f32 v4, v4, v3, 1.0
	v_cmp_gt_u32_e32 vcc, 0xc002, v166
	v_cmp_ne_u32_e64 s[36:37], s30, v166
	v_cmp_ne_u32_e64 s[38:39], s15, v166
	s_and_b64 s[36:37], s[36:37], s[38:39]
	s_and_b64 s[36:37], s[36:37], vcc
	s_nop 1
	v_cndmask_b32_e64 v4, 0, v4, s[36:37]
	ds_write_b32 v2, v4
	s_cmp_eq_u32 s10, 1
	s_cbranch_scc1 .Lupre_done
; __global__ void __launch_bounds__(NWAVES * 64, 2) fwd_kernel(Args args) {
;     ...
;             { pg8::Unit u; for (int i = wave >> 2; S.next(i, u); i += 2)       { const int row = tid & 255; const int ai = row >> 7, wr = (row >> 6) & 1, m = (row >> 4) & 3, fr = row & 15;
;                 const int pp = UPM * u.pm - 1 + 126 * wr + 8 * fr + 4 * ai + m;
;                 const int tok = min(max(pp - (pp > SEQ ? 1 : 0) - (pp > 2 * SEQ + 1 ? 1 : 0), 0), M - 1);
;                 const float* p = SSX + (size_t)tok * 16;
;                 const f32x4 a = *(const f32x4*)p, b = *(const f32x4*)(p + 4), c = *(const f32x4*)(p + 8), d = *(const f32x4*)(p + 12);
;                 const float s = ((a[0] + a[1]) + (a[2] + a[3])) + ((b[0] + b[1]) + (b[2] + b[3])) + ((c[0] + c[1]) + (c[2] + c[3])) + ((d[0] + d[1]) + (d[2] + d[3]));
;                 tab[i * 256 + row] = (pp >= 0 && pp < MP && pp != SEQ && pp != 2 * SEQ + 1) ? 1.0f / sqrtf(s * (1.0f / D) + EPS) : 0.f; } }
	v_add_f32_e32 v50, v50, v51
	v_add_f32_e32 v52, v52, v53
	v_add_f32_e32 v46, v46, v47
	v_add_f32_e32 v48, v48, v49
	v_add_f32_e32 v42, v42, v43
	v_add_f32_e32 v44, v44, v45
	v_add_f32_e32 v38, v38, v39
	v_add_f32_e32 v40, v40, v41
	v_add_f32_e32 v50, v50, v52
	v_add_f32_e32 v46, v46, v48
	v_add_f32_e32 v42, v42, v44
	v_add_f32_e32 v38, v38, v40
	v_add_f32_e32 v3, v50, v46
	v_add_f32_e32 v3, v3, v42
	v_add_f32_e32 v3, v3, v38
	v_fmamk_f32 v3, v3, 0x3a800000, v251
	v_cmp_gt_f32_e32 vcc, s31, v3
	v_mul_f32_e32 v4, 0x4f800000, v3
	s_nop 0
	v_cndmask_b32_e32 v3, v3, v4, vcc
	v_sqrt_f32_e32 v4, v3
	s_nop 0
	v_add_u32_e32 v5, -1, v4
	v_fma_f32 v6, -v5, v4, v3
	v_cmp_ge_f32_e64 s[38:39], 0, v6
	v_add_u32_e32 v6, 1, v4
	s_nop 0
	v_cndmask_b32_e64 v5, v4, v5, s[38:39]
	v_fma_f32 v4, -v6, v4, v3
	v_cmp_lt_f32_e64 s[38:39], 0, v4
	s_nop 1
	v_cndmask_b32_e64 v4, v5, v6, s[38:39]
	v_mul_f32_e32 v5, 0x37800000, v4
	v_cndmask_b32_e32 v4, v4, v5, vcc
	v_cmp_class_f32_e32 vcc, v3, v247
	s_nop 1
	v_cndmask_b32_e32 v3, v4, v3, vcc
	v_div_scale_f32 v4, s[12:13], v3, v3, 1.0
	v_rcp_f32_e32 v5, v4
	s_nop 0
	v_fma_f32 v6, -v4, v5, 1.0
	v_fmac_f32_e32 v5, v6, v5
	v_div_scale_f32 v6, vcc, 1.0, v3, 1.0
	v_mul_f32_e32 v7, v6, v5
	v_fma_f32 v8, -v4, v7, v6
	v_fmac_f32_e32 v7, v8, v5
	v_fma_f32 v4, -v4, v7, v6
	v_div_fmas_f32 v4, v4, v5, v7
	v_div_fixup_f32 v4, v4, v3, 1.0
	v_cmp_gt_u32_e32 vcc, 0xc002, v167
	v_cmp_ne_u32_e64 s[36:37], s30, v167
	v_cmp_ne_u32_e64 s[38:39], s15, v167
	s_and_b64 s[36:37], s[36:37], s[38:39]
	s_and_b64 s[36:37], s[36:37], vcc
	s_nop 1
	v_cndmask_b32_e64 v4, 0, v4, s[36:37]
	ds_write_b32 v2, v4 offset:2048
	s_cmp_eq_u32 s10, 2
	s_cbranch_scc1 .Lupre_done
	v_add_f32_e32 v66, v66, v67
	v_add_f32_e32 v68, v68, v69
	v_add_f32_e32 v62, v62, v63
	v_add_f32_e32 v64, v64, v65
	v_add_f32_e32 v58, v58, v59
	v_add_f32_e32 v60, v60, v61
	v_add_f32_e32 v54, v54, v55
	v_add_f32_e32 v56, v56, v57
	v_add_f32_e32 v66, v66, v68
	v_add_f32_e32 v62, v62, v64
	v_add_f32_e32 v58, v58, v60
	v_add_f32_e32 v54, v54, v56
	v_add_f32_e32 v3, v66, v62
	v_add_f32_e32 v3, v3, v58
	v_add_f32_e32 v3, v3, v54
	v_fmamk_f32 v3, v3, 0x3a800000, v251
	v_cmp_gt_f32_e32 vcc, s31, v3
	v_mul_f32_e32 v4, 0x4f800000, v3
	s_nop 0
	v_cndmask_b32_e32 v3, v3, v4, vcc
	v_sqrt_f32_e32 v4, v3
	s_nop 0
	v_add_u32_e32 v5, -1, v4
	v_fma_f32 v6, -v5, v4, v3
	v_cmp_ge_f32_e64 s[38:39], 0, v6
	v_add_u32_e32 v6, 1, v4
	s_nop 0
	v_cndmask_b32_e64 v5, v4, v5, s[38:39]
	v_fma_f32 v4, -v6, v4, v3
	v_cmp_lt_f32_e64 s[38:39], 0, v4
	s_nop 1
	v_cndmask_b32_e64 v4, v5, v6, s[38:39]
	v_mul_f32_e32 v5, 0x37800000, v4
	v_cndmask_b32_e32 v4, v4, v5, vcc
	v_cmp_class_f32_e32 vcc, v3, v247
	s_nop 1
	v_cndmask_b32_e32 v3, v4, v3, vcc
	v_div_scale_f32 v4, s[12:13], v3, v3, 1.0
	v_rcp_f32_e32 v5, v4
	s_nop 0
	v_fma_f32 v6, -v4, v5, 1.0
	v_fmac_f32_e32 v5, v6, v5
	v_div_scale_f32 v6, vcc, 1.0, v3, 1.0
	v_mul_f32_e32 v7, v6, v5
	v_fma_f32 v8, -v4, v7, v6
	v_fmac_f32_e32 v7, v8, v5
	v_fma_f32 v4, -v4, v7, v6
	v_div_fmas_f32 v4, v4, v5, v7
	v_div_fixup_f32 v4, v4, v3, 1.0
	v_cmp_gt_u32_e32 vcc, 0xc002, v168
	v_cmp_ne_u32_e64 s[36:37], s30, v168
	v_cmp_ne_u32_e64 s[38:39], s15, v168
	s_and_b64 s[36:37], s[36:37], s[38:39]
	s_and_b64 s[36:37], s[36:37], vcc
	s_nop 1
	v_cndmask_b32_e64 v4, 0, v4, s[36:37]
	ds_write_b32 v2, v4 offset:4096
	s_cmp_eq_u32 s10, 3
	s_cbranch_scc1 .Lupre_done
	v_add_f32_e32 v82, v82, v83
	v_add_f32_e32 v84, v84, v85
	v_add_f32_e32 v78, v78, v79
	v_add_f32_e32 v80, v80, v81
	v_add_f32_e32 v74, v74, v75
	v_add_f32_e32 v76, v76, v77
	v_add_f32_e32 v70, v70, v71
	v_add_f32_e32 v72, v72, v73
	v_add_f32_e32 v82, v82, v84
	v_add_f32_e32 v78, v78, v80
	v_add_f32_e32 v74, v74, v76
	v_add_f32_e32 v70, v70, v72
	v_add_f32_e32 v3, v82, v78
	v_add_f32_e32 v3, v3, v74
	v_add_f32_e32 v3, v3, v70
	v_fmamk_f32 v3, v3, 0x3a800000, v251
	v_cmp_gt_f32_e32 vcc, s31, v3
	v_mul_f32_e32 v4, 0x4f800000, v3
	s_nop 0
	v_cndmask_b32_e32 v3, v3, v4, vcc
	v_sqrt_f32_e32 v4, v3
	s_nop 0
	v_add_u32_e32 v5, -1, v4
	v_fma_f32 v6, -v5, v4, v3
	v_cmp_ge_f32_e64 s[38:39], 0, v6
	v_add_u32_e32 v6, 1, v4
	s_nop 0
	v_cndmask_b32_e64 v5, v4, v5, s[38:39]
	v_fma_f32 v4, -v6, v4, v3
	v_cmp_lt_f32_e64 s[38:39], 0, v4
	s_nop 1
	v_cndmask_b32_e64 v4, v5, v6, s[38:39]
	v_mul_f32_e32 v5, 0x37800000, v4
	v_cndmask_b32_e32 v4, v4, v5, vcc
	v_cmp_class_f32_e32 vcc, v3, v247
	s_nop 1
	v_cndmask_b32_e32 v3, v4, v3, vcc
	v_div_scale_f32 v4, s[12:13], v3, v3, 1.0
	v_rcp_f32_e32 v5, v4
	s_nop 0
	v_fma_f32 v6, -v4, v5, 1.0
	v_fmac_f32_e32 v5, v6, v5
	v_div_scale_f32 v6, vcc, 1.0, v3, 1.0
	v_mul_f32_e32 v7, v6, v5
	v_fma_f32 v8, -v4, v7, v6
	v_fmac_f32_e32 v7, v8, v5
	v_fma_f32 v4, -v4, v7, v6
	v_div_fmas_f32 v4, v4, v5, v7
	v_div_fixup_f32 v4, v4, v3, 1.0
	v_cmp_gt_u32_e32 vcc, 0xc002, v169
	v_cmp_ne_u32_e64 s[36:37], s30, v169
	v_cmp_ne_u32_e64 s[38:39], s15, v169
	s_and_b64 s[36:37], s[36:37], s[38:39]
	s_and_b64 s[36:37], s[36:37], vcc
	s_nop 1
	v_cndmask_b32_e64 v4, 0, v4, s[36:37]
	ds_write_b32 v2, v4 offset:6144
	s_cmp_eq_u32 s10, 4
	s_cbranch_scc1 .Lupre_done
; __global__ void __launch_bounds__(NWAVES * 64, 2) fwd_kernel(Args args) {
;     ...
;             { pg8::Unit u; for (int i = wave >> 2; S.next(i, u); i += 2)       { const int row = tid & 255; const int ai = row >> 7, wr = (row >> 6) & 1, m = (row >> 4) & 3, fr = row & 15;
;                 const int pp = UPM * u.pm - 1 + 126 * wr + 8 * fr + 4 * ai + m;
;                 const int tok = min(max(pp - (pp > SEQ ? 1 : 0) - (pp > 2 * SEQ + 1 ? 1 : 0), 0), M - 1);
;                 const float* p = SSX + (size_t)tok * 16;
;                 const f32x4 a = *(const f32x4*)p, b = *(const f32x4*)(p + 4), c = *(const f32x4*)(p + 8), d = *(const f32x4*)(p + 12);
;                 const float s = ((a[0] + a[1]) + (a[2] + a[3])) + ((b[0] + b[1]) + (b[2] + b[3])) + ((c[0] + c[1]) + (c[2] + c[3])) + ((d[0] + d[1]) + (d[2] + d[3]));
;                 tab[i * 256 + row] = (pp >= 0 && pp < MP && pp != SEQ && pp != 2 * SEQ + 1) ? 1.0f / sqrtf(s * (1.0f / D) + EPS) : 0.f; } }
	v_add_f32_e32 v98, v98, v99
	v_add_f32_e32 v100, v100, v101
	v_add_f32_e32 v94, v94, v95
	v_add_f32_e32 v96, v96, v97
	v_add_f32_e32 v90, v90, v91
	v_add_f32_e32 v92, v92, v93
	v_add_f32_e32 v86, v86, v87
	v_add_f32_e32 v88, v88, v89
	v_add_f32_e32 v98, v98, v100
	v_add_f32_e32 v94, v94, v96
	v_add_f32_e32 v90, v90, v92
	v_add_f32_e32 v86, v86, v88
	v_add_f32_e32 v3, v98, v94
	v_add_f32_e32 v3, v3, v90
	v_add_f32_e32 v3, v3, v86
	v_fmamk_f32 v3, v3, 0x3a800000, v251
	v_cmp_gt_f32_e32 vcc, s31, v3
	v_mul_f32_e32 v4, 0x4f800000, v3
	s_nop 0
	v_cndmask_b32_e32 v3, v3, v4, vcc
	v_sqrt_f32_e32 v4, v3
	s_nop 0
	v_add_u32_e32 v5, -1, v4
	v_fma_f32 v6, -v5, v4, v3
	v_cmp_ge_f32_e64 s[38:39], 0, v6
	v_add_u32_e32 v6, 1, v4
	s_nop 0
	v_cndmask_b32_e64 v5, v4, v5, s[38:39]
	v_fma_f32 v4, -v6, v4, v3
	v_cmp_lt_f32_e64 s[38:39], 0, v4
	s_nop 1
	v_cndmask_b32_e64 v4, v5, v6, s[38:39]
	v_mul_f32_e32 v5, 0x37800000, v4
	v_cndmask_b32_e32 v4, v4, v5, vcc
	v_cmp_class_f32_e32 vcc, v3, v247
	s_nop 1
	v_cndmask_b32_e32 v3, v4, v3, vcc
	v_div_scale_f32 v4, s[12:13], v3, v3, 1.0
	v_rcp_f32_e32 v5, v4
	s_nop 0
	v_fma_f32 v6, -v4, v5, 1.0
	v_fmac_f32_e32 v5, v6, v5
	v_div_scale_f32 v6, vcc, 1.0, v3, 1.0
	v_mul_f32_e32 v7, v6, v5
	v_fma_f32 v8, -v4, v7, v6
	v_fmac_f32_e32 v7, v8, v5
	v_fma_f32 v4, -v4, v7, v6
	v_div_fmas_f32 v4, v4, v5, v7
	v_div_fixup_f32 v4, v4, v3, 1.0
	v_cmp_gt_u32_e32 vcc, 0xc002, v170
	v_cmp_ne_u32_e64 s[36:37], s30, v170
	v_cmp_ne_u32_e64 s[38:39], s15, v170
	s_and_b64 s[36:37], s[36:37], s[38:39]
	s_and_b64 s[36:37], s[36:37], vcc
	s_nop 1
	v_cndmask_b32_e64 v4, 0, v4, s[36:37]
	ds_write_b32 v2, v4 offset:8192
	s_cmp_eq_u32 s10, 5
	s_cbranch_scc1 .Lupre_done
	v_add_f32_e32 v114, v114, v115
	v_add_f32_e32 v116, v116, v117
	v_add_f32_e32 v110, v110, v111
	v_add_f32_e32 v112, v112, v113
	v_add_f32_e32 v106, v106, v107
	v_add_f32_e32 v108, v108, v109
	v_add_f32_e32 v102, v102, v103
	v_add_f32_e32 v104, v104, v105
	v_add_f32_e32 v114, v114, v116
	v_add_f32_e32 v110, v110, v112
	v_add_f32_e32 v106, v106, v108
	v_add_f32_e32 v102, v102, v104
	v_add_f32_e32 v3, v114, v110
	v_add_f32_e32 v3, v3, v106
	v_add_f32_e32 v3, v3, v102
	v_fmamk_f32 v3, v3, 0x3a800000, v251
	v_cmp_gt_f32_e32 vcc, s31, v3
	v_mul_f32_e32 v4, 0x4f800000, v3
	s_nop 0
	v_cndmask_b32_e32 v3, v3, v4, vcc
	v_sqrt_f32_e32 v4, v3
	s_nop 0
	v_add_u32_e32 v5, -1, v4
	v_fma_f32 v6, -v5, v4, v3
	v_cmp_ge_f32_e64 s[38:39], 0, v6
	v_add_u32_e32 v6, 1, v4
	s_nop 0
	v_cndmask_b32_e64 v5, v4, v5, s[38:39]
	v_fma_f32 v4, -v6, v4, v3
	v_cmp_lt_f32_e64 s[38:39], 0, v4
	s_nop 1
	v_cndmask_b32_e64 v4, v5, v6, s[38:39]
	v_mul_f32_e32 v5, 0x37800000, v4
	v_cndmask_b32_e32 v4, v4, v5, vcc
	v_cmp_class_f32_e32 vcc, v3, v247
	s_nop 1
	v_cndmask_b32_e32 v3, v4, v3, vcc
	v_div_scale_f32 v4, s[12:13], v3, v3, 1.0
	v_rcp_f32_e32 v5, v4
	s_nop 0
	v_fma_f32 v6, -v4, v5, 1.0
	v_fmac_f32_e32 v5, v6, v5
	v_div_scale_f32 v6, vcc, 1.0, v3, 1.0
	v_mul_f32_e32 v7, v6, v5
	v_fma_f32 v8, -v4, v7, v6
	v_fmac_f32_e32 v7, v8, v5
	v_fma_f32 v4, -v4, v7, v6
	v_div_fmas_f32 v4, v4, v5, v7
	v_div_fixup_f32 v4, v4, v3, 1.0
	v_cmp_gt_u32_e32 vcc, 0xc002, v171
	v_cmp_ne_u32_e64 s[36:37], s30, v171
	v_cmp_ne_u32_e64 s[38:39], s15, v171
	s_and_b64 s[36:37], s[36:37], s[38:39]
	s_and_b64 s[36:37], s[36:37], vcc
	s_nop 1
	v_cndmask_b32_e64 v4, 0, v4, s[36:37]
	ds_write_b32 v2, v4 offset:10240
	s_cmp_eq_u32 s10, 6
	s_cbranch_scc1 .Lupre_done
	v_add_f32_e32 v130, v130, v131
	v_add_f32_e32 v132, v132, v133
	v_add_f32_e32 v126, v126, v127
	v_add_f32_e32 v128, v128, v129
	v_add_f32_e32 v122, v122, v123
	v_add_f32_e32 v124, v124, v125
	v_add_f32_e32 v118, v118, v119
	v_add_f32_e32 v120, v120, v121
	v_add_f32_e32 v130, v130, v132
	v_add_f32_e32 v126, v126, v128
	v_add_f32_e32 v122, v122, v124
	v_add_f32_e32 v118, v118, v120
	v_add_f32_e32 v3, v130, v126
	v_add_f32_e32 v3, v3, v122
	v_add_f32_e32 v3, v3, v118
	v_fmamk_f32 v3, v3, 0x3a800000, v251
	v_cmp_gt_f32_e32 vcc, s31, v3
	v_mul_f32_e32 v4, 0x4f800000, v3
	s_nop 0
	v_cndmask_b32_e32 v3, v3, v4, vcc
	v_sqrt_f32_e32 v4, v3
	s_nop 0
	v_add_u32_e32 v5, -1, v4
	v_fma_f32 v6, -v5, v4, v3
	v_cmp_ge_f32_e64 s[38:39], 0, v6
	v_add_u32_e32 v6, 1, v4
	s_nop 0
	v_cndmask_b32_e64 v5, v4, v5, s[38:39]
	v_fma_f32 v4, -v6, v4, v3
	v_cmp_lt_f32_e64 s[38:39], 0, v4
	s_nop 1
	v_cndmask_b32_e64 v4, v5, v6, s[38:39]
	v_mul_f32_e32 v5, 0x37800000, v4
	v_cndmask_b32_e32 v4, v4, v5, vcc
	v_cmp_class_f32_e32 vcc, v3, v247
	s_nop 1
	v_cndmask_b32_e32 v3, v4, v3, vcc
	v_div_scale_f32 v4, s[12:13], v3, v3, 1.0
	v_rcp_f32_e32 v5, v4
	s_nop 0
	v_fma_f32 v6, -v4, v5, 1.0
	v_fmac_f32_e32 v5, v6, v5
	v_div_scale_f32 v6, vcc, 1.0, v3, 1.0
	v_mul_f32_e32 v7, v6, v5
	v_fma_f32 v8, -v4, v7, v6
	v_fmac_f32_e32 v7, v8, v5
	v_fma_f32 v4, -v4, v7, v6
	v_div_fmas_f32 v4, v4, v5, v7
	v_div_fixup_f32 v4, v4, v3, 1.0
	v_cmp_gt_u32_e32 vcc, 0xc002, v172
	v_cmp_ne_u32_e64 s[36:37], s30, v172
	v_cmp_ne_u32_e64 s[38:39], s15, v172
	s_and_b64 s[36:37], s[36:37], s[38:39]
	s_and_b64 s[36:37], s[36:37], vcc
	s_nop 1
	v_cndmask_b32_e64 v4, 0, v4, s[36:37]
	ds_write_b32 v2, v4 offset:12288
	s_cmp_eq_u32 s10, 7
	s_cbranch_scc1 .Lupre_done
; __global__ void __launch_bounds__(NWAVES * 64, 2) fwd_kernel(Args args) {
;     ...
;             { pg8::Unit u; for (int i = wave >> 2; S.next(i, u); i += 2)       { const int row = tid & 255; const int ai = row >> 7, wr = (row >> 6) & 1, m = (row >> 4) & 3, fr = row & 15;
;                 const int pp = UPM * u.pm - 1 + 126 * wr + 8 * fr + 4 * ai + m;
;                 const int tok = min(max(pp - (pp > SEQ ? 1 : 0) - (pp > 2 * SEQ + 1 ? 1 : 0), 0), M - 1);
;                 const float* p = SSX + (size_t)tok * 16;
;                 const f32x4 a = *(const f32x4*)p, b = *(const f32x4*)(p + 4), c = *(const f32x4*)(p + 8), d = *(const f32x4*)(p + 12);
;                 const float s = ((a[0] + a[1]) + (a[2] + a[3])) + ((b[0] + b[1]) + (b[2] + b[3])) + ((c[0] + c[1]) + (c[2] + c[3])) + ((d[0] + d[1]) + (d[2] + d[3]));
;                 tab[i * 256 + row] = (pp >= 0 && pp < MP && pp != SEQ && pp != 2 * SEQ + 1) ? 1.0f / sqrtf(s * (1.0f / D) + EPS) : 0.f; } }
;             __syncthreads();
	v_add_f32_e32 v146, v146, v147
	v_add_f32_e32 v148, v148, v149
	v_add_f32_e32 v142, v142, v143
	v_add_f32_e32 v144, v144, v145
	v_add_f32_e32 v138, v138, v139
	v_add_f32_e32 v140, v140, v141
	v_add_f32_e32 v134, v134, v135
	v_add_f32_e32 v136, v136, v137
	v_add_f32_e32 v146, v146, v148
	v_add_f32_e32 v142, v142, v144
	v_add_f32_e32 v138, v138, v140
	v_add_f32_e32 v134, v134, v136
	v_add_f32_e32 v3, v146, v142
	v_add_f32_e32 v3, v3, v138
	v_add_f32_e32 v3, v3, v134
	v_fmamk_f32 v3, v3, 0x3a800000, v251
	v_cmp_gt_f32_e32 vcc, s31, v3
	v_mul_f32_e32 v4, 0x4f800000, v3
	s_nop 0
	v_cndmask_b32_e32 v3, v3, v4, vcc
	v_sqrt_f32_e32 v4, v3
	s_nop 0
	v_add_u32_e32 v5, -1, v4
	v_fma_f32 v6, -v5, v4, v3
	v_cmp_ge_f32_e64 s[38:39], 0, v6
	v_add_u32_e32 v6, 1, v4
	s_nop 0
	v_cndmask_b32_e64 v5, v4, v5, s[38:39]
	v_fma_f32 v4, -v6, v4, v3
	v_cmp_lt_f32_e64 s[38:39], 0, v4
	s_nop 1
	v_cndmask_b32_e64 v4, v5, v6, s[38:39]
	v_mul_f32_e32 v5, 0x37800000, v4
	v_cndmask_b32_e32 v4, v4, v5, vcc
	v_cmp_class_f32_e32 vcc, v3, v247
	s_nop 1
	v_cndmask_b32_e32 v3, v4, v3, vcc
	v_div_scale_f32 v4, s[12:13], v3, v3, 1.0
	v_rcp_f32_e32 v5, v4
	s_nop 0
	v_fma_f32 v6, -v4, v5, 1.0
	v_fmac_f32_e32 v5, v6, v5
	v_div_scale_f32 v6, vcc, 1.0, v3, 1.0
	v_mul_f32_e32 v7, v6, v5
	v_fma_f32 v8, -v4, v7, v6
	v_fmac_f32_e32 v7, v8, v5
	v_fma_f32 v4, -v4, v7, v6
	v_div_fmas_f32 v4, v4, v5, v7
	v_div_fixup_f32 v4, v4, v3, 1.0
	v_cmp_gt_u32_e32 vcc, 0xc002, v173
	v_cmp_ne_u32_e64 s[36:37], s30, v173
	v_cmp_ne_u32_e64 s[38:39], s15, v173
	s_and_b64 s[36:37], s[36:37], s[38:39]
	s_and_b64 s[36:37], s[36:37], vcc
	s_nop 1
	v_cndmask_b32_e64 v4, 0, v4, s[36:37]
	ds_write_b32 v2, v4 offset:14336
	s_cmp_eq_u32 s10, 8
	s_cbranch_scc1 .Lupre_done
	v_add_f32_e32 v162, v162, v163
	v_add_f32_e32 v164, v164, v165
	v_add_f32_e32 v158, v158, v159
	v_add_f32_e32 v160, v160, v161
	v_add_f32_e32 v154, v154, v155
	v_add_f32_e32 v156, v156, v157
	v_add_f32_e32 v150, v150, v151
	v_add_f32_e32 v152, v152, v153
	v_add_f32_e32 v162, v162, v164
	v_add_f32_e32 v158, v158, v160
	v_add_f32_e32 v154, v154, v156
	v_add_f32_e32 v150, v150, v152
	v_add_f32_e32 v3, v162, v158
	v_add_f32_e32 v3, v3, v154
	v_add_f32_e32 v3, v3, v150
	v_fmamk_f32 v3, v3, 0x3a800000, v251
	v_cmp_gt_f32_e32 vcc, s31, v3
	v_mul_f32_e32 v4, 0x4f800000, v3
	s_nop 0
	v_cndmask_b32_e32 v3, v3, v4, vcc
	v_sqrt_f32_e32 v4, v3
	s_nop 0
	v_add_u32_e32 v5, -1, v4
	v_fma_f32 v6, -v5, v4, v3
	v_cmp_ge_f32_e64 s[38:39], 0, v6
	v_add_u32_e32 v6, 1, v4
	s_nop 0
	v_cndmask_b32_e64 v5, v4, v5, s[38:39]
	v_fma_f32 v4, -v6, v4, v3
	v_cmp_lt_f32_e64 s[38:39], 0, v4
	s_nop 1
	v_cndmask_b32_e64 v4, v5, v6, s[38:39]
	v_mul_f32_e32 v5, 0x37800000, v4
	v_cndmask_b32_e32 v4, v4, v5, vcc
	v_cmp_class_f32_e32 vcc, v3, v247
	s_nop 1
	v_cndmask_b32_e32 v3, v4, v3, vcc
	v_div_scale_f32 v4, s[12:13], v3, v3, 1.0
	v_rcp_f32_e32 v5, v4
	s_nop 0
	v_fma_f32 v6, -v4, v5, 1.0
	v_fmac_f32_e32 v5, v6, v5
	v_div_scale_f32 v6, vcc, 1.0, v3, 1.0
	v_mul_f32_e32 v7, v6, v5
	v_fma_f32 v8, -v4, v7, v6
	v_fmac_f32_e32 v7, v8, v5
	v_fma_f32 v4, -v4, v7, v6
	v_div_fmas_f32 v4, v4, v5, v7
	v_div_fixup_f32 v4, v4, v3, 1.0
	v_cmp_gt_u32_e32 vcc, 0xc002, v174
	v_cmp_ne_u32_e64 s[36:37], s30, v174
	v_cmp_ne_u32_e64 s[38:39], s15, v174
	s_and_b64 s[36:37], s[36:37], s[38:39]
	s_and_b64 s[36:37], s[36:37], vcc
	s_nop 1
	v_cndmask_b32_e64 v4, 0, v4, s[36:37]
	ds_write_b32 v2, v4 offset:16384
.Lupre_done:
.LBB0_537:
	v_readlane_b32 s12, v254, 13
	s_waitcnt lgkmcnt(0)
	s_barrier
	v_mbcnt_lo_u32_b32 v0, -1, 0
	v_mbcnt_hi_u32_b32 v0, -1, v0
	v_readlane_b32 s0, v252, 43
	v_readlane_b32 s13, v254, 14
	s_andn2_b64 vcc, exec, s[12:13]
	v_add_u32_e32 v2, s0, v0
	v_cndmask_b32_e64 v0, 0, 1, s[12:13]
	v_cmp_ne_u32_e64 s[38:39], 1, v0
	v_readfirstlane_b32 s0, v2
	s_cbranch_vccnz .LBB0_539
	v_readlane_b32 s5, v254, 50
	s_mov_b32 s46, s5
	v_readlane_b32 s99, v254, 47

; #define PG8_STAGE(bufoff, gbase, voff) glds16s2((voff)[0], (voff)[1], (const void*)(gbase), ldsn + (unsigned)(bufoff))
; #define PG8_LDA(dst, b, h) do { _Pragma("unroll") for (int m = 0; m < 4; ++m) _Pragma("unroll") for (int k = 0; k < 2; ++k) dst[m][k] = *(const LAS bf16x8*)(lds + PG8_SA(b, h) + aoff + m * 2048 + k * 1024); } while (0)
; #define PG8_LDB(dst, b, h) do { _Pragma("unroll") for (int n = 0; n < 2; ++n) _Pragma("unroll") for (int k = 0; k < 2; ++k) dst[n][k] = *(const LAS bf16x8*)(lds + PG8_SB(b, h) + boff + n * 2048 + k * 1024); } while (0)
; #define PG8_WAIT_V(n) asm volatile("s_waitcnt vmcnt(" #n ")" ::: "memory")
; #define PG8_WAIT_L(n) asm volatile("s_waitcnt lgkmcnt(" #n ")" ::: "memory")
; #define PG8_BAR __builtin_amdgcn_s_barrier()
; #define PG8_SCHED __builtin_amdgcn_sched_barrier(0)
; template <class Epi, bool ALIGN_EPI, bool EARLY_DRAIN = true, class Pre = NoPre>
; __device__ __forceinline__ void gemm_phase(LAS unsigned char* lds, const Gemm g, const StaticOrder& S, const Epi& E, int wv, const Pre& pre = Pre()) {
;     ...
;         for (int t = th; t < th + (Epi::MIDK ? nt / 2 : nt); t += 2) {
;             const bool last = (t == nt - 2);
;             const char* a1 = cA + (size_t)(t + 1) * kstep;
;             const char* a2 = last ? nA : cA + (size_t)(t + 2) * kstep; const char* b2 = last ? nB : cB + (size_t)(t + 2) * kstep;
;             const char* a3 = a2 + kstep; const char* b3 = b2 + kstep;
;             int lf_ = EARLY_DRAIN ? __builtin_amdgcn_readfirstlane(landed_flag) : landed_flag; if constexpr (EARLY_DRAIN) asm volatile("" : "+s"(lf_)); landed_flag = 0;
;             PG8_LDB(B0, 0, 0); PG8_LDB(B1, 0, 1); PG8_SCHED; PG8_LDA(At, 0, 0); PG8_STAGE(PG8_SA(1, 1), a1 + ahs, voffA);
;             if (!lf_) PG8_WAIT_V(8);
;             PG8_WAIT_L(0); PG8_BAR; PG8_MMA(0, 0, At, B0); PG8_MMA(0, 1, At, B1); PG8_BAR; PG8_SCHED;
;             PG8_LDA(At, 0, 1); PG8_STAGE(PG8_SB(0, 0), b2, voffB); PG8_STAGE(PG8_SB(0, 1), b2 + bhs, voffB); PG8_STAGE(PG8_SA(0, 0), a2, voffA);
;             if (!lf_) PG8_WAIT_V(8);
;             PG8_WAIT_L(0); PG8_BAR; PG8_MMA(1, 0, At, B0); PG8_MMA(1, 1, At, B1); PG8_BAR; PG8_SCHED;
;             PG8_LDB(B0, 1, 0); PG8_LDB(B1, 1, 1); PG8_SCHED; PG8_LDA(At, 1, 0); PG8_STAGE(PG8_SA(0, 1), a2 + ahs, voffA);
.LBB0_553:
	s_add_u32 s14, s86, 0x100
	s_addc_u32 s15, s87, 0
	s_waitcnt lgkmcnt(0)
	s_add_u32 s42, s84, 0x100
	s_addc_u32 s43, s85, 0
	s_barrier
	s_setprio 1
	s_waitcnt lgkmcnt(7)
	v_mfma_f32_16x16x32_bf16 v[2:5], v[74:77], v[38:41], 0
	v_mfma_f32_16x16x32_bf16 v[6:9], v[86:89], v[38:41], 0
	s_waitcnt lgkmcnt(5)
	v_mfma_f32_16x16x32_bf16 v[10:13], v[74:77], v[46:49], 0
	v_mfma_f32_16x16x32_bf16 v[14:17], v[86:89], v[46:49], 0
	s_waitcnt lgkmcnt(3)
	v_mfma_f32_16x16x32_bf16 v[18:21], v[74:77], v[62:65], 0
	v_mfma_f32_16x16x32_bf16 v[22:25], v[86:89], v[62:65], 0
	s_waitcnt lgkmcnt(1)
	v_mfma_f32_16x16x32_bf16 v[26:29], v[74:77], v[90:93], 0
	v_mfma_f32_16x16x32_bf16 v[30:33], v[86:89], v[90:93], 0
	v_mfma_f32_16x16x32_bf16 v[2:5], v[82:85], v[42:45], v[2:5]
	v_mfma_f32_16x16x32_bf16 v[6:9], v[96:99], v[42:45], v[6:9]
	v_mfma_f32_16x16x32_bf16 v[10:13], v[82:85], v[58:61], v[10:13]
	v_mfma_f32_16x16x32_bf16 v[14:17], v[96:99], v[58:61], v[14:17]
	v_mfma_f32_16x16x32_bf16 v[18:21], v[82:85], v[78:81], v[18:21]
	v_mfma_f32_16x16x32_bf16 v[22:25], v[96:99], v[78:81], v[22:25]
	s_waitcnt lgkmcnt(0)
	v_mfma_f32_16x16x32_bf16 v[26:29], v[82:85], v[100:103], v[26:29]
	v_mfma_f32_16x16x32_bf16 v[30:33], v[96:99], v[100:103], v[30:33]
	s_setprio 0
	s_setprio 1
	v_mfma_f32_16x16x32_bf16 v[34:37], v[50:53], v[38:41], 0
	v_mfma_f32_16x16x32_bf16 v[38:41], v[66:69], v[38:41], 0
	v_mfma_f32_16x16x32_bf16 v[34:37], v[54:57], v[42:45], v[34:37]
	v_mfma_f32_16x16x32_bf16 v[38:41], v[70:73], v[42:45], v[38:41]
	v_mfma_f32_16x16x32_bf16 v[42:45], v[50:53], v[46:49], 0
	v_mfma_f32_16x16x32_bf16 v[46:49], v[66:69], v[46:49], 0
	v_mfma_f32_16x16x32_bf16 v[42:45], v[54:57], v[58:61], v[42:45]
	v_mfma_f32_16x16x32_bf16 v[46:49], v[70:73], v[58:61], v[46:49]
	v_mfma_f32_16x16x32_bf16 v[58:61], v[50:53], v[62:65], 0
	v_mfma_f32_16x16x32_bf16 v[62:65], v[66:69], v[62:65], 0
	v_mfma_f32_16x16x32_bf16 v[58:61], v[54:57], v[78:81], v[58:61]
	v_mfma_f32_16x16x32_bf16 v[62:65], v[70:73], v[78:81], v[62:65]
	v_mfma_f32_16x16x32_bf16 v[78:81], v[50:53], v[90:93], 0
	v_mfma_f32_16x16x32_bf16 v[90:93], v[66:69], v[90:93], 0
	v_mfma_f32_16x16x32_bf16 v[78:81], v[54:57], v[100:103], v[78:81]
	v_mfma_f32_16x16x32_bf16 v[92:95], v[70:73], v[100:103], v[90:93]
	s_setprio 0
	s_barrier
	ds_read_b128 v[162:165], v245 offset:16384
	ds_read_b128 v[166:169], v245 offset:17408
	ds_read_b128 v[154:157], v245 offset:18432
	ds_read_b128 v[158:161], v245 offset:19456
	ds_read_b128 v[146:149], v245 offset:20480
	ds_read_b128 v[150:153], v245 offset:21504
	ds_read_b128 v[110:113], v245 offset:22528
	ds_read_b128 v[126:129], v245 offset:23552
	s_mov_b32 m0, s22
	s_nop 0
	global_load_lds_dwordx4 v251, s[42:43]
	s_add_u32 m0, m0, 0x2000
	s_nop 0
	global_load_lds_dwordx4 v247, s[42:43]
	s_add_u32 s42, s84, 0x580100
	s_addc_u32 s43, s85, 0
	s_mov_b32 m0, s23
	s_nop 0
	global_load_lds_dwordx4 v251, s[42:43]
	s_add_u32 m0, m0, 0x2000
	s_nop 0
	global_load_lds_dwordx4 v247, s[42:43]
	v_cndmask_b32_e64 v90, 0, 1, s[88:89]
	s_mov_b32 m0, s13
	s_nop 0
	global_load_lds_dwordx4 v250, s[14:15]
	s_add_u32 m0, m0, 0x2000
	s_nop 0
	global_load_lds_dwordx4 v246, s[14:15]
	v_cmp_ne_u32_e64 s[42:43], 1, v90
	s_andn2_b64 vcc, exec, s[88:89]
	s_cbranch_vccnz .LBB0_555
	s_waitcnt vmcnt(8)
.LBB0_555:
	s_waitcnt lgkmcnt(0)
	s_barrier
	s_setprio 1
	s_waitcnt lgkmcnt(7)
	v_mfma_f32_16x16x32_bf16 v[100:103], v[74:77], v[162:165], 0
	s_waitcnt lgkmcnt(5)
	v_mfma_f32_16x16x32_bf16 v[114:117], v[74:77], v[154:157], 0
	s_waitcnt lgkmcnt(3)
	v_mfma_f32_16x16x32_bf16 v[122:125], v[74:77], v[146:149], 0
	s_waitcnt lgkmcnt(1)
	v_mfma_f32_16x16x32_bf16 v[74:77], v[74:77], v[110:113], 0
	v_mfma_f32_16x16x32_bf16 v[106:109], v[86:89], v[162:165], 0
	v_mfma_f32_16x16x32_bf16 v[118:121], v[86:89], v[154:157], 0
	v_mfma_f32_16x16x32_bf16 v[130:133], v[86:89], v[146:149], 0
	s_waitcnt lgkmcnt(0)
	v_mfma_f32_16x16x32_bf16 v[134:137], v[82:85], v[126:129], v[74:77]
	v_mfma_f32_16x16x32_bf16 v[74:77], v[86:89], v[110:113], 0
	v_mfma_f32_16x16x32_bf16 v[102:105], v[82:85], v[166:169], v[100:103]
	v_mfma_f32_16x16x32_bf16 v[106:109], v[96:99], v[166:169], v[106:109]
	v_mfma_f32_16x16x32_bf16 v[114:117], v[82:85], v[158:161], v[114:117]
	v_mfma_f32_16x16x32_bf16 v[118:121], v[96:99], v[158:161], v[118:121]
	v_mfma_f32_16x16x32_bf16 v[122:125], v[82:85], v[150:153], v[122:125]
	v_mfma_f32_16x16x32_bf16 v[130:133], v[96:99], v[150:153], v[130:133]
	v_mfma_f32_16x16x32_bf16 v[138:141], v[96:99], v[126:129], v[74:77]
	s_setprio 0
	s_setprio 1
	v_mfma_f32_16x16x32_bf16 v[74:77], v[50:53], v[162:165], 0
	v_mfma_f32_16x16x32_bf16 v[142:145], v[54:57], v[166:169], v[74:77]
	v_mfma_f32_16x16x32_bf16 v[74:77], v[66:69], v[162:165], 0
	v_mfma_f32_16x16x32_bf16 v[166:169], v[70:73], v[166:169], v[74:77]
	v_mfma_f32_16x16x32_bf16 v[74:77], v[50:53], v[154:157], 0
	v_mfma_f32_16x16x32_bf16 v[170:173], v[54:57], v[158:161], v[74:77]
	v_mfma_f32_16x16x32_bf16 v[74:77], v[66:69], v[154:157], 0
	v_mfma_f32_16x16x32_bf16 v[174:177], v[70:73], v[158:161], v[74:77]
	v_mfma_f32_16x16x32_bf16 v[74:77], v[50:53], v[146:149], 0
	v_mfma_f32_16x16x32_bf16 v[50:53], v[50:53], v[110:113], 0
	v_mfma_f32_16x16x32_bf16 v[178:181], v[54:57], v[150:153], v[74:77]
	v_mfma_f32_16x16x32_bf16 v[74:77], v[66:69], v[146:149], 0
	v_mfma_f32_16x16x32_bf16 v[186:189], v[54:57], v[126:129], v[50:53]
	v_mfma_f32_16x16x32_bf16 v[50:53], v[66:69], v[110:113], 0
	v_mfma_f32_16x16x32_bf16 v[182:185], v[70:73], v[150:153], v[74:77]
	v_mfma_f32_16x16x32_bf16 v[190:193], v[70:73], v[126:129], v[50:53]
	s_setprio 0
	s_barrier
	v_add_u32_e32 v235, 0x18000, v244
	v_add_u32_e32 v248, 0x1c000, v244
	ds_read_b128 v[162:165], v235
	ds_read_b128 v[210:213], v235 offset:1024
	ds_read_b128 v[214:217], v235 offset:2048
	ds_read_b128 v[218:221], v235 offset:3072
	ds_read_b128 v[194:197], v248
	ds_read_b128 v[198:201], v248 offset:1024
	ds_read_b128 v[202:205], v248 offset:2048
	ds_read_b128 v[206:209], v248 offset:3072
	ds_read_b128 v[96:99], v245 offset:32768
	ds_read_b128 v[154:157], v245 offset:33792
	ds_read_b128 v[126:129], v245 offset:34816
	ds_read_b128 v[158:161], v245 offset:35840
	ds_read_b128 v[110:113], v245 offset:36864
	ds_read_b128 v[230:233], v245 offset:37888
	ds_read_b128 v[222:225], v245 offset:38912
	ds_read_b128 v[226:229], v245 offset:39936
	s_add_u32 s14, s86, 0x2100
	s_addc_u32 s15, s87, 0
	s_mov_b32 m0, s45
	s_nop 0
	global_load_lds_dwordx4 v250, s[14:15]
	s_add_u32 m0, m0, 0x2000
	s_nop 0
	global_load_lds_dwordx4 v246, s[14:15]
	s_and_b64 vcc, exec, s[42:43]
	s_cbranch_vccnz .LBB0_557
	s_waitcnt vmcnt(8)
; #define PG8_BAR __builtin_amdgcn_s_barrier()
; template <class Epi, bool ALIGN_EPI, bool EARLY_DRAIN = true, class Pre = NoPre>
; __device__ __forceinline__ void gemm_phase(LAS unsigned char* lds, const Gemm g, const StaticOrder& S, const Epi& E, int wv, const Pre& pre = Pre()) {
;     ...
;         const bool has_next = S.next(ui + 1, nxt);
;         const char* nA = has_next ? g.A + (size_t)nxt.pm * g.a_tstep + (size_t)(nxt.pm >> 6) * g.a_pad : cA; const char* nB = has_next ? g.Bt + (size_t)nxt.pn * g.b_tstep : cB;
;         int landed_flag = fresh ? 1 : 0;
;         typename Epi::PF pf;
;         if constexpr (Epi::PREF) { int pt_ = lane_now(); asm volatile("" : "+v"(pt_)); E.prefetch(pf, cur, wr, wc, pt_ & 15, pt_ >> 4); }
;         for (int th = 0; th < nt; th += (Epi::MIDK ? nt / 2 : nt)) {
;         if constexpr (Epi::MIDK) { if (th) E.midk(acc, ui, wr, fr); }
;         for (int t = th; t < th + (Epi::MIDK ? nt / 2 : nt); t += 2) {
;             const bool last = (t == nt - 2);
;             const char* a1 = cA + (size_t)(t + 1) * kstep;
;             const char* a2 = last ? nA : cA + (size_t)(t + 2) * kstep; const char* b2 = last ? nB : cB + (size_t)(t + 2) * kstep;
;             const char* a3 = a2 + kstep; const char* b3 = b2 + kstep;
;             int lf_ = EARLY_DRAIN ? __builtin_amdgcn_readfirstlane(landed_flag) : landed_flag; if constexpr (EARLY_DRAIN) asm volatile("" : "+s"(lf_)); landed_flag = 0;
;             PG8_LDB(B0, 0, 0); PG8_LDB(B1, 0, 1); PG8_SCHED; PG8_LDA(At, 0, 0); PG8_STAGE(PG8_SA(1, 1), a1 + ahs, voffA);
;             if (!lf_) PG8_WAIT_V(8);
;             PG8_WAIT_L(0); PG8_BAR; PG8_MMA(0, 0, At, B0); PG8_MMA(0, 1, At, B1); PG8_BAR; PG8_SCHED;
;             PG8_LDA(At, 0, 1); PG8_STAGE(PG8_SB(0, 0), b2, voffB); PG8_STAGE(PG8_SB(0, 1), b2 + bhs, voffB); PG8_STAGE(PG8_SA(0, 0), a2, voffA);
;             if (!lf_) PG8_WAIT_V(8);
;             PG8_WAIT_L(0); PG8_BAR; PG8_MMA(1, 0, At, B0); PG8_MMA(1, 1, At, B1); PG8_BAR; PG8_SCHED;
;             PG8_LDB(B0, 1, 0); PG8_LDB(B1, 1, 1); PG8_SCHED; PG8_LDA(At, 1, 0); PG8_STAGE(PG8_SA(0, 1), a2 + ahs, voffA);
;             if (!lf_) PG8_WAIT_V(8);
;             PG8_WAIT_L(0); PG8_BAR; PG8_MMA(0, 0, At, B0); PG8_MMA(0, 1, At, B1); PG8_BAR; PG8_SCHED;
;             PG8_LDA(At, 1, 1); PG8_STAGE(PG8_SB(1, 0), b3, voffB); PG8_STAGE(PG8_SB(1, 1), b3 + bhs, voffB); PG8_STAGE(PG8_SA(1, 0), a3, voffA);
.LBB0_557:
	s_ashr_i32 s61, s60, 31
	s_lshl_b64 s[14:15], s[60:61], 18
	s_add_u32 s88, s5, s14
	s_addc_u32 s89, s12, s15
	s_and_b64 s[14:15], s[40:41], exec
	s_cselect_b32 s47, s89, s85
	s_cselect_b32 s50, s88, s84
	s_add_u32 s14, s86, 0x180
	s_waitcnt lgkmcnt(0)
	s_addc_u32 s15, s87, 0
	s_add_u32 s40, s84, 0x180
	s_addc_u32 s41, s85, 0
	s_barrier
	s_setprio 1
	s_waitcnt lgkmcnt(7)
	v_mfma_f32_16x16x32_bf16 v[2:5], v[162:165], v[96:99], v[2:5]
	s_waitcnt lgkmcnt(6)
	v_mfma_f32_16x16x32_bf16 v[70:73], v[210:213], v[154:157], v[2:5]
	v_mfma_f32_16x16x32_bf16 v[2:5], v[214:217], v[96:99], v[6:9]
	v_mfma_f32_16x16x32_bf16 v[146:149], v[218:221], v[154:157], v[2:5]
	s_waitcnt lgkmcnt(5)
	v_mfma_f32_16x16x32_bf16 v[2:5], v[162:165], v[126:129], v[10:13]
	s_waitcnt lgkmcnt(4)
	v_mfma_f32_16x16x32_bf16 v[74:77], v[210:213], v[158:161], v[2:5]
	v_mfma_f32_16x16x32_bf16 v[2:5], v[214:217], v[126:129], v[14:17]
	v_mfma_f32_16x16x32_bf16 v[150:153], v[218:221], v[158:161], v[2:5]
	s_waitcnt lgkmcnt(3)
	v_mfma_f32_16x16x32_bf16 v[2:5], v[162:165], v[110:113], v[18:21]
	s_waitcnt lgkmcnt(2)
	v_mfma_f32_16x16x32_bf16 v[82:85], v[210:213], v[230:233], v[2:5]
	v_mfma_f32_16x16x32_bf16 v[2:5], v[214:217], v[110:113], v[22:25]
	v_mfma_f32_16x16x32_bf16 v[66:69], v[218:221], v[230:233], v[2:5]
	s_waitcnt lgkmcnt(1)
	v_mfma_f32_16x16x32_bf16 v[2:5], v[162:165], v[222:225], v[26:29]
	s_waitcnt lgkmcnt(0)
	v_mfma_f32_16x16x32_bf16 v[54:57], v[210:213], v[226:229], v[2:5]
	v_mfma_f32_16x16x32_bf16 v[2:5], v[214:217], v[222:225], v[30:33]
	v_mfma_f32_16x16x32_bf16 v[50:53], v[218:221], v[226:229], v[2:5]
	s_setprio 0
	s_setprio 1
	v_mfma_f32_16x16x32_bf16 v[2:5], v[194:197], v[96:99], v[34:37]
	v_mfma_f32_16x16x32_bf16 v[88:91], v[198:201], v[154:157], v[2:5]
	v_mfma_f32_16x16x32_bf16 v[2:5], v[202:205], v[96:99], v[38:41]
	v_mfma_f32_16x16x32_bf16 v[154:157], v[206:209], v[154:157], v[2:5]
	v_mfma_f32_16x16x32_bf16 v[2:5], v[194:197], v[126:129], v[42:45]
	v_mfma_f32_16x16x32_bf16 v[98:101], v[198:201], v[158:161], v[2:5]
	v_mfma_f32_16x16x32_bf16 v[2:5], v[202:205], v[126:129], v[46:49]
	v_mfma_f32_16x16x32_bf16 v[158:161], v[206:209], v[158:161], v[2:5]
	v_mfma_f32_16x16x32_bf16 v[2:5], v[194:197], v[110:113], v[58:61]
	v_mfma_f32_16x16x32_bf16 v[126:129], v[198:201], v[230:233], v[2:5]
	v_mfma_f32_16x16x32_bf16 v[2:5], v[202:205], v[110:113], v[62:65]
	v_mfma_f32_16x16x32_bf16 v[110:113], v[206:209], v[230:233], v[2:5]
	v_mfma_f32_16x16x32_bf16 v[2:5], v[194:197], v[222:225], v[78:81]
	v_mfma_f32_16x16x32_bf16 v[62:65], v[198:201], v[226:229], v[2:5]
	v_mfma_f32_16x16x32_bf16 v[2:5], v[202:205], v[222:225], v[92:95]
	v_mfma_f32_16x16x32_bf16 v[58:61], v[206:209], v[226:229], v[2:5]
	s_setprio 0
	s_barrier
	ds_read_b128 v[10:13], v245 offset:49152
	ds_read_b128 v[14:17], v245 offset:50176
	ds_read_b128 v[22:25], v245 offset:51200
	ds_read_b128 v[78:81], v245 offset:52224
	ds_read_b128 v[92:95], v245 offset:53248
	ds_read_b128 v[222:225], v245 offset:54272
	ds_read_b128 v[226:229], v245 offset:55296
	ds_read_b128 v[230:233], v245 offset:56320
	s_mov_b32 m0, s64
	s_nop 0
	global_load_lds_dwordx4 v251, s[40:41]
	s_add_u32 m0, m0, 0x2000
	s_nop 0
	global_load_lds_dwordx4 v247, s[40:41]
	s_add_u32 s40, s84, 0x580180
	s_addc_u32 s41, s85, 0
	s_mov_b32 m0, s66
	s_nop 0
	global_load_lds_dwordx4 v251, s[40:41]
	s_add_u32 m0, m0, 0x2000
	s_nop 0
	global_load_lds_dwordx4 v247, s[40:41]
	s_nop 0
	s_mov_b32 m0, s65
	s_nop 0
	global_load_lds_dwordx4 v250, s[14:15]
	s_add_u32 m0, m0, 0x2000
	s_nop 0
	global_load_lds_dwordx4 v246, s[14:15]
	s_waitcnt vmcnt(8)
	s_waitcnt lgkmcnt(0)
	s_barrier
	s_setprio 1
	s_waitcnt lgkmcnt(7)
	v_mfma_f32_16x16x32_bf16 v[2:5], v[162:165], v[10:13], v[102:105]
	s_waitcnt lgkmcnt(6)
	v_mfma_f32_16x16x32_bf16 v[38:41], v[210:213], v[14:17], v[2:5]
	v_mfma_f32_16x16x32_bf16 v[2:5], v[214:217], v[10:13], v[106:109]
	v_mfma_f32_16x16x32_bf16 v[34:37], v[218:221], v[14:17], v[2:5]
	s_waitcnt lgkmcnt(5)
	v_mfma_f32_16x16x32_bf16 v[2:5], v[162:165], v[22:25], v[114:117]
	s_waitcnt lgkmcnt(4)
	v_mfma_f32_16x16x32_bf16 v[26:29], v[210:213], v[78:81], v[2:5]
	v_mfma_f32_16x16x32_bf16 v[2:5], v[214:217], v[22:25], v[118:121]
	v_mfma_f32_16x16x32_bf16 v[18:21], v[218:221], v[78:81], v[2:5]
	s_waitcnt lgkmcnt(3)
	v_mfma_f32_16x16x32_bf16 v[2:5], v[162:165], v[92:95], v[122:125]
	s_waitcnt lgkmcnt(1)
	v_mfma_f32_16x16x32_bf16 v[30:33], v[162:165], v[226:229], v[134:137]
	v_mfma_f32_16x16x32_bf16 v[6:9], v[210:213], v[222:225], v[2:5]
	v_mfma_f32_16x16x32_bf16 v[2:5], v[214:217], v[92:95], v[130:133]
	s_waitcnt lgkmcnt(0)
	v_mfma_f32_16x16x32_bf16 v[106:109], v[210:213], v[230:233], v[30:33]
	v_mfma_f32_16x16x32_bf16 v[30:33], v[214:217], v[226:229], v[138:141]
	v_mfma_f32_16x16x32_bf16 v[2:5], v[218:221], v[222:225], v[2:5]
	v_mfma_f32_16x16x32_bf16 v[162:165], v[218:221], v[230:233], v[30:33]
	s_setprio 0
	s_setprio 1
	v_mfma_f32_16x16x32_bf16 v[30:33], v[194:197], v[10:13], v[142:145]
	v_mfma_f32_16x16x32_bf16 v[10:13], v[202:205], v[10:13], v[166:169]
	v_mfma_f32_16x16x32_bf16 v[42:45], v[206:209], v[14:17], v[10:13]
	v_mfma_f32_16x16x32_bf16 v[10:13], v[194:197], v[22:25], v[170:173]
	v_mfma_f32_16x16x32_bf16 v[46:49], v[198:201], v[14:17], v[30:33]
	v_mfma_f32_16x16x32_bf16 v[30:33], v[198:201], v[78:81], v[10:13]
	v_mfma_f32_16x16x32_bf16 v[10:13], v[202:205], v[22:25], v[174:177]
	v_mfma_f32_16x16x32_bf16 v[22:25], v[206:209], v[78:81], v[10:13]
	v_mfma_f32_16x16x32_bf16 v[10:13], v[194:197], v[92:95], v[178:181]
	v_mfma_f32_16x16x32_bf16 v[78:81], v[194:197], v[226:229], v[186:189]
	v_mfma_f32_16x16x32_bf16 v[14:17], v[198:201], v[222:225], v[10:13]
	v_mfma_f32_16x16x32_bf16 v[10:13], v[202:205], v[92:95], v[182:185]
	v_mfma_f32_16x16x32_bf16 v[114:117], v[198:201], v[230:233], v[78:81]
	v_mfma_f32_16x16x32_bf16 v[78:81], v[202:205], v[226:229], v[190:193]
	v_mfma_f32_16x16x32_bf16 v[10:13], v[206:209], v[222:225], v[10:13]
	v_mfma_f32_16x16x32_bf16 v[166:169], v[206:209], v[230:233], v[78:81]
	s_setprio 0
	s_barrier
	s_add_u32 s51, s86, 0x200
	s_addc_u32 s52, s87, 0
	s_add_u32 s53, s84, 0x200
	s_addc_u32 s61, s85, 0
	s_add_u32 s42, s86, 0x2180
	s_addc_u32 s43, s87, 0
	s_mov_b32 s0, 0
	s_branch .LBB0_559
; #define PG8_STAGE(bufoff, gbase, voff) glds16s2((voff)[0], (voff)[1], (const void*)(gbase), ldsn + (unsigned)(bufoff))
; #define PG8_LDA(dst, b, h) do { _Pragma("unroll") for (int m = 0; m < 4; ++m) _Pragma("unroll") for (int k = 0; k < 2; ++k) dst[m][k] = *(const LAS bf16x8*)(lds + PG8_SA(b, h) + aoff + m * 2048 + k * 1024); } while (0)
; #define PG8_WAIT_V(n) asm volatile("s_waitcnt vmcnt(" #n ")" ::: "memory")
; #define PG8_WAIT_L(n) asm volatile("s_waitcnt lgkmcnt(" #n ")" ::: "memory")
; template <class Epi, bool ALIGN_EPI, bool EARLY_DRAIN = true, class Pre = NoPre>
; __device__ __forceinline__ void gemm_phase(LAS unsigned char* lds, const Gemm g, const StaticOrder& S, const Epi& E, int wv, const Pre& pre = Pre()) {
;     ...
;         for (int t = th; t < th + (Epi::MIDK ? nt / 2 : nt); t += 2) {
;             const bool last = (t == nt - 2);
;             const char* a1 = cA + (size_t)(t + 1) * kstep;
;             const char* a2 = last ? nA : cA + (size_t)(t + 2) * kstep; const char* b2 = last ? nB : cB + (size_t)(t + 2) * kstep;
;             const char* a3 = a2 + kstep; const char* b3 = b2 + kstep;
;             int lf_ = EARLY_DRAIN ? __builtin_amdgcn_readfirstlane(landed_flag) : landed_flag; if constexpr (EARLY_DRAIN) asm volatile("" : "+s"(lf_)); landed_flag = 0;
;             PG8_LDB(B0, 0, 0); PG8_LDB(B1, 0, 1); PG8_SCHED; PG8_LDA(At, 0, 0); PG8_STAGE(PG8_SA(1, 1), a1 + ahs, voffA);
;             if (!lf_) PG8_WAIT_V(8);
;             PG8_WAIT_L(0); PG8_BAR; PG8_MMA(0, 0, At, B0); PG8_MMA(0, 1, At, B1); PG8_BAR; PG8_SCHED;
;             PG8_LDA(At, 0, 1); PG8_STAGE(PG8_SB(0, 0), b2, voffB); PG8_STAGE(PG8_SB(0, 1), b2 + bhs, voffB); PG8_STAGE(PG8_SA(0, 0), a2, voffA);
;             if (!lf_) PG8_WAIT_V(8);
;             PG8_WAIT_L(0); PG8_BAR; PG8_MMA(1, 0, At, B0); PG8_MMA(1, 1, At, B1); PG8_BAR; PG8_SCHED;
;             PG8_LDB(B0, 1, 0); PG8_LDB(B1, 1, 1); PG8_SCHED; PG8_LDA(At, 1, 0); PG8_STAGE(PG8_SA(0, 1), a2 + ahs, voffA);
;             if (!lf_) PG8_WAIT_V(8);
;             PG8_WAIT_L(0); PG8_BAR; PG8_MMA(0, 0, At, B0); PG8_MMA(0, 1, At, B1); PG8_BAR; PG8_SCHED;
;             PG8_LDA(At, 1, 1); PG8_STAGE(PG8_SB(1, 0), b3, voffB); PG8_STAGE(PG8_SB(1, 1), b3 + bhs, voffB); PG8_STAGE(PG8_SA(1, 0), a3, voffA);
;             PG8_WAIT_V(8); PG8_WAIT_L(0); PG8_BAR; PG8_MMA(1, 0, At, B0); PG8_MMA(1, 1, At, B1); PG8_BAR; PG8_SCHED;
.LBB0_558:
	s_add_u32 s14, s86, 0x80
	s_waitcnt lgkmcnt(0)
	s_addc_u32 s15, s87, 0
	s_add_u32 s40, s84, 0x80
	s_addc_u32 s41, s85, 0
	s_barrier
	s_setprio 1
	s_waitcnt lgkmcnt(7)
	v_mfma_f32_16x16x32_bf16 v[78:81], v[178:181], v[154:157], v[78:81]
	s_waitcnt lgkmcnt(6)
	v_mfma_f32_16x16x32_bf16 v[146:149], v[182:185], v[202:205], v[78:81]
	s_waitcnt lgkmcnt(5)
	v_mfma_f32_16x16x32_bf16 v[78:81], v[178:181], v[126:129], v[92:95]
	v_mfma_f32_16x16x32_bf16 v[70:73], v[162:165], v[154:157], v[70:73]
	v_mfma_f32_16x16x32_bf16 v[74:77], v[162:165], v[126:129], v[74:77]
	s_waitcnt lgkmcnt(4)
	v_mfma_f32_16x16x32_bf16 v[150:153], v[182:185], v[158:161], v[78:81]
	s_waitcnt lgkmcnt(3)
	v_mfma_f32_16x16x32_bf16 v[78:81], v[162:165], v[194:197], v[82:85]
	v_mfma_f32_16x16x32_bf16 v[66:69], v[178:181], v[194:197], v[66:69]
	s_waitcnt lgkmcnt(1)
	v_mfma_f32_16x16x32_bf16 v[54:57], v[162:165], v[186:189], v[54:57]
	v_mfma_f32_16x16x32_bf16 v[50:53], v[178:181], v[186:189], v[50:53]
	v_mfma_f32_16x16x32_bf16 v[70:73], v[174:177], v[202:205], v[70:73]
	v_mfma_f32_16x16x32_bf16 v[74:77], v[174:177], v[158:161], v[74:77]
	v_mfma_f32_16x16x32_bf16 v[82:85], v[174:177], v[198:201], v[78:81]
	v_mfma_f32_16x16x32_bf16 v[66:69], v[182:185], v[198:201], v[66:69]
	s_waitcnt lgkmcnt(0)
	v_mfma_f32_16x16x32_bf16 v[54:57], v[174:177], v[190:193], v[54:57]
	v_mfma_f32_16x16x32_bf16 v[50:53], v[182:185], v[190:193], v[50:53]
	s_setprio 0
	s_setprio 1
	v_mfma_f32_16x16x32_bf16 v[78:81], v[138:141], v[154:157], v[86:89]
	v_mfma_f32_16x16x32_bf16 v[88:91], v[142:145], v[202:205], v[78:81]
	v_mfma_f32_16x16x32_bf16 v[78:81], v[166:169], v[154:157], v[102:105]
	v_mfma_f32_16x16x32_bf16 v[154:157], v[170:173], v[202:205], v[78:81]
	v_mfma_f32_16x16x32_bf16 v[78:81], v[138:141], v[126:129], v[96:99]
	v_mfma_f32_16x16x32_bf16 v[98:101], v[142:145], v[158:161], v[78:81]
	v_mfma_f32_16x16x32_bf16 v[78:81], v[166:169], v[126:129], v[118:121]
	v_mfma_f32_16x16x32_bf16 v[158:161], v[170:173], v[158:161], v[78:81]
	v_mfma_f32_16x16x32_bf16 v[78:81], v[138:141], v[194:197], v[122:125]
	v_mfma_f32_16x16x32_bf16 v[126:129], v[142:145], v[198:201], v[78:81]
	v_mfma_f32_16x16x32_bf16 v[78:81], v[166:169], v[194:197], v[110:113]
	v_mfma_f32_16x16x32_bf16 v[62:65], v[138:141], v[186:189], v[62:65]
	v_mfma_f32_16x16x32_bf16 v[58:61], v[166:169], v[186:189], v[58:61]
	v_mfma_f32_16x16x32_bf16 v[110:113], v[170:173], v[198:201], v[78:81]
	v_mfma_f32_16x16x32_bf16 v[62:65], v[142:145], v[190:193], v[62:65]
	v_mfma_f32_16x16x32_bf16 v[58:61], v[170:173], v[190:193], v[58:61]
	s_setprio 0
	s_barrier
	s_nop 0
	ds_read_b128 v[78:81], v245 offset:49152
	ds_read_b128 v[92:95], v245 offset:50176
	ds_read_b128 v[102:105], v245 offset:51200
	ds_read_b128 v[118:121], v245 offset:52224
	ds_read_b128 v[122:125], v245 offset:53248
	ds_read_b128 v[186:189], v245 offset:54272
	ds_read_b128 v[190:193], v245 offset:55296
	ds_read_b128 v[194:197], v245 offset:56320
	s_mov_b32 m0, s64
	s_nop 0
	global_load_lds_dwordx4 v251, s[40:41]
	s_add_u32 m0, m0, 0x2000
	s_nop 0
	global_load_lds_dwordx4 v247, s[40:41]
	s_add_u32 s40, s84, 0x580080
	s_addc_u32 s41, s85, 0
	s_mov_b32 m0, s66
	s_nop 0
	global_load_lds_dwordx4 v251, s[40:41]
	s_add_u32 m0, m0, 0x2000
	s_nop 0
	global_load_lds_dwordx4 v247, s[40:41]
	s_nop 0
	s_mov_b32 m0, s65
	s_nop 0
	global_load_lds_dwordx4 v250, s[14:15]
	s_add_u32 m0, m0, 0x2000
	s_nop 0
	global_load_lds_dwordx4 v246, s[14:15]
	s_waitcnt vmcnt(8)
	s_waitcnt lgkmcnt(0)
	s_barrier
	s_setprio 1
	s_waitcnt lgkmcnt(7)
	v_mfma_f32_16x16x32_bf16 v[38:41], v[162:165], v[78:81], v[38:41]
	v_mfma_f32_16x16x32_bf16 v[34:37], v[178:181], v[78:81], v[34:37]
	s_waitcnt lgkmcnt(5)
	v_mfma_f32_16x16x32_bf16 v[26:29], v[162:165], v[102:105], v[26:29]
	v_mfma_f32_16x16x32_bf16 v[18:21], v[178:181], v[102:105], v[18:21]
	s_waitcnt lgkmcnt(3)
	v_mfma_f32_16x16x32_bf16 v[6:9], v[162:165], v[122:125], v[6:9]
	v_mfma_f32_16x16x32_bf16 v[2:5], v[178:181], v[122:125], v[2:5]
	s_waitcnt lgkmcnt(1)
	v_mfma_f32_16x16x32_bf16 v[106:109], v[162:165], v[190:193], v[106:109]
	v_mfma_f32_16x16x32_bf16 v[130:133], v[178:181], v[190:193], v[130:133]
	v_mfma_f32_16x16x32_bf16 v[38:41], v[174:177], v[92:95], v[38:41]
	v_mfma_f32_16x16x32_bf16 v[34:37], v[182:185], v[92:95], v[34:37]
	v_mfma_f32_16x16x32_bf16 v[26:29], v[174:177], v[118:121], v[26:29]
	v_mfma_f32_16x16x32_bf16 v[18:21], v[182:185], v[118:121], v[18:21]
	v_mfma_f32_16x16x32_bf16 v[6:9], v[174:177], v[186:189], v[6:9]
	v_mfma_f32_16x16x32_bf16 v[2:5], v[182:185], v[186:189], v[2:5]
	s_waitcnt lgkmcnt(0)
	v_mfma_f32_16x16x32_bf16 v[106:109], v[174:177], v[194:197], v[106:109]
	v_mfma_f32_16x16x32_bf16 v[162:165], v[182:185], v[194:197], v[130:133]
	s_setprio 0
	s_setprio 1
	v_mfma_f32_16x16x32_bf16 v[46:49], v[138:141], v[78:81], v[46:49]
	v_mfma_f32_16x16x32_bf16 v[42:45], v[166:169], v[78:81], v[42:45]
	v_mfma_f32_16x16x32_bf16 v[78:81], v[138:141], v[190:193], v[114:117]
	v_mfma_f32_16x16x32_bf16 v[30:33], v[138:141], v[102:105], v[30:33]
	v_mfma_f32_16x16x32_bf16 v[22:25], v[166:169], v[102:105], v[22:25]
	v_mfma_f32_16x16x32_bf16 v[14:17], v[138:141], v[122:125], v[14:17]
	v_mfma_f32_16x16x32_bf16 v[10:13], v[166:169], v[122:125], v[10:13]
	v_mfma_f32_16x16x32_bf16 v[114:117], v[142:145], v[194:197], v[78:81]
	v_mfma_f32_16x16x32_bf16 v[78:81], v[166:169], v[190:193], v[134:137]
	v_mfma_f32_16x16x32_bf16 v[46:49], v[142:145], v[92:95], v[46:49]
	v_mfma_f32_16x16x32_bf16 v[42:45], v[170:173], v[92:95], v[42:45]
	v_mfma_f32_16x16x32_bf16 v[30:33], v[142:145], v[118:121], v[30:33]
	v_mfma_f32_16x16x32_bf16 v[22:25], v[170:173], v[118:121], v[22:25]
	v_mfma_f32_16x16x32_bf16 v[14:17], v[142:145], v[186:189], v[14:17]
	v_mfma_f32_16x16x32_bf16 v[10:13], v[170:173], v[186:189], v[10:13]
	v_mfma_f32_16x16x32_bf16 v[166:169], v[170:173], v[194:197], v[78:81]
	s_setprio 0
	s_barrier
	s_add_i32 s0, s0, 2
	s_add_u32 s51, s51, 0x100
	s_addc_u32 s52, s52, 0
	s_add_u32 s53, s53, 0x100
	s_addc_u32 s61, s61, 0
	s_add_u32 s42, s42, 0x100
	s_addc_u32 s43, s43, 0
	s_cmp_gt_u32 s0, 13
	s_cbranch_scc1 .LBB0_565

; #define PG8_STAGE(bufoff, gbase, voff) glds16s2((voff)[0], (voff)[1], (const void*)(gbase), ldsn + (unsigned)(bufoff))
; #define PG8_LDA(dst, b, h) do { _Pragma("unroll") for (int m = 0; m < 4; ++m) _Pragma("unroll") for (int k = 0; k < 2; ++k) dst[m][k] = *(const LAS bf16x8*)(lds + PG8_SA(b, h) + aoff + m * 2048 + k * 1024); } while (0)
; #define PG8_WAIT_V(n) asm volatile("s_waitcnt vmcnt(" #n ")" ::: "memory")
; #define PG8_WAIT_L(n) asm volatile("s_waitcnt lgkmcnt(" #n ")" ::: "memory")
; template <class Epi, bool ALIGN_EPI, bool EARLY_DRAIN = true, class Pre = NoPre>
; __device__ __forceinline__ void gemm_phase(LAS unsigned char* lds, const Gemm g, const StaticOrder& S, const Epi& E, int wv, const Pre& pre = Pre()) {
;     ...
;         for (int t = th; t < th + (Epi::MIDK ? nt / 2 : nt); t += 2) {
;             const bool last = (t == nt - 2);
;             const char* a1 = cA + (size_t)(t + 1) * kstep;
;             const char* a2 = last ? nA : cA + (size_t)(t + 2) * kstep; const char* b2 = last ? nB : cB + (size_t)(t + 2) * kstep;
;             const char* a3 = a2 + kstep; const char* b3 = b2 + kstep;
;             int lf_ = EARLY_DRAIN ? __builtin_amdgcn_readfirstlane(landed_flag) : landed_flag; if constexpr (EARLY_DRAIN) asm volatile("" : "+s"(lf_)); landed_flag = 0;
;             PG8_LDB(B0, 0, 0); PG8_LDB(B1, 0, 1); PG8_SCHED; PG8_LDA(At, 0, 0); PG8_STAGE(PG8_SA(1, 1), a1 + ahs, voffA);
;             if (!lf_) PG8_WAIT_V(8);
;             PG8_WAIT_L(0); PG8_BAR; PG8_MMA(0, 0, At, B0); PG8_MMA(0, 1, At, B1); PG8_BAR; PG8_SCHED;
;             PG8_LDA(At, 0, 1); PG8_STAGE(PG8_SB(0, 0), b2, voffB); PG8_STAGE(PG8_SB(0, 1), b2 + bhs, voffB); PG8_STAGE(PG8_SA(0, 0), a2, voffA);
;             if (!lf_) PG8_WAIT_V(8);
;             PG8_WAIT_L(0); PG8_BAR; PG8_MMA(1, 0, At, B0); PG8_MMA(1, 1, At, B1); PG8_BAR; PG8_SCHED;
;             PG8_LDB(B0, 1, 0); PG8_LDB(B1, 1, 1); PG8_SCHED; PG8_LDA(At, 1, 0); PG8_STAGE(PG8_SA(0, 1), a2 + ahs, voffA);
;             if (!lf_) PG8_WAIT_V(8);
;             PG8_WAIT_L(0); PG8_BAR; PG8_MMA(0, 0, At, B0); PG8_MMA(0, 1, At, B1); PG8_BAR; PG8_SCHED;
;             PG8_LDA(At, 1, 1); PG8_STAGE(PG8_SB(1, 0), b3, voffB); PG8_STAGE(PG8_SB(1, 1), b3 + bhs, voffB); PG8_STAGE(PG8_SA(1, 0), a3, voffA);
;             PG8_WAIT_V(8); PG8_WAIT_L(0); PG8_BAR; PG8_MMA(1, 0, At, B0); PG8_MMA(1, 1, At, B1); PG8_BAR; PG8_SCHED;
.LBB0_561:
	s_waitcnt lgkmcnt(0)
	s_cmp_eq_u32 s0, 12
	s_cselect_b32 s87, s71, s52
	s_cselect_b32 s86, s70, s51
	s_cselect_b32 s85, s47, s61
	s_cselect_b32 s84, s50, s53
	s_barrier
	s_setprio 1
	s_waitcnt lgkmcnt(7)
	v_mfma_f32_16x16x32_bf16 v[70:73], v[130:133], v[102:105], v[70:73]
	v_mfma_f32_16x16x32_bf16 v[78:81], v[178:181], v[102:105], v[146:149]
	s_waitcnt lgkmcnt(5)
	v_mfma_f32_16x16x32_bf16 v[74:77], v[130:133], v[118:121], v[74:77]
	v_mfma_f32_16x16x32_bf16 v[92:95], v[178:181], v[118:121], v[150:153]
	s_waitcnt lgkmcnt(3)
	v_mfma_f32_16x16x32_bf16 v[82:85], v[130:133], v[194:197], v[82:85]
	v_mfma_f32_16x16x32_bf16 v[66:69], v[178:181], v[194:197], v[66:69]
	s_waitcnt lgkmcnt(1)
	v_mfma_f32_16x16x32_bf16 v[54:57], v[130:133], v[186:189], v[54:57]
	v_mfma_f32_16x16x32_bf16 v[50:53], v[178:181], v[186:189], v[50:53]
	v_mfma_f32_16x16x32_bf16 v[70:73], v[174:177], v[202:205], v[70:73]
	v_mfma_f32_16x16x32_bf16 v[78:81], v[182:185], v[202:205], v[78:81]
	v_mfma_f32_16x16x32_bf16 v[74:77], v[174:177], v[122:125], v[74:77]
	v_mfma_f32_16x16x32_bf16 v[92:95], v[182:185], v[122:125], v[92:95]
	v_mfma_f32_16x16x32_bf16 v[82:85], v[174:177], v[198:201], v[82:85]
	v_mfma_f32_16x16x32_bf16 v[66:69], v[182:185], v[198:201], v[66:69]
	s_waitcnt lgkmcnt(0)
	v_mfma_f32_16x16x32_bf16 v[54:57], v[174:177], v[190:193], v[54:57]
	v_mfma_f32_16x16x32_bf16 v[50:53], v[182:185], v[190:193], v[50:53]
	s_setprio 0
	s_setprio 1
	v_mfma_f32_16x16x32_bf16 v[96:99], v[134:137], v[118:121], v[98:101]
	v_mfma_f32_16x16x32_bf16 v[118:121], v[142:145], v[118:121], v[158:161]
	v_mfma_f32_16x16x32_bf16 v[86:89], v[134:137], v[102:105], v[88:91]
	v_mfma_f32_16x16x32_bf16 v[102:105], v[142:145], v[102:105], v[154:157]
	v_mfma_f32_16x16x32_bf16 v[96:99], v[138:141], v[122:125], v[96:99]
	v_mfma_f32_16x16x32_bf16 v[118:121], v[170:173], v[122:125], v[118:121]
	v_mfma_f32_16x16x32_bf16 v[122:125], v[134:137], v[194:197], v[126:129]
	v_mfma_f32_16x16x32_bf16 v[110:113], v[142:145], v[194:197], v[110:113]
	v_mfma_f32_16x16x32_bf16 v[62:65], v[134:137], v[186:189], v[62:65]
	v_mfma_f32_16x16x32_bf16 v[58:61], v[142:145], v[186:189], v[58:61]
	v_mfma_f32_16x16x32_bf16 v[86:89], v[138:141], v[202:205], v[86:89]
	v_mfma_f32_16x16x32_bf16 v[102:105], v[170:173], v[202:205], v[102:105]
	v_mfma_f32_16x16x32_bf16 v[122:125], v[138:141], v[198:201], v[122:125]
	v_mfma_f32_16x16x32_bf16 v[110:113], v[170:173], v[198:201], v[110:113]
	v_mfma_f32_16x16x32_bf16 v[62:65], v[138:141], v[190:193], v[62:65]
	v_mfma_f32_16x16x32_bf16 v[58:61], v[170:173], v[190:193], v[58:61]
	s_setprio 0
	s_barrier
	ds_read_b128 v[190:193], v245 offset:16384
	ds_read_b128 v[194:197], v245 offset:17408
	ds_read_b128 v[158:161], v245 offset:18432
	ds_read_b128 v[186:189], v245 offset:19456
	ds_read_b128 v[150:153], v245 offset:20480
	ds_read_b128 v[154:157], v245 offset:21504
	ds_read_b128 v[126:129], v245 offset:22528
	ds_read_b128 v[146:149], v245 offset:23552
	s_mov_b32 m0, s22
	s_nop 0
	global_load_lds_dwordx4 v251, s[84:85]
	s_add_u32 m0, m0, 0x2000
	s_nop 0
	global_load_lds_dwordx4 v247, s[84:85]
	s_add_u32 s14, s84, 0x580000
	s_addc_u32 s15, s85, 0
	s_mov_b32 m0, s23
	s_nop 0
	global_load_lds_dwordx4 v251, s[14:15]
	s_add_u32 m0, m0, 0x2000
	s_nop 0
	global_load_lds_dwordx4 v247, s[14:15]
	v_cndmask_b32_e64 v90, 0, 1, vcc
	s_mov_b32 m0, s13
	s_nop 0
	global_load_lds_dwordx4 v250, s[86:87]
	s_add_u32 m0, m0, 0x2000
	s_nop 0
	global_load_lds_dwordx4 v246, s[86:87]
	v_cmp_ne_u32_e64 s[40:41], 1, v90
	s_andn2_b64 vcc, exec, vcc
	s_cbranch_vccnz .LBB0_563
	s_waitcnt vmcnt(8)
.LBB0_563:
	s_waitcnt lgkmcnt(0)
	s_barrier
	s_setprio 1
	s_waitcnt lgkmcnt(7)
	v_mfma_f32_16x16x32_bf16 v[38:41], v[130:133], v[190:193], v[38:41]
	v_mfma_f32_16x16x32_bf16 v[34:37], v[178:181], v[190:193], v[34:37]
	s_waitcnt lgkmcnt(5)
	v_mfma_f32_16x16x32_bf16 v[26:29], v[130:133], v[158:161], v[26:29]
	v_mfma_f32_16x16x32_bf16 v[18:21], v[178:181], v[158:161], v[18:21]
	s_waitcnt lgkmcnt(3)
	v_mfma_f32_16x16x32_bf16 v[6:9], v[130:133], v[150:153], v[6:9]
	v_mfma_f32_16x16x32_bf16 v[2:5], v[178:181], v[150:153], v[2:5]
	s_waitcnt lgkmcnt(1)
	v_mfma_f32_16x16x32_bf16 v[106:109], v[130:133], v[126:129], v[106:109]
	v_mfma_f32_16x16x32_bf16 v[130:133], v[178:181], v[126:129], v[162:165]
	v_mfma_f32_16x16x32_bf16 v[38:41], v[174:177], v[194:197], v[38:41]
	v_mfma_f32_16x16x32_bf16 v[34:37], v[182:185], v[194:197], v[34:37]
	v_mfma_f32_16x16x32_bf16 v[26:29], v[174:177], v[186:189], v[26:29]
	v_mfma_f32_16x16x32_bf16 v[18:21], v[182:185], v[186:189], v[18:21]
	v_mfma_f32_16x16x32_bf16 v[6:9], v[174:177], v[154:157], v[6:9]
	v_mfma_f32_16x16x32_bf16 v[2:5], v[182:185], v[154:157], v[2:5]
	s_waitcnt lgkmcnt(0)
	v_mfma_f32_16x16x32_bf16 v[106:109], v[174:177], v[146:149], v[106:109]
	v_mfma_f32_16x16x32_bf16 v[130:133], v[182:185], v[146:149], v[130:133]
	s_setprio 0
	s_setprio 1
	v_mfma_f32_16x16x32_bf16 v[46:49], v[134:137], v[190:193], v[46:49]
	v_mfma_f32_16x16x32_bf16 v[42:45], v[142:145], v[190:193], v[42:45]
	v_mfma_f32_16x16x32_bf16 v[30:33], v[134:137], v[158:161], v[30:33]
	v_mfma_f32_16x16x32_bf16 v[22:25], v[142:145], v[158:161], v[22:25]
	v_mfma_f32_16x16x32_bf16 v[14:17], v[134:137], v[150:153], v[14:17]
	v_mfma_f32_16x16x32_bf16 v[10:13], v[142:145], v[150:153], v[10:13]
	v_mfma_f32_16x16x32_bf16 v[114:117], v[134:137], v[126:129], v[114:117]
	v_mfma_f32_16x16x32_bf16 v[126:129], v[142:145], v[126:129], v[166:169]
	v_mfma_f32_16x16x32_bf16 v[46:49], v[138:141], v[194:197], v[46:49]
	v_mfma_f32_16x16x32_bf16 v[42:45], v[170:173], v[194:197], v[42:45]
	v_mfma_f32_16x16x32_bf16 v[30:33], v[138:141], v[186:189], v[30:33]
	v_mfma_f32_16x16x32_bf16 v[22:25], v[170:173], v[186:189], v[22:25]
	v_mfma_f32_16x16x32_bf16 v[14:17], v[138:141], v[154:157], v[14:17]
	v_mfma_f32_16x16x32_bf16 v[10:13], v[170:173], v[154:157], v[10:13]
	v_mfma_f32_16x16x32_bf16 v[114:117], v[138:141], v[146:149], v[114:117]
	v_mfma_f32_16x16x32_bf16 v[134:137], v[170:173], v[146:149], v[126:129]
	s_setprio 0
	s_barrier
	ds_read_b128 v[162:165], v235
	ds_read_b128 v[174:177], v235 offset:1024
	ds_read_b128 v[178:181], v235 offset:2048
	ds_read_b128 v[182:185], v235 offset:3072
	ds_read_b128 v[138:141], v248
	ds_read_b128 v[142:145], v248 offset:1024
	ds_read_b128 v[166:169], v248 offset:2048
	ds_read_b128 v[170:173], v248 offset:3072
	ds_read_b128 v[154:157], v245 offset:32768
	ds_read_b128 v[202:205], v245 offset:33792
	ds_read_b128 v[126:129], v245 offset:34816
	ds_read_b128 v[158:161], v245 offset:35840
	ds_read_b128 v[194:197], v245 offset:36864
	ds_read_b128 v[198:201], v245 offset:37888
	ds_read_b128 v[186:189], v245 offset:38912
	ds_read_b128 v[190:193], v245 offset:39936
	s_add_u32 s14, s86, 0x2000
	s_addc_u32 s15, s87, 0
	s_mov_b32 m0, s45
	s_nop 0
	global_load_lds_dwordx4 v250, s[14:15]
	s_add_u32 m0, m0, 0x2000
	s_nop 0
	global_load_lds_dwordx4 v246, s[14:15]
	s_and_b64 vcc, exec, s[40:41]
	s_cbranch_vccnz .LBB0_558
	s_waitcnt vmcnt(8)
	s_branch .LBB0_558

; #define PG8_STAGE(bufoff, gbase, voff) glds16s2((voff)[0], (voff)[1], (const void*)(gbase), ldsn + (unsigned)(bufoff))
; #define PG8_LDA(dst, b, h) do { _Pragma("unroll") for (int m = 0; m < 4; ++m) _Pragma("unroll") for (int k = 0; k < 2; ++k) dst[m][k] = *(const LAS bf16x8*)(lds + PG8_SA(b, h) + aoff + m * 2048 + k * 1024); } while (0)
; #define PG8_WAIT_V(n) asm volatile("s_waitcnt vmcnt(" #n ")" ::: "memory")
; #define PG8_WAIT_L(n) asm volatile("s_waitcnt lgkmcnt(" #n ")" ::: "memory")
; template <class Epi, bool ALIGN_EPI, bool EARLY_DRAIN = true, class Pre = NoPre>
; __device__ __forceinline__ void gemm_phase(LAS unsigned char* lds, const Gemm g, const StaticOrder& S, const Epi& E, int wv, const Pre& pre = Pre()) {
;     ...
;         for (int t = th; t < th + (Epi::MIDK ? nt / 2 : nt); t += 2) {
;             const bool last = (t == nt - 2);
;             const char* a1 = cA + (size_t)(t + 1) * kstep;
;             const char* a2 = last ? nA : cA + (size_t)(t + 2) * kstep; const char* b2 = last ? nB : cB + (size_t)(t + 2) * kstep;
;             const char* a3 = a2 + kstep; const char* b3 = b2 + kstep;
;             int lf_ = EARLY_DRAIN ? __builtin_amdgcn_readfirstlane(landed_flag) : landed_flag; if constexpr (EARLY_DRAIN) asm volatile("" : "+s"(lf_)); landed_flag = 0;
;             PG8_LDB(B0, 0, 0); PG8_LDB(B1, 0, 1); PG8_SCHED; PG8_LDA(At, 0, 0); PG8_STAGE(PG8_SA(1, 1), a1 + ahs, voffA);
;             if (!lf_) PG8_WAIT_V(8);
;             PG8_WAIT_L(0); PG8_BAR; PG8_MMA(0, 0, At, B0); PG8_MMA(0, 1, At, B1); PG8_BAR; PG8_SCHED;
;             PG8_LDA(At, 0, 1); PG8_STAGE(PG8_SB(0, 0), b2, voffB); PG8_STAGE(PG8_SB(0, 1), b2 + bhs, voffB); PG8_STAGE(PG8_SA(0, 0), a2, voffA);
;             if (!lf_) PG8_WAIT_V(8);
;             PG8_WAIT_L(0); PG8_BAR; PG8_MMA(1, 0, At, B0); PG8_MMA(1, 1, At, B1); PG8_BAR; PG8_SCHED;
;             PG8_LDB(B0, 1, 0); PG8_LDB(B1, 1, 1); PG8_SCHED; PG8_LDA(At, 1, 0); PG8_STAGE(PG8_SA(0, 1), a2 + ahs, voffA);
;             if (!lf_) PG8_WAIT_V(8);
;             PG8_WAIT_L(0); PG8_BAR; PG8_MMA(0, 0, At, B0); PG8_MMA(0, 1, At, B1); PG8_BAR; PG8_SCHED;
;             PG8_LDA(At, 1, 1); PG8_STAGE(PG8_SB(1, 0), b3, voffB); PG8_STAGE(PG8_SB(1, 1), b3 + bhs, voffB); PG8_STAGE(PG8_SA(1, 0), a3, voffA);
;             PG8_WAIT_V(8); PG8_WAIT_L(0); PG8_BAR; PG8_MMA(1, 0, At, B0); PG8_MMA(1, 1, At, B1); PG8_BAR; PG8_SCHED;
.LBB0_690:
	v_add_u32_e32 v174, 0x10000, v201
	v_add_u32_e32 v190, 0x14000, v201
	ds_read_b128 v[146:149], v174
	ds_read_b128 v[158:161], v174 offset:1024
	ds_read_b128 v[166:169], v174 offset:2048
	ds_read_b128 v[174:177], v174 offset:3072
	ds_read_b128 v[178:181], v190
	ds_read_b128 v[182:185], v190 offset:1024
	ds_read_b128 v[186:189], v190 offset:2048
	ds_read_b128 v[190:193], v190 offset:3072
	s_cmp_eq_u32 s80, 40
	s_cselect_b32 s68, s30, s52
	s_cselect_b32 s69, s31, s53
	s_cselect_b32 s60, s34, s70
	s_cselect_b32 s61, s35, s71
	s_add_u32 s40, s68, 0x80
	s_addc_u32 s41, s69, 0
	ds_read_b128 v[194:197], v202
	ds_read_b128 v[204:207], v202 offset:1024
	ds_read_b128 v[208:211], v202 offset:2048
	ds_read_b128 v[212:215], v202 offset:3072
	ds_read_b128 v[216:219], v202 offset:4096
	ds_read_b128 v[220:223], v202 offset:5120
	ds_read_b128 v[224:227], v202 offset:6144
	ds_read_b128 v[228:231], v202 offset:7168
	s_mov_b32 m0, s27
	s_nop 0
	global_load_lds_dwordx4 v0, s[36:37]
	s_add_u32 m0, m0, 0x2000
	s_nop 0
	global_load_lds_dwordx4 v199, s[36:37]
	s_waitcnt vmcnt(8)
	s_waitcnt lgkmcnt(0)
	s_barrier
	s_setprio 1
	s_waitcnt lgkmcnt(7)
	v_mfma_f32_16x16x32_bf16 v[170:173], v[146:149], v[194:197], v[170:173]
	v_mfma_f32_16x16x32_bf16 v[162:165], v[166:169], v[194:197], v[162:165]
	s_waitcnt lgkmcnt(5)
	v_mfma_f32_16x16x32_bf16 v[142:145], v[146:149], v[208:211], v[142:145]
	v_mfma_f32_16x16x32_bf16 v[138:141], v[166:169], v[208:211], v[138:141]
	s_waitcnt lgkmcnt(3)
	v_mfma_f32_16x16x32_bf16 v[126:129], v[146:149], v[216:219], v[126:129]
	v_mfma_f32_16x16x32_bf16 v[122:125], v[166:169], v[216:219], v[122:125]
	s_waitcnt lgkmcnt(1)
	v_mfma_f32_16x16x32_bf16 v[102:105], v[146:149], v[224:227], v[102:105]
	v_mfma_f32_16x16x32_bf16 v[98:101], v[166:169], v[224:227], v[98:101]
	v_mfma_f32_16x16x32_bf16 v[170:173], v[158:161], v[204:207], v[170:173]
	v_mfma_f32_16x16x32_bf16 v[162:165], v[174:177], v[204:207], v[162:165]
	v_mfma_f32_16x16x32_bf16 v[142:145], v[158:161], v[212:215], v[142:145]
	v_mfma_f32_16x16x32_bf16 v[138:141], v[174:177], v[212:215], v[138:141]
	v_mfma_f32_16x16x32_bf16 v[126:129], v[158:161], v[220:223], v[126:129]
	v_mfma_f32_16x16x32_bf16 v[122:125], v[174:177], v[220:223], v[122:125]
	s_waitcnt lgkmcnt(0)
	v_mfma_f32_16x16x32_bf16 v[102:105], v[158:161], v[228:231], v[102:105]
	v_mfma_f32_16x16x32_bf16 v[98:101], v[174:177], v[228:231], v[98:101]
	s_setprio 0
	s_setprio 1
	v_mfma_f32_16x16x32_bf16 v[154:157], v[178:181], v[194:197], v[154:157]
	v_mfma_f32_16x16x32_bf16 v[150:153], v[186:189], v[194:197], v[150:153]
	v_mfma_f32_16x16x32_bf16 v[134:137], v[178:181], v[208:211], v[134:137]
	v_mfma_f32_16x16x32_bf16 v[130:133], v[186:189], v[208:211], v[130:133]
	v_mfma_f32_16x16x32_bf16 v[114:117], v[178:181], v[216:219], v[114:117]
	v_mfma_f32_16x16x32_bf16 v[106:109], v[186:189], v[216:219], v[106:109]
	v_mfma_f32_16x16x32_bf16 v[86:89], v[178:181], v[224:227], v[86:89]
	v_mfma_f32_16x16x32_bf16 v[82:85], v[186:189], v[224:227], v[82:85]
	v_mfma_f32_16x16x32_bf16 v[154:157], v[182:185], v[204:207], v[154:157]
	v_mfma_f32_16x16x32_bf16 v[150:153], v[190:193], v[204:207], v[150:153]
	v_mfma_f32_16x16x32_bf16 v[134:137], v[182:185], v[212:215], v[134:137]
	v_mfma_f32_16x16x32_bf16 v[130:133], v[190:193], v[212:215], v[130:133]
	v_mfma_f32_16x16x32_bf16 v[114:117], v[182:185], v[220:223], v[114:117]
	v_mfma_f32_16x16x32_bf16 v[106:109], v[190:193], v[220:223], v[106:109]
	v_mfma_f32_16x16x32_bf16 v[86:89], v[182:185], v[228:231], v[86:89]
	v_mfma_f32_16x16x32_bf16 v[82:85], v[190:193], v[228:231], v[82:85]
	s_setprio 0
	s_barrier
	ds_read_b128 v[194:197], v202 offset:16384
	ds_read_b128 v[204:207], v202 offset:17408
	ds_read_b128 v[208:211], v202 offset:18432
	ds_read_b128 v[212:215], v202 offset:19456
	ds_read_b128 v[216:219], v202 offset:20480
	ds_read_b128 v[220:223], v202 offset:21504
	ds_read_b128 v[224:227], v202 offset:22528
	ds_read_b128 v[228:231], v202 offset:23552
	s_mov_b32 m0, s10
	s_nop 0
	global_load_lds_dwordx4 v198, s[60:61]
	s_add_u32 m0, m0, 0x2000
	s_nop 0
	global_load_lds_dwordx4 v200, s[60:61]
	s_add_u32 s14, s60, 0xb0000
	s_addc_u32 s15, s61, 0
	s_mov_b32 m0, s12
	s_nop 0
	global_load_lds_dwordx4 v198, s[14:15]
	s_add_u32 m0, m0, 0x2000
	s_nop 0
	global_load_lds_dwordx4 v200, s[14:15]
	s_nop 0
	s_mov_b32 m0, s5
	s_nop 0
	global_load_lds_dwordx4 v0, s[68:69]
	s_add_u32 m0, m0, 0x2000
	s_nop 0
	global_load_lds_dwordx4 v199, s[68:69]
	s_waitcnt vmcnt(8)
	s_waitcnt lgkmcnt(0)
	s_barrier
; #define PG8_STAGE(bufoff, gbase, voff) glds16s2((voff)[0], (voff)[1], (const void*)(gbase), ldsn + (unsigned)(bufoff))
; #define PG8_LDA(dst, b, h) do { _Pragma("unroll") for (int m = 0; m < 4; ++m) _Pragma("unroll") for (int k = 0; k < 2; ++k) dst[m][k] = *(const LAS bf16x8*)(lds + PG8_SA(b, h) + aoff + m * 2048 + k * 1024); } while (0)
; #define PG8_WAIT_V(n) asm volatile("s_waitcnt vmcnt(" #n ")" ::: "memory")
; #define PG8_WAIT_L(n) asm volatile("s_waitcnt lgkmcnt(" #n ")" ::: "memory")
; template <class Epi, bool ALIGN_EPI, bool EARLY_DRAIN = true, class Pre = NoPre>
; __device__ __forceinline__ void gemm_phase(LAS unsigned char* lds, const Gemm g, const StaticOrder& S, const Epi& E, int wv, const Pre& pre = Pre()) {
;     ...
;         for (int t = th; t < th + (Epi::MIDK ? nt / 2 : nt); t += 2) {
;             const bool last = (t == nt - 2);
;             const char* a1 = cA + (size_t)(t + 1) * kstep;
;             const char* a2 = last ? nA : cA + (size_t)(t + 2) * kstep; const char* b2 = last ? nB : cB + (size_t)(t + 2) * kstep;
;             const char* a3 = a2 + kstep; const char* b3 = b2 + kstep;
;             int lf_ = EARLY_DRAIN ? __builtin_amdgcn_readfirstlane(landed_flag) : landed_flag; if constexpr (EARLY_DRAIN) asm volatile("" : "+s"(lf_)); landed_flag = 0;
;             PG8_LDB(B0, 0, 0); PG8_LDB(B1, 0, 1); PG8_SCHED; PG8_LDA(At, 0, 0); PG8_STAGE(PG8_SA(1, 1), a1 + ahs, voffA);
;             if (!lf_) PG8_WAIT_V(8);
;             PG8_WAIT_L(0); PG8_BAR; PG8_MMA(0, 0, At, B0); PG8_MMA(0, 1, At, B1); PG8_BAR; PG8_SCHED;
;             PG8_LDA(At, 0, 1); PG8_STAGE(PG8_SB(0, 0), b2, voffB); PG8_STAGE(PG8_SB(0, 1), b2 + bhs, voffB); PG8_STAGE(PG8_SA(0, 0), a2, voffA);
;             if (!lf_) PG8_WAIT_V(8);
;             PG8_WAIT_L(0); PG8_BAR; PG8_MMA(1, 0, At, B0); PG8_MMA(1, 1, At, B1); PG8_BAR; PG8_SCHED;
;             PG8_LDB(B0, 1, 0); PG8_LDB(B1, 1, 1); PG8_SCHED; PG8_LDA(At, 1, 0); PG8_STAGE(PG8_SA(0, 1), a2 + ahs, voffA);
;             if (!lf_) PG8_WAIT_V(8);
;             PG8_WAIT_L(0); PG8_BAR; PG8_MMA(0, 0, At, B0); PG8_MMA(0, 1, At, B1); PG8_BAR; PG8_SCHED;
;             PG8_LDA(At, 1, 1); PG8_STAGE(PG8_SB(1, 0), b3, voffB); PG8_STAGE(PG8_SB(1, 1), b3 + bhs, voffB); PG8_STAGE(PG8_SA(1, 0), a3, voffA);
;             PG8_WAIT_V(8); PG8_WAIT_L(0); PG8_BAR; PG8_MMA(1, 0, At, B0); PG8_MMA(1, 1, At, B1); PG8_BAR; PG8_SCHED;
	s_setprio 1
	s_waitcnt lgkmcnt(7)
	v_mfma_f32_16x16x32_bf16 v[74:77], v[146:149], v[194:197], v[74:77]
	v_mfma_f32_16x16x32_bf16 v[70:73], v[166:169], v[194:197], v[70:73]
	s_waitcnt lgkmcnt(5)
	v_mfma_f32_16x16x32_bf16 v[50:53], v[146:149], v[208:211], v[50:53]
	v_mfma_f32_16x16x32_bf16 v[46:49], v[166:169], v[208:211], v[46:49]
	s_waitcnt lgkmcnt(3)
	v_mfma_f32_16x16x32_bf16 v[30:33], v[146:149], v[216:219], v[30:33]
	v_mfma_f32_16x16x32_bf16 v[26:29], v[166:169], v[216:219], v[26:29]
	s_waitcnt lgkmcnt(1)
	v_mfma_f32_16x16x32_bf16 v[14:17], v[146:149], v[224:227], v[14:17]
	v_mfma_f32_16x16x32_bf16 v[10:13], v[166:169], v[224:227], v[10:13]
	v_mfma_f32_16x16x32_bf16 v[74:77], v[158:161], v[204:207], v[74:77]
	v_mfma_f32_16x16x32_bf16 v[70:73], v[174:177], v[204:207], v[70:73]
	v_mfma_f32_16x16x32_bf16 v[50:53], v[158:161], v[212:215], v[50:53]
	v_mfma_f32_16x16x32_bf16 v[46:49], v[174:177], v[212:215], v[46:49]
	v_mfma_f32_16x16x32_bf16 v[30:33], v[158:161], v[220:223], v[30:33]
	v_mfma_f32_16x16x32_bf16 v[26:29], v[174:177], v[220:223], v[26:29]
	s_waitcnt lgkmcnt(0)
	v_mfma_f32_16x16x32_bf16 v[14:17], v[158:161], v[228:231], v[14:17]
	v_mfma_f32_16x16x32_bf16 v[10:13], v[174:177], v[228:231], v[10:13]
	s_setprio 0
	s_setprio 1
	v_mfma_f32_16x16x32_bf16 v[62:65], v[178:181], v[194:197], v[62:65]
	v_mfma_f32_16x16x32_bf16 v[58:61], v[186:189], v[194:197], v[58:61]
	v_mfma_f32_16x16x32_bf16 v[38:41], v[178:181], v[208:211], v[38:41]
	v_mfma_f32_16x16x32_bf16 v[34:37], v[186:189], v[208:211], v[34:37]
	v_mfma_f32_16x16x32_bf16 v[22:25], v[178:181], v[216:219], v[22:25]
	v_mfma_f32_16x16x32_bf16 v[18:21], v[186:189], v[216:219], v[18:21]
	v_mfma_f32_16x16x32_bf16 v[6:9], v[178:181], v[224:227], v[6:9]
	v_mfma_f32_16x16x32_bf16 v[2:5], v[186:189], v[224:227], v[2:5]
	v_mfma_f32_16x16x32_bf16 v[62:65], v[182:185], v[204:207], v[62:65]
	v_mfma_f32_16x16x32_bf16 v[58:61], v[190:193], v[204:207], v[58:61]
	v_mfma_f32_16x16x32_bf16 v[38:41], v[182:185], v[212:215], v[38:41]
	v_mfma_f32_16x16x32_bf16 v[34:37], v[190:193], v[212:215], v[34:37]
	v_mfma_f32_16x16x32_bf16 v[22:25], v[182:185], v[220:223], v[22:25]
	v_mfma_f32_16x16x32_bf16 v[18:21], v[190:193], v[220:223], v[18:21]
	v_mfma_f32_16x16x32_bf16 v[6:9], v[182:185], v[228:231], v[6:9]
	v_mfma_f32_16x16x32_bf16 v[2:5], v[190:193], v[228:231], v[2:5]
	s_setprio 0
	s_barrier
	v_add_u32_e32 v174, 0x18000, v201
	v_add_u32_e32 v190, 0x1c000, v201
	ds_read_b128 v[146:149], v174
	ds_read_b128 v[158:161], v174 offset:1024
	ds_read_b128 v[166:169], v174 offset:2048
	ds_read_b128 v[174:177], v174 offset:3072
	ds_read_b128 v[178:181], v190
	ds_read_b128 v[182:185], v190 offset:1024
	ds_read_b128 v[186:189], v190 offset:2048
	ds_read_b128 v[190:193], v190 offset:3072
	ds_read_b128 v[194:197], v202 offset:32768
	ds_read_b128 v[204:207], v202 offset:33792
	ds_read_b128 v[208:211], v202 offset:34816
	ds_read_b128 v[212:215], v202 offset:35840
	ds_read_b128 v[216:219], v202 offset:36864
	ds_read_b128 v[220:223], v202 offset:37888
	ds_read_b128 v[224:227], v202 offset:38912
	ds_read_b128 v[228:231], v202 offset:39936
	s_add_u32 s14, s68, 0xb0000
	s_addc_u32 s15, s69, 0
	s_mov_b32 m0, s13
	s_nop 0
	global_load_lds_dwordx4 v0, s[14:15]
	s_add_u32 m0, m0, 0x2000
	s_nop 0
	global_load_lds_dwordx4 v199, s[14:15]
	s_waitcnt vmcnt(8)
	s_waitcnt lgkmcnt(0)
	s_barrier
	s_setprio 1
	s_waitcnt lgkmcnt(7)
	v_mfma_f32_16x16x32_bf16 v[170:173], v[146:149], v[194:197], v[170:173]
	v_mfma_f32_16x16x32_bf16 v[162:165], v[166:169], v[194:197], v[162:165]
	s_waitcnt lgkmcnt(5)
	v_mfma_f32_16x16x32_bf16 v[142:145], v[146:149], v[208:211], v[142:145]
	v_mfma_f32_16x16x32_bf16 v[138:141], v[166:169], v[208:211], v[138:141]
	s_waitcnt lgkmcnt(3)
	v_mfma_f32_16x16x32_bf16 v[126:129], v[146:149], v[216:219], v[126:129]
	v_mfma_f32_16x16x32_bf16 v[122:125], v[166:169], v[216:219], v[122:125]
	s_waitcnt lgkmcnt(1)
	v_mfma_f32_16x16x32_bf16 v[102:105], v[146:149], v[224:227], v[102:105]
	v_mfma_f32_16x16x32_bf16 v[98:101], v[166:169], v[224:227], v[98:101]
	v_mfma_f32_16x16x32_bf16 v[170:173], v[158:161], v[204:207], v[170:173]
	v_mfma_f32_16x16x32_bf16 v[162:165], v[174:177], v[204:207], v[162:165]
	v_mfma_f32_16x16x32_bf16 v[142:145], v[158:161], v[212:215], v[142:145]
	v_mfma_f32_16x16x32_bf16 v[138:141], v[174:177], v[212:215], v[138:141]
	v_mfma_f32_16x16x32_bf16 v[126:129], v[158:161], v[220:223], v[126:129]
	v_mfma_f32_16x16x32_bf16 v[122:125], v[174:177], v[220:223], v[122:125]
	s_waitcnt lgkmcnt(0)
	v_mfma_f32_16x16x32_bf16 v[102:105], v[158:161], v[228:231], v[102:105]
	v_mfma_f32_16x16x32_bf16 v[98:101], v[174:177], v[228:231], v[98:101]
	s_setprio 0
	s_setprio 1
	v_mfma_f32_16x16x32_bf16 v[154:157], v[178:181], v[194:197], v[154:157]
	v_mfma_f32_16x16x32_bf16 v[150:153], v[186:189], v[194:197], v[150:153]
	v_mfma_f32_16x16x32_bf16 v[134:137], v[178:181], v[208:211], v[134:137]
	v_mfma_f32_16x16x32_bf16 v[130:133], v[186:189], v[208:211], v[130:133]
	v_mfma_f32_16x16x32_bf16 v[114:117], v[178:181], v[216:219], v[114:117]
	v_mfma_f32_16x16x32_bf16 v[106:109], v[186:189], v[216:219], v[106:109]
	v_mfma_f32_16x16x32_bf16 v[86:89], v[178:181], v[224:227], v[86:89]
	v_mfma_f32_16x16x32_bf16 v[82:85], v[186:189], v[224:227], v[82:85]
	v_mfma_f32_16x16x32_bf16 v[154:157], v[182:185], v[204:207], v[154:157]
	v_mfma_f32_16x16x32_bf16 v[150:153], v[190:193], v[204:207], v[150:153]
	v_mfma_f32_16x16x32_bf16 v[134:137], v[182:185], v[212:215], v[134:137]
	v_mfma_f32_16x16x32_bf16 v[130:133], v[190:193], v[212:215], v[130:133]
	v_mfma_f32_16x16x32_bf16 v[114:117], v[182:185], v[220:223], v[114:117]
	v_mfma_f32_16x16x32_bf16 v[106:109], v[190:193], v[220:223], v[106:109]
	v_mfma_f32_16x16x32_bf16 v[86:89], v[182:185], v[228:231], v[86:89]
	v_mfma_f32_16x16x32_bf16 v[82:85], v[190:193], v[228:231], v[82:85]
	s_setprio 0
	s_barrier
; #define PG8_STAGE(bufoff, gbase, voff) glds16s2((voff)[0], (voff)[1], (const void*)(gbase), ldsn + (unsigned)(bufoff))
; #define PG8_LDA(dst, b, h) do { _Pragma("unroll") for (int m = 0; m < 4; ++m) _Pragma("unroll") for (int k = 0; k < 2; ++k) dst[m][k] = *(const LAS bf16x8*)(lds + PG8_SA(b, h) + aoff + m * 2048 + k * 1024); } while (0)
; #define PG8_WAIT_V(n) asm volatile("s_waitcnt vmcnt(" #n ")" ::: "memory")
; template <class Epi, bool ALIGN_EPI, bool EARLY_DRAIN = true, class Pre = NoPre>
; __device__ __forceinline__ void gemm_phase(LAS unsigned char* lds, const Gemm g, const StaticOrder& S, const Epi& E, int wv, const Pre& pre = Pre()) {
;     ...
;         for (int t = th; t < th + (Epi::MIDK ? nt / 2 : nt); t += 2) {
;             const bool last = (t == nt - 2);
;             const char* a1 = cA + (size_t)(t + 1) * kstep;
;             const char* a2 = last ? nA : cA + (size_t)(t + 2) * kstep; const char* b2 = last ? nB : cB + (size_t)(t + 2) * kstep;
;             const char* a3 = a2 + kstep; const char* b3 = b2 + kstep;
;             int lf_ = EARLY_DRAIN ? __builtin_amdgcn_readfirstlane(landed_flag) : landed_flag; if constexpr (EARLY_DRAIN) asm volatile("" : "+s"(lf_)); landed_flag = 0;
;             PG8_LDB(B0, 0, 0); PG8_LDB(B1, 0, 1); PG8_SCHED; PG8_LDA(At, 0, 0); PG8_STAGE(PG8_SA(1, 1), a1 + ahs, voffA);
;             if (!lf_) PG8_WAIT_V(8);
;             PG8_WAIT_L(0); PG8_BAR; PG8_MMA(0, 0, At, B0); PG8_MMA(0, 1, At, B1); PG8_BAR; PG8_SCHED;
;             PG8_LDA(At, 0, 1); PG8_STAGE(PG8_SB(0, 0), b2, voffB); PG8_STAGE(PG8_SB(0, 1), b2 + bhs, voffB); PG8_STAGE(PG8_SA(0, 0), a2, voffA);
;             if (!lf_) PG8_WAIT_V(8);
;             PG8_WAIT_L(0); PG8_BAR; PG8_MMA(1, 0, At, B0); PG8_MMA(1, 1, At, B1); PG8_BAR; PG8_SCHED;
;             PG8_LDB(B0, 1, 0); PG8_LDB(B1, 1, 1); PG8_SCHED; PG8_LDA(At, 1, 0); PG8_STAGE(PG8_SA(0, 1), a2 + ahs, voffA);
;             if (!lf_) PG8_WAIT_V(8);
;             PG8_WAIT_L(0); PG8_BAR; PG8_MMA(0, 0, At, B0); PG8_MMA(0, 1, At, B1); PG8_BAR; PG8_SCHED;
;             PG8_LDA(At, 1, 1); PG8_STAGE(PG8_SB(1, 0), b3, voffB); PG8_STAGE(PG8_SB(1, 1), b3 + bhs, voffB); PG8_STAGE(PG8_SA(1, 0), a3, voffA);
;             PG8_WAIT_V(8); PG8_WAIT_L(0); PG8_BAR; PG8_MMA(1, 0, At, B0); PG8_MMA(1, 1, At, B1); PG8_BAR; PG8_SCHED;
;         }
;         }
;         if constexpr (ALIGN_EPI) { if (wr == 0) PG8_BAR; }
	ds_read_b128 v[194:197], v202 offset:49152
	ds_read_b128 v[204:207], v202 offset:50176
	ds_read_b128 v[208:211], v202 offset:51200
	ds_read_b128 v[212:215], v202 offset:52224
	ds_read_b128 v[216:219], v202 offset:53248
	ds_read_b128 v[220:223], v202 offset:54272
	ds_read_b128 v[224:227], v202 offset:55296
	ds_read_b128 v[228:231], v202 offset:56320
	s_add_u32 s14, s60, 0x80
	s_addc_u32 s15, s61, 0
	s_mov_b32 m0, s24
	s_nop 0
	global_load_lds_dwordx4 v198, s[14:15]
	s_add_u32 m0, m0, 0x2000
	s_nop 0
	global_load_lds_dwordx4 v200, s[14:15]
	s_add_u32 s14, s60, 0xb0080
	s_addc_u32 s15, s61, 0
	s_mov_b32 m0, s26
	s_nop 0
	global_load_lds_dwordx4 v198, s[14:15]
	s_add_u32 m0, m0, 0x2000
	s_nop 0
	global_load_lds_dwordx4 v200, s[14:15]
	s_nop 0
	s_mov_b32 m0, s25
	s_nop 0
	global_load_lds_dwordx4 v0, s[40:41]
	s_add_u32 m0, m0, 0x2000
	s_nop 0
	global_load_lds_dwordx4 v199, s[40:41]
	s_waitcnt vmcnt(8)
	s_waitcnt lgkmcnt(0)
	s_barrier
	s_setprio 1
	s_waitcnt lgkmcnt(7)
	v_mfma_f32_16x16x32_bf16 v[74:77], v[146:149], v[194:197], v[74:77]
	v_mfma_f32_16x16x32_bf16 v[70:73], v[166:169], v[194:197], v[70:73]
	s_waitcnt lgkmcnt(5)
	v_mfma_f32_16x16x32_bf16 v[50:53], v[146:149], v[208:211], v[50:53]
	v_mfma_f32_16x16x32_bf16 v[46:49], v[166:169], v[208:211], v[46:49]
	s_waitcnt lgkmcnt(3)
	v_mfma_f32_16x16x32_bf16 v[30:33], v[146:149], v[216:219], v[30:33]
	v_mfma_f32_16x16x32_bf16 v[26:29], v[166:169], v[216:219], v[26:29]
	s_waitcnt lgkmcnt(1)
	v_mfma_f32_16x16x32_bf16 v[14:17], v[146:149], v[224:227], v[14:17]
	v_mfma_f32_16x16x32_bf16 v[10:13], v[166:169], v[224:227], v[10:13]
	v_mfma_f32_16x16x32_bf16 v[74:77], v[158:161], v[204:207], v[74:77]
	v_mfma_f32_16x16x32_bf16 v[70:73], v[174:177], v[204:207], v[70:73]
	v_mfma_f32_16x16x32_bf16 v[50:53], v[158:161], v[212:215], v[50:53]
	v_mfma_f32_16x16x32_bf16 v[46:49], v[174:177], v[212:215], v[46:49]
	v_mfma_f32_16x16x32_bf16 v[30:33], v[158:161], v[220:223], v[30:33]
	v_mfma_f32_16x16x32_bf16 v[26:29], v[174:177], v[220:223], v[26:29]
	s_waitcnt lgkmcnt(0)
	v_mfma_f32_16x16x32_bf16 v[14:17], v[158:161], v[228:231], v[14:17]
	v_mfma_f32_16x16x32_bf16 v[10:13], v[174:177], v[228:231], v[10:13]
	s_setprio 0
	s_setprio 1
	v_mfma_f32_16x16x32_bf16 v[62:65], v[178:181], v[194:197], v[62:65]
	v_mfma_f32_16x16x32_bf16 v[58:61], v[186:189], v[194:197], v[58:61]
	v_mfma_f32_16x16x32_bf16 v[38:41], v[178:181], v[208:211], v[38:41]
	v_mfma_f32_16x16x32_bf16 v[34:37], v[186:189], v[208:211], v[34:37]
	v_mfma_f32_16x16x32_bf16 v[22:25], v[178:181], v[216:219], v[22:25]
	v_mfma_f32_16x16x32_bf16 v[18:21], v[186:189], v[216:219], v[18:21]
	v_mfma_f32_16x16x32_bf16 v[6:9], v[178:181], v[224:227], v[6:9]
	v_mfma_f32_16x16x32_bf16 v[2:5], v[186:189], v[224:227], v[2:5]
	v_mfma_f32_16x16x32_bf16 v[62:65], v[182:185], v[204:207], v[62:65]
	v_mfma_f32_16x16x32_bf16 v[58:61], v[190:193], v[204:207], v[58:61]
	v_mfma_f32_16x16x32_bf16 v[38:41], v[182:185], v[212:215], v[38:41]
	v_mfma_f32_16x16x32_bf16 v[34:37], v[190:193], v[212:215], v[34:37]
	v_mfma_f32_16x16x32_bf16 v[22:25], v[182:185], v[220:223], v[22:25]
	v_mfma_f32_16x16x32_bf16 v[18:21], v[190:193], v[220:223], v[18:21]
	v_mfma_f32_16x16x32_bf16 v[6:9], v[182:185], v[228:231], v[6:9]
	v_mfma_f32_16x16x32_bf16 v[2:5], v[190:193], v[228:231], v[2:5]
	s_setprio 0
	s_barrier
	s_add_i32 s80, s80, 2
	s_add_u32 s52, s52, 0x100
	s_addc_u32 s53, s53, 0
	s_add_u32 s70, s70, 0x100
	s_addc_u32 s71, s71, 0
	s_add_u32 s36, s36, 0x100
	s_addc_u32 s37, s37, 0
	s_cmp_gt_u32 s80, 41
	s_cbranch_scc0 .LBB0_690
	s_and_b64 vcc, exec, s[18:19]
	s_cbranch_vccz .LBB0_693
	s_barrier

; #define PG8_STAGE(bufoff, gbase, voff) glds16s2((voff)[0], (voff)[1], (const void*)(gbase), ldsn + (unsigned)(bufoff))
; #define PG8_LDA(dst, b, h) do { _Pragma("unroll") for (int m = 0; m < 4; ++m) _Pragma("unroll") for (int k = 0; k < 2; ++k) dst[m][k] = *(const LAS bf16x8*)(lds + PG8_SA(b, h) + aoff + m * 2048 + k * 1024); } while (0)
; #define PG8_LDB(dst, b, h) do { _Pragma("unroll") for (int n = 0; n < 2; ++n) _Pragma("unroll") for (int k = 0; k < 2; ++k) dst[n][k] = *(const LAS bf16x8*)(lds + PG8_SB(b, h) + boff + n * 2048 + k * 1024); } while (0)
; #define PG8_WAIT_V(n) asm volatile("s_waitcnt vmcnt(" #n ")" ::: "memory")
; #define PG8_WAIT_L(n) asm volatile("s_waitcnt lgkmcnt(" #n ")" ::: "memory")
; #define PG8_BAR __builtin_amdgcn_s_barrier()
; #define PG8_SCHED __builtin_amdgcn_sched_barrier(0)
; template <class Epi, bool ALIGN_EPI, bool EARLY_DRAIN = true, class Pre = NoPre>
; __device__ __forceinline__ void gemm_phase(LAS unsigned char* lds, const Gemm g, const StaticOrder& S, const Epi& E, int wv, const Pre& pre = Pre()) {
;     ...
;         for (int t = th; t < th + (Epi::MIDK ? nt / 2 : nt); t += 2) {
;             const bool last = (t == nt - 2);
;             const char* a1 = cA + (size_t)(t + 1) * kstep;
;             const char* a2 = last ? nA : cA + (size_t)(t + 2) * kstep; const char* b2 = last ? nB : cB + (size_t)(t + 2) * kstep;
;             const char* a3 = a2 + kstep; const char* b3 = b2 + kstep;
;             int lf_ = EARLY_DRAIN ? __builtin_amdgcn_readfirstlane(landed_flag) : landed_flag; if constexpr (EARLY_DRAIN) asm volatile("" : "+s"(lf_)); landed_flag = 0;
;             PG8_LDB(B0, 0, 0); PG8_LDB(B1, 0, 1); PG8_SCHED; PG8_LDA(At, 0, 0); PG8_STAGE(PG8_SA(1, 1), a1 + ahs, voffA);
;             if (!lf_) PG8_WAIT_V(8);
;             PG8_WAIT_L(0); PG8_BAR; PG8_MMA(0, 0, At, B0); PG8_MMA(0, 1, At, B1); PG8_BAR; PG8_SCHED;
;             PG8_LDA(At, 0, 1); PG8_STAGE(PG8_SB(0, 0), b2, voffB); PG8_STAGE(PG8_SB(0, 1), b2 + bhs, voffB); PG8_STAGE(PG8_SA(0, 0), a2, voffA);
;             if (!lf_) PG8_WAIT_V(8);
;             PG8_WAIT_L(0); PG8_BAR; PG8_MMA(1, 0, At, B0); PG8_MMA(1, 1, At, B1); PG8_BAR; PG8_SCHED;
;             PG8_LDB(B0, 1, 0); PG8_LDB(B1, 1, 1); PG8_SCHED; PG8_LDA(At, 1, 0); PG8_STAGE(PG8_SA(0, 1), a2 + ahs, voffA);
.LBB0_729:
	s_add_u32 s14, s70, 0x100
	s_waitcnt lgkmcnt(0)
	s_addc_u32 s15, s71, 0
	s_add_u32 s24, s68, 0x100
	s_addc_u32 s25, s69, 0
	s_barrier
	s_setprio 1
	s_waitcnt lgkmcnt(7)
	v_mfma_f32_16x16x32_bf16 v[2:5], v[82:85], v[38:41], 0
	v_mfma_f32_16x16x32_bf16 v[6:9], v[90:93], v[38:41], 0
	s_waitcnt lgkmcnt(5)
	v_mfma_f32_16x16x32_bf16 v[10:13], v[82:85], v[46:49], 0
	v_mfma_f32_16x16x32_bf16 v[14:17], v[90:93], v[46:49], 0
	s_waitcnt lgkmcnt(3)
	v_mfma_f32_16x16x32_bf16 v[18:21], v[82:85], v[54:57], 0
	v_mfma_f32_16x16x32_bf16 v[22:25], v[90:93], v[54:57], 0
	s_waitcnt lgkmcnt(1)
	v_mfma_f32_16x16x32_bf16 v[26:29], v[82:85], v[62:65], 0
	v_mfma_f32_16x16x32_bf16 v[30:33], v[90:93], v[62:65], 0
	v_mfma_f32_16x16x32_bf16 v[2:5], v[86:89], v[42:45], v[2:5]
	v_mfma_f32_16x16x32_bf16 v[6:9], v[94:97], v[42:45], v[6:9]
	v_mfma_f32_16x16x32_bf16 v[10:13], v[86:89], v[50:53], v[10:13]
	v_mfma_f32_16x16x32_bf16 v[14:17], v[94:97], v[50:53], v[14:17]
	v_mfma_f32_16x16x32_bf16 v[18:21], v[86:89], v[58:61], v[18:21]
	v_mfma_f32_16x16x32_bf16 v[22:25], v[94:97], v[58:61], v[22:25]
	s_waitcnt lgkmcnt(0)
	v_mfma_f32_16x16x32_bf16 v[26:29], v[86:89], v[98:101], v[26:29]
	v_mfma_f32_16x16x32_bf16 v[30:33], v[94:97], v[98:101], v[30:33]
	s_setprio 0
	s_setprio 1
	v_mfma_f32_16x16x32_bf16 v[34:37], v[66:69], v[38:41], 0
	v_mfma_f32_16x16x32_bf16 v[38:41], v[74:77], v[38:41], 0
	v_mfma_f32_16x16x32_bf16 v[34:37], v[70:73], v[42:45], v[34:37]
	v_mfma_f32_16x16x32_bf16 v[38:41], v[78:81], v[42:45], v[38:41]
	v_mfma_f32_16x16x32_bf16 v[42:45], v[66:69], v[46:49], 0
	v_mfma_f32_16x16x32_bf16 v[46:49], v[74:77], v[46:49], 0
	v_mfma_f32_16x16x32_bf16 v[42:45], v[70:73], v[50:53], v[42:45]
	v_mfma_f32_16x16x32_bf16 v[46:49], v[78:81], v[50:53], v[46:49]
	v_mfma_f32_16x16x32_bf16 v[50:53], v[66:69], v[54:57], 0
	v_mfma_f32_16x16x32_bf16 v[54:57], v[74:77], v[54:57], 0
	v_mfma_f32_16x16x32_bf16 v[50:53], v[70:73], v[58:61], v[50:53]
	v_mfma_f32_16x16x32_bf16 v[54:57], v[78:81], v[58:61], v[54:57]
	v_mfma_f32_16x16x32_bf16 v[58:61], v[66:69], v[62:65], 0
	v_mfma_f32_16x16x32_bf16 v[62:65], v[74:77], v[62:65], 0
	v_mfma_f32_16x16x32_bf16 v[58:61], v[70:73], v[98:101], v[58:61]
	v_mfma_f32_16x16x32_bf16 v[62:65], v[78:81], v[98:101], v[62:65]
	s_setprio 0
	s_barrier
	ds_read_b128 v[154:157], v250 offset:16384
	ds_read_b128 v[162:165], v250 offset:17408
	ds_read_b128 v[130:133], v250 offset:18432
	ds_read_b128 v[146:149], v250 offset:19456
	ds_read_b128 v[110:113], v250 offset:20480
	ds_read_b128 v[118:121], v250 offset:21504
	ds_read_b128 v[102:105], v250 offset:22528
	ds_read_b128 v[106:109], v250 offset:23552
	s_mov_b32 m0, s12
	s_nop 0
	global_load_lds_dwordx4 v230, s[24:25]
	s_add_u32 m0, m0, 0x2000
	s_nop 0
	global_load_lds_dwordx4 v232, s[24:25]
	s_add_u32 s24, s68, 0xb0100
	s_addc_u32 s25, s69, 0
	s_mov_b32 m0, s13
	s_nop 0
	global_load_lds_dwordx4 v230, s[24:25]
	s_add_u32 m0, m0, 0x2000
	s_nop 0
	global_load_lds_dwordx4 v232, s[24:25]
	v_cndmask_b32_e64 v98, 0, 1, s[84:85]
	s_mov_b32 m0, s10
	s_nop 0
	global_load_lds_dwordx4 v0, s[14:15]
	s_add_u32 m0, m0, 0x2000
	s_nop 0
	global_load_lds_dwordx4 v231, s[14:15]
	v_cmp_ne_u32_e64 s[38:39], 1, v98
	s_andn2_b64 vcc, exec, s[84:85]
	s_cbranch_vccnz .LBB0_731
	s_waitcnt vmcnt(8)
.LBB0_731:
	s_waitcnt lgkmcnt(0)
	s_barrier
	s_setprio 1
	s_waitcnt lgkmcnt(7)
	v_mfma_f32_16x16x32_bf16 v[98:101], v[82:85], v[154:157], 0
	s_waitcnt lgkmcnt(5)
	v_mfma_f32_16x16x32_bf16 v[122:125], v[82:85], v[130:133], 0
	s_waitcnt lgkmcnt(3)
	v_mfma_f32_16x16x32_bf16 v[134:137], v[82:85], v[110:113], 0
	s_waitcnt lgkmcnt(1)
	v_mfma_f32_16x16x32_bf16 v[82:85], v[82:85], v[102:105], 0
	v_mfma_f32_16x16x32_bf16 v[114:117], v[90:93], v[154:157], 0
	v_mfma_f32_16x16x32_bf16 v[126:129], v[90:93], v[130:133], 0
	v_mfma_f32_16x16x32_bf16 v[138:141], v[90:93], v[110:113], 0
	s_waitcnt lgkmcnt(0)
	v_mfma_f32_16x16x32_bf16 v[142:145], v[86:89], v[106:109], v[82:85]
	v_mfma_f32_16x16x32_bf16 v[82:85], v[90:93], v[102:105], 0
	v_mfma_f32_16x16x32_bf16 v[98:101], v[86:89], v[162:165], v[98:101]
	v_mfma_f32_16x16x32_bf16 v[114:117], v[94:97], v[162:165], v[114:117]
	v_mfma_f32_16x16x32_bf16 v[122:125], v[86:89], v[146:149], v[122:125]
	v_mfma_f32_16x16x32_bf16 v[126:129], v[94:97], v[146:149], v[126:129]
	v_mfma_f32_16x16x32_bf16 v[134:137], v[86:89], v[118:121], v[134:137]
	v_mfma_f32_16x16x32_bf16 v[138:141], v[94:97], v[118:121], v[138:141]
	v_mfma_f32_16x16x32_bf16 v[150:153], v[94:97], v[106:109], v[82:85]
	s_setprio 0
	s_setprio 1
	v_mfma_f32_16x16x32_bf16 v[82:85], v[66:69], v[154:157], 0
	v_mfma_f32_16x16x32_bf16 v[158:161], v[70:73], v[162:165], v[82:85]
	v_mfma_f32_16x16x32_bf16 v[82:85], v[74:77], v[154:157], 0
	v_mfma_f32_16x16x32_bf16 v[166:169], v[78:81], v[162:165], v[82:85]
	v_mfma_f32_16x16x32_bf16 v[82:85], v[66:69], v[130:133], 0
	v_mfma_f32_16x16x32_bf16 v[170:173], v[70:73], v[146:149], v[82:85]
	v_mfma_f32_16x16x32_bf16 v[82:85], v[74:77], v[130:133], 0
	v_mfma_f32_16x16x32_bf16 v[174:177], v[78:81], v[146:149], v[82:85]
	v_mfma_f32_16x16x32_bf16 v[82:85], v[66:69], v[110:113], 0
	v_mfma_f32_16x16x32_bf16 v[66:69], v[66:69], v[102:105], 0
	v_mfma_f32_16x16x32_bf16 v[178:181], v[70:73], v[118:121], v[82:85]
	v_mfma_f32_16x16x32_bf16 v[82:85], v[74:77], v[110:113], 0
	v_mfma_f32_16x16x32_bf16 v[186:189], v[70:73], v[106:109], v[66:69]
	v_mfma_f32_16x16x32_bf16 v[66:69], v[74:77], v[102:105], 0
	v_mfma_f32_16x16x32_bf16 v[182:185], v[78:81], v[118:121], v[82:85]
	v_mfma_f32_16x16x32_bf16 v[190:193], v[78:81], v[106:109], v[66:69]
	s_setprio 0
	s_barrier
	v_add_u32_e32 v244, 0x18000, v233
	v_add_u32_e32 v245, 0x1c000, v233
	ds_read_b128 v[210:213], v244
	ds_read_b128 v[214:217], v244 offset:1024
	ds_read_b128 v[218:221], v244 offset:2048
	ds_read_b128 v[222:225], v244 offset:3072
	ds_read_b128 v[194:197], v245
	ds_read_b128 v[198:201], v245 offset:1024
	ds_read_b128 v[202:205], v245 offset:2048
	ds_read_b128 v[206:209], v245 offset:3072
	ds_read_b128 v[106:109], v250 offset:32768
	ds_read_b128 v[130:133], v250 offset:33792
	ds_read_b128 v[86:89], v250 offset:34816
	ds_read_b128 v[102:105], v250 offset:35840
	ds_read_b128 v[70:73], v250 offset:36864
	ds_read_b128 v[82:85], v250 offset:37888
	ds_read_b128 v[66:69], v250 offset:38912
	ds_read_b128 v[226:229], v250 offset:39936
	s_add_u32 s14, s70, 0xb0100
	s_addc_u32 s15, s71, 0
	s_mov_b32 m0, s99
	s_nop 0
	global_load_lds_dwordx4 v0, s[14:15]
	s_add_u32 m0, m0, 0x2000
	s_nop 0
	global_load_lds_dwordx4 v231, s[14:15]
	s_and_b64 vcc, exec, s[38:39]
	s_cbranch_vccnz .LBB0_733
	s_waitcnt vmcnt(8)
; #define PG8_STAGE(bufoff, gbase, voff) glds16s2((voff)[0], (voff)[1], (const void*)(gbase), ldsn + (unsigned)(bufoff))
; #define PG8_LDA(dst, b, h) do { _Pragma("unroll") for (int m = 0; m < 4; ++m) _Pragma("unroll") for (int k = 0; k < 2; ++k) dst[m][k] = *(const LAS bf16x8*)(lds + PG8_SA(b, h) + aoff + m * 2048 + k * 1024); } while (0)
; #define PG8_WAIT_V(n) asm volatile("s_waitcnt vmcnt(" #n ")" ::: "memory")
; #define PG8_WAIT_L(n) asm volatile("s_waitcnt lgkmcnt(" #n ")" ::: "memory")
; template <class Epi, bool ALIGN_EPI, bool EARLY_DRAIN = true, class Pre = NoPre>
; __device__ __forceinline__ void gemm_phase(LAS unsigned char* lds, const Gemm g, const StaticOrder& S, const Epi& E, int wv, const Pre& pre = Pre()) {
;     ...
;         for (int t = th; t < th + (Epi::MIDK ? nt / 2 : nt); t += 2) {
;             const bool last = (t == nt - 2);
;             const char* a1 = cA + (size_t)(t + 1) * kstep;
;             const char* a2 = last ? nA : cA + (size_t)(t + 2) * kstep; const char* b2 = last ? nB : cB + (size_t)(t + 2) * kstep;
;             const char* a3 = a2 + kstep; const char* b3 = b2 + kstep;
;             int lf_ = EARLY_DRAIN ? __builtin_amdgcn_readfirstlane(landed_flag) : landed_flag; if constexpr (EARLY_DRAIN) asm volatile("" : "+s"(lf_)); landed_flag = 0;
;             PG8_LDB(B0, 0, 0); PG8_LDB(B1, 0, 1); PG8_SCHED; PG8_LDA(At, 0, 0); PG8_STAGE(PG8_SA(1, 1), a1 + ahs, voffA);
;             if (!lf_) PG8_WAIT_V(8);
;             PG8_WAIT_L(0); PG8_BAR; PG8_MMA(0, 0, At, B0); PG8_MMA(0, 1, At, B1); PG8_BAR; PG8_SCHED;
;             PG8_LDA(At, 0, 1); PG8_STAGE(PG8_SB(0, 0), b2, voffB); PG8_STAGE(PG8_SB(0, 1), b2 + bhs, voffB); PG8_STAGE(PG8_SA(0, 0), a2, voffA);
;             if (!lf_) PG8_WAIT_V(8);
;             PG8_WAIT_L(0); PG8_BAR; PG8_MMA(1, 0, At, B0); PG8_MMA(1, 1, At, B1); PG8_BAR; PG8_SCHED;
;             PG8_LDB(B0, 1, 0); PG8_LDB(B1, 1, 1); PG8_SCHED; PG8_LDA(At, 1, 0); PG8_STAGE(PG8_SA(0, 1), a2 + ahs, voffA);
;             if (!lf_) PG8_WAIT_V(8);
;             PG8_WAIT_L(0); PG8_BAR; PG8_MMA(0, 0, At, B0); PG8_MMA(0, 1, At, B1); PG8_BAR; PG8_SCHED;
;             PG8_LDA(At, 1, 1); PG8_STAGE(PG8_SB(1, 0), b3, voffB); PG8_STAGE(PG8_SB(1, 1), b3 + bhs, voffB); PG8_STAGE(PG8_SA(1, 0), a3, voffA);
;             PG8_WAIT_V(8); PG8_WAIT_L(0); PG8_BAR; PG8_MMA(1, 0, At, B0); PG8_MMA(1, 1, At, B1); PG8_BAR; PG8_SCHED;
.LBB0_733:
	s_add_u32 s14, s70, 0x180
	s_addc_u32 s15, s71, 0
	s_waitcnt lgkmcnt(0)
	s_add_u32 s24, s68, 0x180
	s_addc_u32 s25, s69, 0
	s_barrier
	s_setprio 1
	s_waitcnt lgkmcnt(7)
	v_mfma_f32_16x16x32_bf16 v[2:5], v[210:213], v[106:109], v[2:5]
	s_waitcnt lgkmcnt(6)
	v_mfma_f32_16x16x32_bf16 v[162:165], v[214:217], v[130:133], v[2:5]
	v_mfma_f32_16x16x32_bf16 v[2:5], v[218:221], v[106:109], v[6:9]
	v_mfma_f32_16x16x32_bf16 v[154:157], v[222:225], v[130:133], v[2:5]
	s_waitcnt lgkmcnt(5)
	v_mfma_f32_16x16x32_bf16 v[2:5], v[210:213], v[86:89], v[10:13]
	s_waitcnt lgkmcnt(4)
	v_mfma_f32_16x16x32_bf16 v[118:121], v[214:217], v[102:105], v[2:5]
	v_mfma_f32_16x16x32_bf16 v[2:5], v[218:221], v[86:89], v[14:17]
	v_mfma_f32_16x16x32_bf16 v[110:113], v[222:225], v[102:105], v[2:5]
	s_waitcnt lgkmcnt(3)
	v_mfma_f32_16x16x32_bf16 v[2:5], v[210:213], v[70:73], v[18:21]
	s_waitcnt lgkmcnt(2)
	v_mfma_f32_16x16x32_bf16 v[94:97], v[214:217], v[82:85], v[2:5]
	v_mfma_f32_16x16x32_bf16 v[2:5], v[218:221], v[70:73], v[22:25]
	v_mfma_f32_16x16x32_bf16 v[90:93], v[222:225], v[82:85], v[2:5]
	s_waitcnt lgkmcnt(1)
	v_mfma_f32_16x16x32_bf16 v[2:5], v[210:213], v[66:69], v[26:29]
	s_waitcnt lgkmcnt(0)
	v_mfma_f32_16x16x32_bf16 v[78:81], v[214:217], v[226:229], v[2:5]
	v_mfma_f32_16x16x32_bf16 v[2:5], v[218:221], v[66:69], v[30:33]
	v_mfma_f32_16x16x32_bf16 v[74:77], v[222:225], v[226:229], v[2:5]
	s_setprio 0
	s_setprio 1
	v_mfma_f32_16x16x32_bf16 v[2:5], v[194:197], v[106:109], v[34:37]
	v_mfma_f32_16x16x32_bf16 v[146:149], v[198:201], v[130:133], v[2:5]
	v_mfma_f32_16x16x32_bf16 v[2:5], v[202:205], v[106:109], v[38:41]
	v_mfma_f32_16x16x32_bf16 v[130:133], v[206:209], v[130:133], v[2:5]
	v_mfma_f32_16x16x32_bf16 v[2:5], v[194:197], v[86:89], v[42:45]
	v_mfma_f32_16x16x32_bf16 v[106:109], v[198:201], v[102:105], v[2:5]
	v_mfma_f32_16x16x32_bf16 v[2:5], v[202:205], v[86:89], v[46:49]
	v_mfma_f32_16x16x32_bf16 v[102:105], v[206:209], v[102:105], v[2:5]
	v_mfma_f32_16x16x32_bf16 v[2:5], v[194:197], v[70:73], v[50:53]
	v_mfma_f32_16x16x32_bf16 v[86:89], v[198:201], v[82:85], v[2:5]
	v_mfma_f32_16x16x32_bf16 v[2:5], v[202:205], v[70:73], v[54:57]
	v_mfma_f32_16x16x32_bf16 v[82:85], v[206:209], v[82:85], v[2:5]
	v_mfma_f32_16x16x32_bf16 v[2:5], v[194:197], v[66:69], v[58:61]
	v_mfma_f32_16x16x32_bf16 v[70:73], v[198:201], v[226:229], v[2:5]
	v_mfma_f32_16x16x32_bf16 v[2:5], v[202:205], v[66:69], v[62:65]
	v_mfma_f32_16x16x32_bf16 v[66:69], v[206:209], v[226:229], v[2:5]
	s_setprio 0
	s_barrier
	s_nop 4
	ds_read_b128 v[2:5], v250 offset:49152
	ds_read_b128 v[6:9], v250 offset:50176
	ds_read_b128 v[18:21], v250 offset:51200
	ds_read_b128 v[22:25], v250 offset:52224
	ds_read_b128 v[226:229], v250 offset:53248
	ds_read_b128 v[236:239], v250 offset:54272
	ds_read_b128 v[240:243], v250 offset:55296
	ds_read_b128 v[246:249], v250 offset:56320
	s_mov_b32 m0, s64
	s_nop 0
	global_load_lds_dwordx4 v230, s[24:25]
	s_add_u32 m0, m0, 0x2000
	s_nop 0
	global_load_lds_dwordx4 v232, s[24:25]
	s_add_u32 s24, s68, 0xb0180
	s_addc_u32 s25, s69, 0
	s_mov_b32 m0, s66
	s_nop 0
	global_load_lds_dwordx4 v230, s[24:25]
	s_add_u32 m0, m0, 0x2000
	s_nop 0
	global_load_lds_dwordx4 v232, s[24:25]
	s_nop 0
	s_mov_b32 m0, s65
	s_nop 0
	global_load_lds_dwordx4 v0, s[14:15]
	s_add_u32 m0, m0, 0x2000
	s_nop 0
	global_load_lds_dwordx4 v231, s[14:15]
	s_waitcnt vmcnt(8)
	s_waitcnt lgkmcnt(0)
	s_barrier
	s_setprio 1
	s_waitcnt lgkmcnt(7)
	v_mfma_f32_16x16x32_bf16 v[10:13], v[210:213], v[2:5], v[98:101]
	s_waitcnt lgkmcnt(6)
	v_mfma_f32_16x16x32_bf16 v[62:65], v[214:217], v[6:9], v[10:13]
	v_mfma_f32_16x16x32_bf16 v[10:13], v[218:221], v[2:5], v[114:117]
	v_mfma_f32_16x16x32_bf16 v[58:61], v[222:225], v[6:9], v[10:13]
	s_waitcnt lgkmcnt(5)
	v_mfma_f32_16x16x32_bf16 v[10:13], v[210:213], v[18:21], v[122:125]
	s_waitcnt lgkmcnt(4)
	v_mfma_f32_16x16x32_bf16 v[46:49], v[214:217], v[22:25], v[10:13]
	v_mfma_f32_16x16x32_bf16 v[10:13], v[218:221], v[18:21], v[126:129]
	v_mfma_f32_16x16x32_bf16 v[42:45], v[222:225], v[22:25], v[10:13]
	s_waitcnt lgkmcnt(3)
	v_mfma_f32_16x16x32_bf16 v[10:13], v[210:213], v[226:229], v[134:137]
	s_waitcnt lgkmcnt(2)
	v_mfma_f32_16x16x32_bf16 v[30:33], v[214:217], v[236:239], v[10:13]
	v_mfma_f32_16x16x32_bf16 v[10:13], v[218:221], v[226:229], v[138:141]
	v_mfma_f32_16x16x32_bf16 v[26:29], v[222:225], v[236:239], v[10:13]
	s_waitcnt lgkmcnt(1)
	v_mfma_f32_16x16x32_bf16 v[10:13], v[210:213], v[240:243], v[142:145]
	s_waitcnt lgkmcnt(0)
	v_mfma_f32_16x16x32_bf16 v[14:17], v[214:217], v[246:249], v[10:13]
	v_mfma_f32_16x16x32_bf16 v[10:13], v[218:221], v[240:243], v[150:153]
	v_mfma_f32_16x16x32_bf16 v[10:13], v[222:225], v[246:249], v[10:13]
	s_setprio 0
	s_setprio 1
	v_mfma_f32_16x16x32_bf16 v[34:37], v[194:197], v[2:5], v[158:161]
	v_mfma_f32_16x16x32_bf16 v[2:5], v[202:205], v[2:5], v[166:169]
	v_mfma_f32_16x16x32_bf16 v[50:53], v[206:209], v[6:9], v[2:5]
	v_mfma_f32_16x16x32_bf16 v[2:5], v[194:197], v[18:21], v[170:173]
	v_mfma_f32_16x16x32_bf16 v[38:41], v[198:201], v[22:25], v[2:5]
	v_mfma_f32_16x16x32_bf16 v[2:5], v[202:205], v[18:21], v[174:177]
	v_mfma_f32_16x16x32_bf16 v[54:57], v[198:201], v[6:9], v[34:37]
	v_mfma_f32_16x16x32_bf16 v[34:37], v[206:209], v[22:25], v[2:5]
	v_mfma_f32_16x16x32_bf16 v[2:5], v[194:197], v[226:229], v[178:181]
	v_mfma_f32_16x16x32_bf16 v[22:25], v[198:201], v[236:239], v[2:5]
	v_mfma_f32_16x16x32_bf16 v[2:5], v[202:205], v[226:229], v[182:185]
	v_mfma_f32_16x16x32_bf16 v[18:21], v[206:209], v[236:239], v[2:5]
	v_mfma_f32_16x16x32_bf16 v[2:5], v[194:197], v[240:243], v[186:189]
	v_mfma_f32_16x16x32_bf16 v[6:9], v[198:201], v[246:249], v[2:5]
	v_mfma_f32_16x16x32_bf16 v[2:5], v[202:205], v[240:243], v[190:193]
	v_mfma_f32_16x16x32_bf16 v[2:5], v[206:209], v[246:249], v[2:5]
	s_setprio 0
	s_barrier
	s_add_u32 s19, s70, 0x200
	s_addc_u32 s24, s71, 0
	s_add_u32 s25, s68, 0x200
	s_addc_u32 s26, s69, 0
	s_add_u32 s68, s70, 0xb0180
	s_addc_u32 s69, s71, 0
	s_mov_b32 s0, 0
	s_branch .LBB0_735
; #define PG8_STAGE(bufoff, gbase, voff) glds16s2((voff)[0], (voff)[1], (const void*)(gbase), ldsn + (unsigned)(bufoff))
; #define PG8_LDA(dst, b, h) do { _Pragma("unroll") for (int m = 0; m < 4; ++m) _Pragma("unroll") for (int k = 0; k < 2; ++k) dst[m][k] = *(const LAS bf16x8*)(lds + PG8_SA(b, h) + aoff + m * 2048 + k * 1024); } while (0)
; #define PG8_MMA(ai, bj, At, Bt) do { __builtin_amdgcn_s_setprio(1); _Pragma("unroll") for (int m = 0; m < 4; ++m) _Pragma("unroll") for (int n = 0; n < 2; ++n) _Pragma("unroll") for (int k = 0; k < 2; ++k) \
;         acc[ai][bj][m][n] = __builtin_amdgcn_mfma_f32_16x16x32_bf16(Bt[n][k], At[m][k], acc[ai][bj][m][n], 0, 0, 0); __builtin_amdgcn_s_setprio(0); } while (0)
; #define PG8_WAIT_V(n) asm volatile("s_waitcnt vmcnt(" #n ")" ::: "memory")
; #define PG8_WAIT_L(n) asm volatile("s_waitcnt lgkmcnt(" #n ")" ::: "memory")
; #define PG8_BAR __builtin_amdgcn_s_barrier()
; #define PG8_SCHED __builtin_amdgcn_sched_barrier(0)
; template <class Epi, bool ALIGN_EPI, bool EARLY_DRAIN = true, class Pre = NoPre>
; __device__ __forceinline__ void gemm_phase(LAS unsigned char* lds, const Gemm g, const StaticOrder& S, const Epi& E, int wv, const Pre& pre = Pre()) {
;     ...
;             PG8_WAIT_L(0); PG8_BAR; PG8_MMA(0, 0, At, B0); PG8_MMA(0, 1, At, B1); PG8_BAR; PG8_SCHED;
;             PG8_LDA(At, 1, 1); PG8_STAGE(PG8_SB(1, 0), b3, voffB); PG8_STAGE(PG8_SB(1, 1), b3 + bhs, voffB); PG8_STAGE(PG8_SA(1, 0), a3, voffA);
;             PG8_WAIT_V(8); PG8_WAIT_L(0); PG8_BAR; PG8_MMA(1, 0, At, B0); PG8_MMA(1, 1, At, B1); PG8_BAR; PG8_SCHED;
;         }
.LBB0_734:
	s_add_u32 s14, s84, 0x80
	s_waitcnt lgkmcnt(0)
	s_addc_u32 s15, s85, 0
	s_add_u32 s38, s70, 0x80
	s_addc_u32 s39, s71, 0
	s_barrier
	s_setprio 1
	s_waitcnt lgkmcnt(7)
	v_mfma_f32_16x16x32_bf16 v[98:101], v[158:161], v[130:133], v[98:101]
	s_waitcnt lgkmcnt(6)
	v_mfma_f32_16x16x32_bf16 v[162:165], v[166:169], v[202:205], v[98:101]
	v_mfma_f32_16x16x32_bf16 v[98:101], v[170:173], v[130:133], v[114:117]
	v_mfma_f32_16x16x32_bf16 v[154:157], v[174:177], v[202:205], v[98:101]
	s_waitcnt lgkmcnt(5)
	v_mfma_f32_16x16x32_bf16 v[98:101], v[158:161], v[194:197], v[118:121]
	s_waitcnt lgkmcnt(4)
	v_mfma_f32_16x16x32_bf16 v[118:121], v[166:169], v[198:201], v[98:101]
	v_mfma_f32_16x16x32_bf16 v[98:101], v[170:173], v[194:197], v[110:113]
	s_waitcnt lgkmcnt(3)
	v_mfma_f32_16x16x32_bf16 v[94:97], v[158:161], v[186:189], v[94:97]
	v_mfma_f32_16x16x32_bf16 v[90:93], v[170:173], v[186:189], v[90:93]
	s_waitcnt lgkmcnt(1)
	v_mfma_f32_16x16x32_bf16 v[78:81], v[158:161], v[178:181], v[78:81]
	v_mfma_f32_16x16x32_bf16 v[74:77], v[170:173], v[178:181], v[74:77]
	v_mfma_f32_16x16x32_bf16 v[110:113], v[174:177], v[198:201], v[98:101]
	v_mfma_f32_16x16x32_bf16 v[94:97], v[166:169], v[190:193], v[94:97]
	v_mfma_f32_16x16x32_bf16 v[90:93], v[174:177], v[190:193], v[90:93]
	s_waitcnt lgkmcnt(0)
	v_mfma_f32_16x16x32_bf16 v[78:81], v[166:169], v[182:185], v[78:81]
	v_mfma_f32_16x16x32_bf16 v[74:77], v[174:177], v[182:185], v[74:77]
	s_setprio 0
	s_setprio 1
	v_mfma_f32_16x16x32_bf16 v[98:101], v[134:137], v[130:133], v[122:125]
	v_mfma_f32_16x16x32_bf16 v[146:149], v[138:141], v[202:205], v[98:101]
	v_mfma_f32_16x16x32_bf16 v[98:101], v[142:145], v[130:133], v[126:129]
	v_mfma_f32_16x16x32_bf16 v[130:133], v[150:153], v[202:205], v[98:101]
	v_mfma_f32_16x16x32_bf16 v[98:101], v[134:137], v[194:197], v[106:109]
	v_mfma_f32_16x16x32_bf16 v[106:109], v[138:141], v[198:201], v[98:101]
	v_mfma_f32_16x16x32_bf16 v[98:101], v[142:145], v[194:197], v[102:105]
	v_mfma_f32_16x16x32_bf16 v[86:89], v[134:137], v[186:189], v[86:89]
	v_mfma_f32_16x16x32_bf16 v[82:85], v[142:145], v[186:189], v[82:85]
	v_mfma_f32_16x16x32_bf16 v[70:73], v[134:137], v[178:181], v[70:73]
	v_mfma_f32_16x16x32_bf16 v[66:69], v[142:145], v[178:181], v[66:69]
	v_mfma_f32_16x16x32_bf16 v[102:105], v[150:153], v[198:201], v[98:101]
	v_mfma_f32_16x16x32_bf16 v[86:89], v[138:141], v[190:193], v[86:89]
	v_mfma_f32_16x16x32_bf16 v[82:85], v[150:153], v[190:193], v[82:85]
	v_mfma_f32_16x16x32_bf16 v[70:73], v[138:141], v[182:185], v[70:73]
	v_mfma_f32_16x16x32_bf16 v[66:69], v[150:153], v[182:185], v[66:69]
	s_setprio 0
	s_barrier
	ds_read_b128 v[98:101], v250 offset:49152
	ds_read_b128 v[114:117], v250 offset:50176
	ds_read_b128 v[122:125], v250 offset:51200
	ds_read_b128 v[126:129], v250 offset:52224
	ds_read_b128 v[178:181], v250 offset:53248
	ds_read_b128 v[182:185], v250 offset:54272
	ds_read_b128 v[186:189], v250 offset:55296
	ds_read_b128 v[190:193], v250 offset:56320
	s_mov_b32 m0, s64
	s_nop 0
	global_load_lds_dwordx4 v230, s[38:39]
	s_add_u32 m0, m0, 0x2000
	s_nop 0
	global_load_lds_dwordx4 v232, s[38:39]
	s_add_u32 s38, s70, 0xb0080
	s_addc_u32 s39, s71, 0
	s_mov_b32 m0, s66
	s_nop 0
	global_load_lds_dwordx4 v230, s[38:39]
	s_add_u32 m0, m0, 0x2000
	s_nop 0
	global_load_lds_dwordx4 v232, s[38:39]
	s_nop 0
	s_mov_b32 m0, s65
	s_nop 0
	global_load_lds_dwordx4 v0, s[14:15]
	s_add_u32 m0, m0, 0x2000
	s_nop 0
	global_load_lds_dwordx4 v231, s[14:15]
	s_waitcnt vmcnt(8)
	s_waitcnt lgkmcnt(0)
	s_barrier
	s_setprio 1
	s_waitcnt lgkmcnt(7)
	v_mfma_f32_16x16x32_bf16 v[62:65], v[158:161], v[98:101], v[62:65]
	v_mfma_f32_16x16x32_bf16 v[58:61], v[170:173], v[98:101], v[58:61]
	s_waitcnt lgkmcnt(5)
	v_mfma_f32_16x16x32_bf16 v[46:49], v[158:161], v[122:125], v[46:49]
	v_mfma_f32_16x16x32_bf16 v[42:45], v[170:173], v[122:125], v[42:45]
	s_waitcnt lgkmcnt(3)
	v_mfma_f32_16x16x32_bf16 v[30:33], v[158:161], v[178:181], v[30:33]
	v_mfma_f32_16x16x32_bf16 v[26:29], v[170:173], v[178:181], v[26:29]
	s_waitcnt lgkmcnt(1)
	v_mfma_f32_16x16x32_bf16 v[14:17], v[158:161], v[186:189], v[14:17]
	v_mfma_f32_16x16x32_bf16 v[10:13], v[170:173], v[186:189], v[10:13]
	v_mfma_f32_16x16x32_bf16 v[62:65], v[166:169], v[114:117], v[62:65]
	v_mfma_f32_16x16x32_bf16 v[58:61], v[174:177], v[114:117], v[58:61]
	v_mfma_f32_16x16x32_bf16 v[46:49], v[166:169], v[126:129], v[46:49]
	v_mfma_f32_16x16x32_bf16 v[42:45], v[174:177], v[126:129], v[42:45]
	v_mfma_f32_16x16x32_bf16 v[30:33], v[166:169], v[182:185], v[30:33]
	v_mfma_f32_16x16x32_bf16 v[26:29], v[174:177], v[182:185], v[26:29]
	s_waitcnt lgkmcnt(0)
	v_mfma_f32_16x16x32_bf16 v[14:17], v[166:169], v[190:193], v[14:17]
	v_mfma_f32_16x16x32_bf16 v[10:13], v[174:177], v[190:193], v[10:13]
	s_setprio 0
	s_setprio 1
	v_mfma_f32_16x16x32_bf16 v[54:57], v[134:137], v[98:101], v[54:57]
	v_mfma_f32_16x16x32_bf16 v[50:53], v[142:145], v[98:101], v[50:53]
	v_mfma_f32_16x16x32_bf16 v[38:41], v[134:137], v[122:125], v[38:41]
	v_mfma_f32_16x16x32_bf16 v[34:37], v[142:145], v[122:125], v[34:37]
	v_mfma_f32_16x16x32_bf16 v[22:25], v[134:137], v[178:181], v[22:25]
	v_mfma_f32_16x16x32_bf16 v[18:21], v[142:145], v[178:181], v[18:21]
	v_mfma_f32_16x16x32_bf16 v[6:9], v[134:137], v[186:189], v[6:9]
	v_mfma_f32_16x16x32_bf16 v[2:5], v[142:145], v[186:189], v[2:5]
	v_mfma_f32_16x16x32_bf16 v[54:57], v[138:141], v[114:117], v[54:57]
	v_mfma_f32_16x16x32_bf16 v[50:53], v[150:153], v[114:117], v[50:53]
	v_mfma_f32_16x16x32_bf16 v[38:41], v[138:141], v[126:129], v[38:41]
	v_mfma_f32_16x16x32_bf16 v[34:37], v[150:153], v[126:129], v[34:37]
	v_mfma_f32_16x16x32_bf16 v[22:25], v[138:141], v[182:185], v[22:25]
	v_mfma_f32_16x16x32_bf16 v[18:21], v[150:153], v[182:185], v[18:21]
	v_mfma_f32_16x16x32_bf16 v[6:9], v[138:141], v[190:193], v[6:9]
	v_mfma_f32_16x16x32_bf16 v[2:5], v[150:153], v[190:193], v[2:5]
	s_setprio 0
	s_barrier
	s_add_i32 s0, s0, 2
	s_add_u32 s19, s19, 0x100
	s_addc_u32 s24, s24, 0
	s_add_u32 s25, s25, 0x100
	s_addc_u32 s26, s26, 0
	s_add_u32 s68, s68, 0x100
	s_addc_u32 s69, s69, 0
	s_cmp_gt_u32 s0, 41
	s_cbranch_scc1 .LBB0_741

; #define PG8_STAGE(bufoff, gbase, voff) glds16s2((voff)[0], (voff)[1], (const void*)(gbase), ldsn + (unsigned)(bufoff))
; #define PG8_LDA(dst, b, h) do { _Pragma("unroll") for (int m = 0; m < 4; ++m) _Pragma("unroll") for (int k = 0; k < 2; ++k) dst[m][k] = *(const LAS bf16x8*)(lds + PG8_SA(b, h) + aoff + m * 2048 + k * 1024); } while (0)
; #define PG8_LDB(dst, b, h) do { _Pragma("unroll") for (int n = 0; n < 2; ++n) _Pragma("unroll") for (int k = 0; k < 2; ++k) dst[n][k] = *(const LAS bf16x8*)(lds + PG8_SB(b, h) + boff + n * 2048 + k * 1024); } while (0)
; #define PG8_MMA(ai, bj, At, Bt) do { __builtin_amdgcn_s_setprio(1); _Pragma("unroll") for (int m = 0; m < 4; ++m) _Pragma("unroll") for (int n = 0; n < 2; ++n) _Pragma("unroll") for (int k = 0; k < 2; ++k) \
;         acc[ai][bj][m][n] = __builtin_amdgcn_mfma_f32_16x16x32_bf16(Bt[n][k], At[m][k], acc[ai][bj][m][n], 0, 0, 0); __builtin_amdgcn_s_setprio(0); } while (0)
; template <class Epi, bool ALIGN_EPI, bool EARLY_DRAIN = true, class Pre = NoPre>
; __device__ __forceinline__ void gemm_phase(LAS unsigned char* lds, const Gemm g, const StaticOrder& S, const Epi& E, int wv, const Pre& pre = Pre()) {
;     ...
;             const bool last = (t == nt - 2);
;             const char* a1 = cA + (size_t)(t + 1) * kstep;
;             const char* a2 = last ? nA : cA + (size_t)(t + 2) * kstep; const char* b2 = last ? nB : cB + (size_t)(t + 2) * kstep;
;             const char* a3 = a2 + kstep; const char* b3 = b2 + kstep;
;             int lf_ = EARLY_DRAIN ? __builtin_amdgcn_readfirstlane(landed_flag) : landed_flag; if constexpr (EARLY_DRAIN) asm volatile("" : "+s"(lf_)); landed_flag = 0;
;             PG8_LDB(B0, 0, 0); PG8_LDB(B1, 0, 1); PG8_SCHED; PG8_LDA(At, 0, 0); PG8_STAGE(PG8_SA(1, 1), a1 + ahs, voffA);
;             if (!lf_) PG8_WAIT_V(8);
;             PG8_WAIT_L(0); PG8_BAR; PG8_MMA(0, 0, At, B0); PG8_MMA(0, 1, At, B1); PG8_BAR; PG8_SCHED;
;             PG8_LDA(At, 0, 1); PG8_STAGE(PG8_SB(0, 0), b2, voffB); PG8_STAGE(PG8_SB(0, 1), b2 + bhs, voffB); PG8_STAGE(PG8_SA(0, 0), a2, voffA);
;             if (!lf_) PG8_WAIT_V(8);
;             PG8_WAIT_L(0); PG8_BAR; PG8_MMA(1, 0, At, B0); PG8_MMA(1, 1, At, B1); PG8_BAR; PG8_SCHED;
;             PG8_LDB(B0, 1, 0); PG8_LDB(B1, 1, 1); PG8_SCHED; PG8_LDA(At, 1, 0); PG8_STAGE(PG8_SA(0, 1), a2 + ahs, voffA);
;             if (!lf_) PG8_WAIT_V(8);
.LBB0_737:
	s_waitcnt lgkmcnt(0)
	s_cmp_eq_u32 s0, 40
	s_cselect_b32 s85, s35, s24
	s_cselect_b32 s84, s34, s19
	s_cselect_b32 s71, s77, s26
	s_cselect_b32 s70, s76, s25
	s_barrier
	s_setprio 1
	s_waitcnt lgkmcnt(7)
	v_mfma_f32_16x16x32_bf16 v[98:101], v[158:161], v[126:129], v[162:165]
	v_mfma_f32_16x16x32_bf16 v[114:117], v[170:173], v[126:129], v[154:157]
	s_waitcnt lgkmcnt(5)
	v_mfma_f32_16x16x32_bf16 v[118:121], v[158:161], v[194:197], v[118:121]
	v_mfma_f32_16x16x32_bf16 v[110:113], v[170:173], v[194:197], v[110:113]
	s_waitcnt lgkmcnt(3)
	v_mfma_f32_16x16x32_bf16 v[94:97], v[158:161], v[186:189], v[94:97]
	v_mfma_f32_16x16x32_bf16 v[90:93], v[170:173], v[186:189], v[90:93]
	s_waitcnt lgkmcnt(1)
	v_mfma_f32_16x16x32_bf16 v[78:81], v[158:161], v[178:181], v[78:81]
	v_mfma_f32_16x16x32_bf16 v[74:77], v[170:173], v[178:181], v[74:77]
	v_mfma_f32_16x16x32_bf16 v[98:101], v[166:169], v[202:205], v[98:101]
	v_mfma_f32_16x16x32_bf16 v[114:117], v[174:177], v[202:205], v[114:117]
	v_mfma_f32_16x16x32_bf16 v[118:121], v[166:169], v[198:201], v[118:121]
	v_mfma_f32_16x16x32_bf16 v[110:113], v[174:177], v[198:201], v[110:113]
	v_mfma_f32_16x16x32_bf16 v[94:97], v[166:169], v[190:193], v[94:97]
	v_mfma_f32_16x16x32_bf16 v[90:93], v[174:177], v[190:193], v[90:93]
	s_waitcnt lgkmcnt(0)
	v_mfma_f32_16x16x32_bf16 v[78:81], v[166:169], v[182:185], v[78:81]
	v_mfma_f32_16x16x32_bf16 v[74:77], v[174:177], v[182:185], v[74:77]
	s_setprio 0
	s_setprio 1
	v_mfma_f32_16x16x32_bf16 v[122:125], v[134:137], v[126:129], v[146:149]
	v_mfma_f32_16x16x32_bf16 v[126:129], v[142:145], v[126:129], v[130:133]
	v_mfma_f32_16x16x32_bf16 v[106:109], v[134:137], v[194:197], v[106:109]
	v_mfma_f32_16x16x32_bf16 v[102:105], v[142:145], v[194:197], v[102:105]
	v_mfma_f32_16x16x32_bf16 v[86:89], v[134:137], v[186:189], v[86:89]
	v_mfma_f32_16x16x32_bf16 v[82:85], v[142:145], v[186:189], v[82:85]
	v_mfma_f32_16x16x32_bf16 v[70:73], v[134:137], v[178:181], v[70:73]
	v_mfma_f32_16x16x32_bf16 v[66:69], v[142:145], v[178:181], v[66:69]
	v_mfma_f32_16x16x32_bf16 v[122:125], v[138:141], v[202:205], v[122:125]
	v_mfma_f32_16x16x32_bf16 v[126:129], v[150:153], v[202:205], v[126:129]
	v_mfma_f32_16x16x32_bf16 v[106:109], v[138:141], v[198:201], v[106:109]
	v_mfma_f32_16x16x32_bf16 v[102:105], v[150:153], v[198:201], v[102:105]
	v_mfma_f32_16x16x32_bf16 v[86:89], v[138:141], v[190:193], v[86:89]
	v_mfma_f32_16x16x32_bf16 v[82:85], v[150:153], v[190:193], v[82:85]
	v_mfma_f32_16x16x32_bf16 v[70:73], v[138:141], v[182:185], v[70:73]
	v_mfma_f32_16x16x32_bf16 v[66:69], v[150:153], v[182:185], v[66:69]
	s_setprio 0
	s_barrier
	ds_read_b128 v[186:189], v250 offset:16384
	ds_read_b128 v[190:193], v250 offset:17408
	ds_read_b128 v[178:181], v250 offset:18432
	ds_read_b128 v[182:185], v250 offset:19456
	ds_read_b128 v[154:157], v250 offset:20480
	ds_read_b128 v[162:165], v250 offset:21504
	ds_read_b128 v[130:133], v250 offset:22528
	ds_read_b128 v[146:149], v250 offset:23552
	s_mov_b32 m0, s12
	s_nop 0
	global_load_lds_dwordx4 v230, s[70:71]
	s_add_u32 m0, m0, 0x2000
	s_nop 0
	global_load_lds_dwordx4 v232, s[70:71]
	s_add_u32 s14, s70, 0xb0000
	s_addc_u32 s15, s71, 0
	s_mov_b32 m0, s13
	s_nop 0
	global_load_lds_dwordx4 v230, s[14:15]
	s_add_u32 m0, m0, 0x2000
	s_nop 0
	global_load_lds_dwordx4 v232, s[14:15]
	v_cndmask_b32_e64 v194, 0, 1, s[86:87]
	s_mov_b32 m0, s10
	s_nop 0
	global_load_lds_dwordx4 v0, s[84:85]
	s_add_u32 m0, m0, 0x2000
	s_nop 0
	global_load_lds_dwordx4 v231, s[84:85]
	v_cmp_ne_u32_e64 s[38:39], 1, v194
	s_andn2_b64 vcc, exec, s[86:87]
	s_cbranch_vccnz .LBB0_739
	s_waitcnt vmcnt(8)
.LBB0_739:
	s_waitcnt lgkmcnt(0)
	s_barrier
	s_setprio 1
	s_waitcnt lgkmcnt(7)
	v_mfma_f32_16x16x32_bf16 v[62:65], v[158:161], v[186:189], v[62:65]
	v_mfma_f32_16x16x32_bf16 v[58:61], v[170:173], v[186:189], v[58:61]
	s_waitcnt lgkmcnt(5)
	v_mfma_f32_16x16x32_bf16 v[46:49], v[158:161], v[178:181], v[46:49]
	v_mfma_f32_16x16x32_bf16 v[42:45], v[170:173], v[178:181], v[42:45]
	s_waitcnt lgkmcnt(3)
	v_mfma_f32_16x16x32_bf16 v[30:33], v[158:161], v[154:157], v[30:33]
	v_mfma_f32_16x16x32_bf16 v[26:29], v[170:173], v[154:157], v[26:29]
	s_waitcnt lgkmcnt(1)
	v_mfma_f32_16x16x32_bf16 v[14:17], v[158:161], v[130:133], v[14:17]
	v_mfma_f32_16x16x32_bf16 v[10:13], v[170:173], v[130:133], v[10:13]
	v_mfma_f32_16x16x32_bf16 v[62:65], v[166:169], v[190:193], v[62:65]
	v_mfma_f32_16x16x32_bf16 v[58:61], v[174:177], v[190:193], v[58:61]
	v_mfma_f32_16x16x32_bf16 v[46:49], v[166:169], v[182:185], v[46:49]
	v_mfma_f32_16x16x32_bf16 v[42:45], v[174:177], v[182:185], v[42:45]
	v_mfma_f32_16x16x32_bf16 v[30:33], v[166:169], v[162:165], v[30:33]
	v_mfma_f32_16x16x32_bf16 v[26:29], v[174:177], v[162:165], v[26:29]
	s_waitcnt lgkmcnt(0)
	v_mfma_f32_16x16x32_bf16 v[14:17], v[166:169], v[146:149], v[14:17]
	v_mfma_f32_16x16x32_bf16 v[10:13], v[174:177], v[146:149], v[10:13]
	s_setprio 0
	s_setprio 1
	v_mfma_f32_16x16x32_bf16 v[54:57], v[134:137], v[186:189], v[54:57]
	v_mfma_f32_16x16x32_bf16 v[50:53], v[142:145], v[186:189], v[50:53]
	v_mfma_f32_16x16x32_bf16 v[38:41], v[134:137], v[178:181], v[38:41]
	v_mfma_f32_16x16x32_bf16 v[34:37], v[142:145], v[178:181], v[34:37]
	v_mfma_f32_16x16x32_bf16 v[22:25], v[134:137], v[154:157], v[22:25]
	v_mfma_f32_16x16x32_bf16 v[18:21], v[142:145], v[154:157], v[18:21]
	v_mfma_f32_16x16x32_bf16 v[6:9], v[134:137], v[130:133], v[6:9]
	v_mfma_f32_16x16x32_bf16 v[2:5], v[142:145], v[130:133], v[2:5]
	v_mfma_f32_16x16x32_bf16 v[54:57], v[138:141], v[190:193], v[54:57]
	v_mfma_f32_16x16x32_bf16 v[50:53], v[150:153], v[190:193], v[50:53]
	v_mfma_f32_16x16x32_bf16 v[38:41], v[138:141], v[182:185], v[38:41]
	v_mfma_f32_16x16x32_bf16 v[34:37], v[150:153], v[182:185], v[34:37]
	v_mfma_f32_16x16x32_bf16 v[22:25], v[138:141], v[162:165], v[22:25]
	v_mfma_f32_16x16x32_bf16 v[18:21], v[150:153], v[162:165], v[18:21]
	v_mfma_f32_16x16x32_bf16 v[6:9], v[138:141], v[146:149], v[6:9]
	v_mfma_f32_16x16x32_bf16 v[2:5], v[150:153], v[146:149], v[2:5]
	s_setprio 0
	s_barrier
	ds_read_b128 v[158:161], v244
	ds_read_b128 v[166:169], v244 offset:1024
	ds_read_b128 v[170:173], v244 offset:2048
	ds_read_b128 v[174:177], v244 offset:3072
	ds_read_b128 v[134:137], v245
	ds_read_b128 v[138:141], v245 offset:1024
	ds_read_b128 v[142:145], v245 offset:2048
	ds_read_b128 v[150:153], v245 offset:3072
	ds_read_b128 v[130:133], v250 offset:32768
	ds_read_b128 v[202:205], v250 offset:33792
	ds_read_b128 v[194:197], v250 offset:34816
	ds_read_b128 v[198:201], v250 offset:35840
	ds_read_b128 v[186:189], v250 offset:36864
	ds_read_b128 v[190:193], v250 offset:37888
	ds_read_b128 v[178:181], v250 offset:38912
	ds_read_b128 v[182:185], v250 offset:39936
	s_add_u32 s14, s84, 0xb0000
	s_addc_u32 s15, s85, 0
	s_mov_b32 m0, s99
	s_nop 0
	global_load_lds_dwordx4 v0, s[14:15]
	s_add_u32 m0, m0, 0x2000
	s_nop 0
	global_load_lds_dwordx4 v231, s[14:15]
	s_and_b64 vcc, exec, s[38:39]
	s_cbranch_vccnz .LBB0_734
	s_waitcnt vmcnt(8)
	s_branch .LBB0_734
